# GEMM main loops: fragment ds_reads ordered by first use and the post-barrier wait split into a two-rung counted lgkmcnt wait (first 8 MFMAs of each cluster start before the cluster's last fragments la
# speedup vs baseline: 1.0077x; 1.0077x over previous
.LBB0_403:
	s_add_u32 s14, s4, 0x100
	s_addc_u32 s15, s5, 0
	s_add_i32 s38, 0, 0x10000
	v_add_u32_e32 v12, s38, v193
	ds_read_b128 v[0:3], v12
	ds_read_b128 v[8:11], v12 offset:2048
	ds_read_b128 v[4:7], v12 offset:1024
	ds_read_b128 v[12:15], v12 offset:3072
	s_cmp_eq_u32 s37, 12
	s_cselect_b32 s19, s9, s15
	s_cselect_b32 s18, s8, s14
	s_cselect_b32 s17, s11, s36
	s_cselect_b32 s16, s10, s7
	v_lshl_add_u64 v[190:191], s[4:5], 0, v[186:187]
	s_add_i32 m0, s23, 0xc000
	ds_read_b128 v[16:19], v206
	ds_read_b128 v[24:27], v206 offset:2048
	ds_read_b128 v[162:165], v206 offset:4096
	ds_read_b128 v[170:173], v206 offset:6144
	ds_read_b128 v[20:23], v206 offset:1024
	ds_read_b128 v[28:31], v206 offset:3072
	ds_read_b128 v[166:169], v206 offset:5120
	ds_read_b128 v[174:177], v206 offset:7168
	global_load_lds_dwordx4 v[190:191], off
	v_lshl_add_u64 v[190:191], s[4:5], 0, v[188:189]
	s_add_i32 m0, s23, 0xe000
	s_nop 0
	global_load_lds_dwordx4 v[190:191], off
	s_waitcnt lgkmcnt(8)
	s_barrier
	s_waitcnt lgkmcnt(4)
	s_setprio 1
	v_mfma_f32_16x16x32_f16 v[158:161], v[0:3], v[16:19], v[158:161]
	v_mfma_f32_16x16x32_f16 v[142:145], v[8:11], v[16:19], v[142:145]
	v_mfma_f32_16x16x32_f16 v[150:153], v[0:3], v[24:27], v[150:153]
	v_mfma_f32_16x16x32_f16 v[134:137], v[8:11], v[24:27], v[134:137]
	v_mfma_f32_16x16x32_f16 v[154:157], v[0:3], v[162:165], v[154:157]
	v_mfma_f32_16x16x32_f16 v[138:141], v[8:11], v[162:165], v[138:141]
	v_mfma_f32_16x16x32_f16 v[146:149], v[0:3], v[170:173], v[146:149]
	v_mfma_f32_16x16x32_f16 v[130:133], v[8:11], v[170:173], v[130:133]
	s_waitcnt lgkmcnt(0)
	v_mfma_f32_16x16x32_f16 v[158:161], v[4:7], v[20:23], v[158:161]
	v_mfma_f32_16x16x32_f16 v[142:145], v[12:15], v[20:23], v[142:145]
	v_mfma_f32_16x16x32_f16 v[150:153], v[4:7], v[28:31], v[150:153]
	v_mfma_f32_16x16x32_f16 v[134:137], v[12:15], v[28:31], v[134:137]
	v_mfma_f32_16x16x32_f16 v[154:157], v[4:7], v[166:169], v[154:157]
	v_mfma_f32_16x16x32_f16 v[138:141], v[12:15], v[166:169], v[138:141]
	v_mfma_f32_16x16x32_f16 v[146:149], v[4:7], v[174:177], v[146:149]
	v_mfma_f32_16x16x32_f16 v[130:133], v[12:15], v[174:177], v[130:133]
	s_setprio 0
	s_barrier
	s_add_i32 s39, 0, 0x14000
	s_add_i32 s4, s38, s22
	v_add_u32_e32 v32, s39, v193
	v_lshl_add_u64 v[190:191], s[16:17], 0, v[178:179]
	s_mov_b32 m0, s4
	ds_read_b128 v[208:211], v32
	ds_read_b128 v[216:219], v32 offset:2048
	ds_read_b128 v[212:215], v32 offset:1024
	ds_read_b128 v[230:233], v32 offset:3072
	global_load_lds_dwordx4 v[190:191], off
	v_lshl_add_u64 v[238:239], s[16:17], 0, v[180:181]
	s_add_i32 m0, s4, 0x2000
	s_nop 0
	global_load_lds_dwordx4 v[238:239], off
	s_barrier
	s_waitcnt lgkmcnt(0)
	s_setprio 1
	s_waitcnt lgkmcnt(0)
	v_mfma_f32_16x16x32_f16 v[94:97], v[208:211], v[16:19], v[94:97]
	v_mfma_f32_16x16x32_f16 v[16:19], v[216:219], v[16:19], v[78:81]
	v_mfma_f32_16x16x32_f16 v[94:97], v[212:215], v[20:23], v[94:97]
	v_mfma_f32_16x16x32_f16 v[16:19], v[230:233], v[20:23], v[16:19]
	v_mfma_f32_16x16x32_f16 v[20:23], v[208:211], v[24:27], v[86:89]
	v_mfma_f32_16x16x32_f16 v[24:27], v[216:219], v[24:27], v[70:73]
	v_mfma_f32_16x16x32_f16 v[70:73], v[216:219], v[162:165], v[74:77]
	v_mfma_f32_16x16x32_f16 v[74:77], v[230:233], v[166:169], v[70:73]
	v_mfma_f32_16x16x32_f16 v[70:73], v[208:211], v[170:173], v[82:85]
	v_mfma_f32_16x16x32_f16 v[66:69], v[216:219], v[170:173], v[66:69]
	v_mfma_f32_16x16x32_f16 v[20:23], v[212:215], v[28:31], v[20:23]
	v_mfma_f32_16x16x32_f16 v[24:27], v[230:233], v[28:31], v[24:27]
	v_mfma_f32_16x16x32_f16 v[28:31], v[208:211], v[162:165], v[90:93]
	v_mfma_f32_16x16x32_f16 v[82:85], v[212:215], v[174:177], v[70:73]
	v_mfma_f32_16x16x32_f16 v[66:69], v[230:233], v[174:177], v[66:69]
	v_mfma_f32_16x16x32_f16 v[28:31], v[212:215], v[166:169], v[28:31]
	s_setprio 0
	s_mov_b32 m0, s23
	v_lshl_add_u64 v[240:241], s[18:19], 0, v[178:179]
	s_barrier
	ds_read_b128 v[70:73], v206 offset:16384
	ds_read_b128 v[86:89], v206 offset:18432
	ds_read_b128 v[162:165], v206 offset:20480
	ds_read_b128 v[170:173], v206 offset:22528
	ds_read_b128 v[78:81], v206 offset:17408
	ds_read_b128 v[90:93], v206 offset:19456
	ds_read_b128 v[166:169], v206 offset:21504
	ds_read_b128 v[174:177], v206 offset:23552
	global_load_lds_dwordx4 v[240:241], off
	v_lshl_add_u64 v[242:243], s[18:19], 0, v[180:181]
	s_mov_b32 m0, s24
	s_nop 0
	global_load_lds_dwordx4 v[242:243], off
	s_barrier
	s_waitcnt lgkmcnt(3)
	s_setprio 1
	v_mfma_f32_16x16x32_f16 v[126:129], v[0:3], v[70:73], v[126:129]
	v_mfma_f32_16x16x32_f16 v[110:113], v[8:11], v[70:73], v[110:113]
	v_mfma_f32_16x16x32_f16 v[118:121], v[0:3], v[86:89], v[118:121]
	v_mfma_f32_16x16x32_f16 v[102:105], v[8:11], v[86:89], v[102:105]
	v_mfma_f32_16x16x32_f16 v[122:125], v[0:3], v[162:165], v[122:125]
	v_mfma_f32_16x16x32_f16 v[106:109], v[8:11], v[162:165], v[106:109]
	v_mfma_f32_16x16x32_f16 v[0:3], v[0:3], v[170:173], v[114:117]
	v_mfma_f32_16x16x32_f16 v[126:129], v[4:7], v[78:81], v[126:129]
	s_waitcnt lgkmcnt(0)
	v_mfma_f32_16x16x32_f16 v[110:113], v[12:15], v[78:81], v[110:113]
	v_mfma_f32_16x16x32_f16 v[118:121], v[4:7], v[90:93], v[118:121]
	v_mfma_f32_16x16x32_f16 v[102:105], v[12:15], v[90:93], v[102:105]
	v_mfma_f32_16x16x32_f16 v[122:125], v[4:7], v[166:169], v[122:125]
	v_mfma_f32_16x16x32_f16 v[106:109], v[12:15], v[166:169], v[106:109]
	v_mfma_f32_16x16x32_f16 v[0:3], v[4:7], v[174:177], v[0:3]
	v_mfma_f32_16x16x32_f16 v[4:7], v[8:11], v[170:173], v[98:101]
	v_mfma_f32_16x16x32_f16 v[4:7], v[12:15], v[174:177], v[4:7]
	s_setprio 0
	s_barrier
	s_add_u32 s4, s16, 0x40000
	s_addc_u32 s5, s17, 0
	s_add_i32 s38, s39, s22
	v_lshl_add_u64 v[8:9], s[4:5], 0, v[178:179]
	s_mov_b32 m0, s38
	s_nop 0
	global_load_lds_dwordx4 v[8:9], off
	v_lshl_add_u64 v[8:9], s[4:5], 0, v[180:181]
	s_add_i32 m0, s38, 0x2000
	s_nop 0
	global_load_lds_dwordx4 v[8:9], off
	s_waitcnt vmcnt(6)
	s_barrier
	s_setprio 1
	v_mfma_f32_16x16x32_f16 v[12:15], v[216:219], v[70:73], v[46:49]
	v_mfma_f32_16x16x32_f16 v[46:49], v[208:211], v[86:89], v[54:57]
	v_mfma_f32_16x16x32_f16 v[54:57], v[212:215], v[90:93], v[46:49]
	v_mfma_f32_16x16x32_f16 v[46:49], v[208:211], v[162:165], v[58:61]
	v_mfma_f32_16x16x32_f16 v[38:41], v[216:219], v[86:89], v[38:41]
	v_mfma_f32_16x16x32_f16 v[58:61], v[212:215], v[166:169], v[46:49]
	v_mfma_f32_16x16x32_f16 v[42:45], v[216:219], v[162:165], v[42:45]
	v_mfma_f32_16x16x32_f16 v[46:49], v[208:211], v[170:173], v[50:53]
	v_mfma_f32_16x16x32_f16 v[34:37], v[216:219], v[170:173], v[34:37]
	v_mfma_f32_16x16x32_f16 v[8:11], v[208:211], v[70:73], v[62:65]
	v_mfma_f32_16x16x32_f16 v[38:41], v[230:233], v[90:93], v[38:41]
	v_mfma_f32_16x16x32_f16 v[42:45], v[230:233], v[166:169], v[42:45]
	v_mfma_f32_16x16x32_f16 v[50:53], v[212:215], v[174:177], v[46:49]
	v_mfma_f32_16x16x32_f16 v[34:37], v[230:233], v[174:177], v[34:37]
	v_mfma_f32_16x16x32_f16 v[8:11], v[212:215], v[78:81], v[8:11]
	v_mfma_f32_16x16x32_f16 v[12:15], v[230:233], v[78:81], v[12:15]
	s_setprio 0
	s_add_i32 s38, 0, 0x18000
	v_add_u32_e32 v32, s38, v193
	s_barrier
	ds_read_b128 v[46:49], v32
	ds_read_b128 v[62:65], v32 offset:1024
	ds_read_b128 v[98:101], v32 offset:2048
	ds_read_b128 v[162:165], v32 offset:3072
	s_add_u32 s4, s18, 0x40000
	s_addc_u32 s5, s19, 0
	s_mov_b32 m0, s25
	v_lshl_add_u64 v[86:87], s[4:5], 0, v[178:179]
	ds_read_b128 v[70:73], v206 offset:32768
	ds_read_b128 v[78:81], v206 offset:33792
	ds_read_b128 v[90:93], v206 offset:34816
	ds_read_b128 v[114:117], v206 offset:35840
	ds_read_b128 v[166:169], v206 offset:36864
	ds_read_b128 v[170:173], v206 offset:37888
	ds_read_b128 v[174:177], v206 offset:38912
	ds_read_b128 v[208:211], v206 offset:39936
	global_load_lds_dwordx4 v[86:87], off
	v_lshl_add_u64 v[86:87], s[4:5], 0, v[180:181]
	s_mov_b32 m0, s26
	s_nop 0
	global_load_lds_dwordx4 v[86:87], off
	s_waitcnt lgkmcnt(8)
	s_barrier
	s_waitcnt lgkmcnt(4)
	s_setprio 1
	v_mfma_f32_16x16x32_f16 v[86:89], v[46:49], v[70:73], v[158:161]
	v_mfma_f32_16x16x32_f16 v[158:161], v[62:65], v[78:81], v[86:89]
	v_mfma_f32_16x16x32_f16 v[86:89], v[98:101], v[70:73], v[142:145]
	v_mfma_f32_16x16x32_f16 v[142:145], v[162:165], v[78:81], v[86:89]
	v_mfma_f32_16x16x32_f16 v[86:89], v[46:49], v[90:93], v[150:153]
	v_mfma_f32_16x16x32_f16 v[150:153], v[62:65], v[114:117], v[86:89]
	v_mfma_f32_16x16x32_f16 v[86:89], v[98:101], v[90:93], v[134:137]
	v_mfma_f32_16x16x32_f16 v[134:137], v[162:165], v[114:117], v[86:89]
	s_waitcnt lgkmcnt(0)
	v_mfma_f32_16x16x32_f16 v[86:89], v[46:49], v[166:169], v[154:157]
	v_mfma_f32_16x16x32_f16 v[154:157], v[62:65], v[170:173], v[86:89]
	v_mfma_f32_16x16x32_f16 v[86:89], v[98:101], v[166:169], v[138:141]
	v_mfma_f32_16x16x32_f16 v[138:141], v[162:165], v[170:173], v[86:89]
	v_mfma_f32_16x16x32_f16 v[86:89], v[46:49], v[174:177], v[146:149]
	v_mfma_f32_16x16x32_f16 v[146:149], v[62:65], v[208:211], v[86:89]
	v_mfma_f32_16x16x32_f16 v[86:89], v[98:101], v[174:177], v[130:133]
	v_mfma_f32_16x16x32_f16 v[130:133], v[162:165], v[208:211], v[86:89]
	s_setprio 0
	s_barrier
	s_add_i32 s18, 0, 0x1c000
	s_add_i32 s4, s38, s22
	v_add_u32_e32 v32, s18, v193
	s_nop 1
	v_lshl_add_u64 v[86:87], v[190:191], 0, s[84:85]
	s_mov_b32 m0, s4
	ds_read_b128 v[212:215], v32
	ds_read_b128 v[230:233], v32 offset:2048
	ds_read_b128 v[216:219], v32 offset:1024
	ds_read_b128 v[234:237], v32 offset:3072
	global_load_lds_dwordx4 v[86:87], off
	v_lshl_add_u64 v[86:87], v[238:239], 0, s[84:85]
	s_add_i32 m0, s4, 0x2000
	s_nop 0
	global_load_lds_dwordx4 v[86:87], off
	s_barrier
	s_waitcnt lgkmcnt(0)
	s_setprio 1
	s_waitcnt lgkmcnt(0)
	v_mfma_f32_16x16x32_f16 v[86:89], v[212:215], v[70:73], v[94:97]
	v_mfma_f32_16x16x32_f16 v[16:19], v[230:233], v[70:73], v[16:19]
	v_mfma_f32_16x16x32_f16 v[94:97], v[216:219], v[78:81], v[86:89]
	v_mfma_f32_16x16x32_f16 v[78:81], v[234:237], v[78:81], v[16:19]
	v_mfma_f32_16x16x32_f16 v[16:19], v[212:215], v[90:93], v[20:23]
	v_mfma_f32_16x16x32_f16 v[86:89], v[216:219], v[114:117], v[16:19]
	v_mfma_f32_16x16x32_f16 v[16:19], v[230:233], v[90:93], v[24:27]
	v_mfma_f32_16x16x32_f16 v[70:73], v[234:237], v[114:117], v[16:19]
	v_mfma_f32_16x16x32_f16 v[16:19], v[212:215], v[166:169], v[28:31]
	v_mfma_f32_16x16x32_f16 v[90:93], v[216:219], v[170:173], v[16:19]
	v_mfma_f32_16x16x32_f16 v[16:19], v[230:233], v[166:169], v[74:77]
	v_mfma_f32_16x16x32_f16 v[74:77], v[234:237], v[170:173], v[16:19]
	v_mfma_f32_16x16x32_f16 v[16:19], v[212:215], v[174:177], v[82:85]
	v_mfma_f32_16x16x32_f16 v[82:85], v[216:219], v[208:211], v[16:19]
	v_mfma_f32_16x16x32_f16 v[16:19], v[230:233], v[174:177], v[66:69]
	v_mfma_f32_16x16x32_f16 v[66:69], v[234:237], v[208:211], v[16:19]
	s_setprio 0
	s_mov_b32 m0, s28
	v_lshl_add_u64 v[114:115], v[240:241], 0, s[84:85]
	s_barrier
	s_nop 2
	ds_read_b128 v[16:19], v206 offset:49152
	ds_read_b128 v[20:23], v206 offset:50176
	ds_read_b128 v[24:27], v206 offset:51200
	ds_read_b128 v[28:31], v206 offset:52224
	ds_read_b128 v[166:169], v206 offset:53248
	ds_read_b128 v[174:177], v206 offset:55296
	ds_read_b128 v[170:173], v206 offset:54272
	ds_read_b128 v[208:211], v206 offset:56320
	global_load_lds_dwordx4 v[114:115], off
	v_lshl_add_u64 v[114:115], v[242:243], 0, s[84:85]
	s_mov_b32 m0, s29
	s_nop 0
	global_load_lds_dwordx4 v[114:115], off
	s_barrier
	s_waitcnt lgkmcnt(2)
	s_setprio 1
	v_mfma_f32_16x16x32_f16 v[114:117], v[46:49], v[16:19], v[126:129]
	v_mfma_f32_16x16x32_f16 v[126:129], v[62:65], v[20:23], v[114:117]
	v_mfma_f32_16x16x32_f16 v[114:117], v[46:49], v[24:27], v[118:121]
	v_mfma_f32_16x16x32_f16 v[118:121], v[62:65], v[28:31], v[114:117]
	v_mfma_f32_16x16x32_f16 v[114:117], v[46:49], v[166:169], v[122:125]
	v_mfma_f32_16x16x32_f16 v[0:3], v[46:49], v[174:177], v[0:3]
	v_mfma_f32_16x16x32_f16 v[110:113], v[98:101], v[16:19], v[110:113]
	v_mfma_f32_16x16x32_f16 v[102:105], v[98:101], v[24:27], v[102:105]
	s_waitcnt lgkmcnt(0)
	v_mfma_f32_16x16x32_f16 v[122:125], v[62:65], v[170:173], v[114:117]
	v_mfma_f32_16x16x32_f16 v[106:109], v[98:101], v[166:169], v[106:109]
	v_mfma_f32_16x16x32_f16 v[114:117], v[62:65], v[208:211], v[0:3]
	v_mfma_f32_16x16x32_f16 v[0:3], v[98:101], v[174:177], v[4:7]
	v_mfma_f32_16x16x32_f16 v[110:113], v[162:165], v[20:23], v[110:113]
	v_mfma_f32_16x16x32_f16 v[102:105], v[162:165], v[28:31], v[102:105]
	v_mfma_f32_16x16x32_f16 v[106:109], v[162:165], v[170:173], v[106:109]
	v_mfma_f32_16x16x32_f16 v[98:101], v[162:165], v[208:211], v[0:3]
	s_setprio 0
	s_barrier
	s_add_u32 s4, s16, 0x40080
	s_addc_u32 s5, s17, 0
	s_add_i32 s16, s18, s22
	v_lshl_add_u64 v[0:1], s[4:5], 0, v[178:179]
	s_mov_b32 m0, s16
	s_nop 0
	global_load_lds_dwordx4 v[0:1], off
	v_lshl_add_u64 v[0:1], s[4:5], 0, v[180:181]
	s_add_i32 m0, s16, 0x2000
	s_nop 0
	global_load_lds_dwordx4 v[0:1], off
	s_waitcnt vmcnt(6)
	s_barrier
	s_setprio 1
	v_mfma_f32_16x16x32_f16 v[0:3], v[212:215], v[16:19], v[8:11]
	v_mfma_f32_16x16x32_f16 v[62:65], v[216:219], v[20:23], v[0:3]
	v_mfma_f32_16x16x32_f16 v[0:3], v[230:233], v[16:19], v[12:15]
	v_mfma_f32_16x16x32_f16 v[46:49], v[234:237], v[20:23], v[0:3]
	v_mfma_f32_16x16x32_f16 v[0:3], v[212:215], v[24:27], v[54:57]
	v_mfma_f32_16x16x32_f16 v[54:57], v[216:219], v[28:31], v[0:3]
	v_mfma_f32_16x16x32_f16 v[0:3], v[230:233], v[24:27], v[38:41]
	v_mfma_f32_16x16x32_f16 v[38:41], v[234:237], v[28:31], v[0:3]
	v_mfma_f32_16x16x32_f16 v[0:3], v[212:215], v[166:169], v[58:61]
	v_mfma_f32_16x16x32_f16 v[58:61], v[216:219], v[170:173], v[0:3]
	v_mfma_f32_16x16x32_f16 v[0:3], v[230:233], v[166:169], v[42:45]
	v_mfma_f32_16x16x32_f16 v[42:45], v[234:237], v[170:173], v[0:3]
	v_mfma_f32_16x16x32_f16 v[0:3], v[212:215], v[174:177], v[50:53]
	v_mfma_f32_16x16x32_f16 v[50:53], v[216:219], v[208:211], v[0:3]
	v_mfma_f32_16x16x32_f16 v[0:3], v[230:233], v[174:177], v[34:37]
	v_mfma_f32_16x16x32_f16 v[34:37], v[234:237], v[208:211], v[0:3]
	s_setprio 0
	s_add_i32 s37, s37, 2
	s_add_u32 s7, s7, 0x100
	s_addc_u32 s36, s36, 0
	s_cmp_gt_u32 s37, 13
	s_mov_b64 s[4:5], s[14:15]
	s_barrier
	s_cbranch_scc0 .LBB0_403
	s_lshl_b32 s7, s34, 8
	s_cmp_lt_i32 s35, 28
	s_mov_b64 s[4:5], -1
	s_cbranch_scc0 .LBB0_431
	s_add_i32 s16, s7, s27
	v_or_b32_e32 v207, s16, v192
	s_cmp_gt_i32 s35, 3
	s_cbranch_scc0 .LBB0_411
	s_add_i32 s4, s35, -12
	s_cmp_gt_u32 s4, 7
	s_mov_b64 s[4:5], -1
	s_cbranch_scc0 .LBB0_408
	s_lshl_b32 s4, s35, 8
	s_add_i32 s5, s4, 0xfffffc00
	s_cmp_lt_u32 s35, 12
	s_cselect_b32 s4, s4, s5
	v_and_b32_e32 v10, 7, v220
	v_and_b32_e32 v11, 8, v220
	v_cmp_ne_u32_e32 vcc, 0, v11
	v_and_b32_e32 v12, 0x60, v194
	v_lshlrev_b32_e32 v12, 1, v12
	v_lshl_or_b32 v12, v11, 2, v12
	v_and_b32_e32 v13, 0x18, v194
	v_or_b32_e32 v12, v12, v13
	v_or_b32_e32 v32, s4, v12
	v_or_b32_e32 v14, s16, v10
	v_mov_b64_e32 v[4:5], s[70:71]
	v_mad_i64_i32 v[0:1], s[4:5], v14, s33, v[4:5]
	v_lshlrev_b64 v[6:7], 1, v[32:33]
	v_lshl_add_u64 v[16:17], v[0:1], 0, v[6:7]
	v_mov_b32_e32 v32, 0x30000
	v_lshl_add_u64 v[18:19], v[16:17], 0, v[32:33]
	v_lshl_add_u64 v[20:21], v[18:19], 0, v[32:33]
	v_lshl_add_u64 v[22:23], v[20:21], 0, v[32:33]
	v_mov_b32_e32 v8, 0x180000
	v_mov_b32_e32 v9, 0
	v_lshl_add_u64 v[24:25], v[16:17], 0, v[8:9]
	v_lshl_add_u64 v[26:27], v[24:25], 0, v[32:33]
	v_lshl_add_u64 v[28:29], v[26:27], 0, v[32:33]
	v_lshl_add_u64 v[30:31], v[28:29], 0, v[32:33]
	v_mov_b32_e32 v8, 0x18000
	v_cvt_pk_f16_f32 v158, v158, v159
	v_cvt_pk_f16_f32 v159, v160, v161
	v_cvt_pk_f16_f32 v160, v142, v143
	v_cvt_pk_f16_f32 v161, v144, v145
	v_cvt_pk_f16_f32 v94, v94, v95
	v_cvt_pk_f16_f32 v95, v96, v97
	v_cvt_pk_f16_f32 v96, v78, v79
	v_cvt_pk_f16_f32 v97, v80, v81
	v_mov_b32_dpp v0, v158 row_ror:8 row_mask:0xf bank_mask:0xf
	v_mov_b32_dpp v1, v159 row_ror:8 row_mask:0xf bank_mask:0xf
	v_mov_b32_dpp v2, v160 row_ror:8 row_mask:0xf bank_mask:0xf
	v_mov_b32_dpp v3, v161 row_ror:8 row_mask:0xf bank_mask:0xf
	v_mov_b32_dpp v4, v94 row_ror:8 row_mask:0xf bank_mask:0xf
	v_mov_b32_dpp v5, v95 row_ror:8 row_mask:0xf bank_mask:0xf
	v_mov_b32_dpp v6, v96 row_ror:8 row_mask:0xf bank_mask:0xf
	v_mov_b32_dpp v7, v97 row_ror:8 row_mask:0xf bank_mask:0xf
	v_cndmask_b32_e32 v158, v158, v4, vcc
	v_cndmask_b32_e32 v159, v159, v5, vcc
	v_cndmask_b32_e32 v160, v160, v6, vcc
	v_cndmask_b32_e32 v161, v161, v7, vcc
	v_cndmask_b32_e32 v94, v0, v94, vcc
	v_cndmask_b32_e32 v95, v1, v95, vcc
	v_cndmask_b32_e32 v96, v2, v96, vcc
	v_cndmask_b32_e32 v97, v3, v97, vcc
	v_lshl_add_u64 v[10:11], v[16:17], 0, v[8:9]
	global_store_dwordx4 v[16:17], v[158:161], off
	global_store_dwordx4 v[10:11], v[94:97], off
	v_cvt_pk_f16_f32 v150, v150, v151
	v_cvt_pk_f16_f32 v151, v152, v153
	v_cvt_pk_f16_f32 v152, v134, v135
	v_cvt_pk_f16_f32 v153, v136, v137
	v_cvt_pk_f16_f32 v86, v86, v87
	v_cvt_pk_f16_f32 v87, v88, v89
	v_cvt_pk_f16_f32 v88, v70, v71
	v_cvt_pk_f16_f32 v89, v72, v73
	v_mov_b32_dpp v0, v150 row_ror:8 row_mask:0xf bank_mask:0xf
	v_mov_b32_dpp v1, v151 row_ror:8 row_mask:0xf bank_mask:0xf
	v_mov_b32_dpp v2, v152 row_ror:8 row_mask:0xf bank_mask:0xf
	v_mov_b32_dpp v3, v153 row_ror:8 row_mask:0xf bank_mask:0xf
	v_mov_b32_dpp v4, v86 row_ror:8 row_mask:0xf bank_mask:0xf
	v_mov_b32_dpp v5, v87 row_ror:8 row_mask:0xf bank_mask:0xf
	v_mov_b32_dpp v6, v88 row_ror:8 row_mask:0xf bank_mask:0xf
	v_mov_b32_dpp v7, v89 row_ror:8 row_mask:0xf bank_mask:0xf
	v_cndmask_b32_e32 v150, v150, v4, vcc
	v_cndmask_b32_e32 v151, v151, v5, vcc
	v_cndmask_b32_e32 v152, v152, v6, vcc
	v_cndmask_b32_e32 v153, v153, v7, vcc
	v_cndmask_b32_e32 v86, v0, v86, vcc
	v_cndmask_b32_e32 v87, v1, v87, vcc
	v_cndmask_b32_e32 v88, v2, v88, vcc
	v_cndmask_b32_e32 v89, v3, v89, vcc
	v_lshl_add_u64 v[10:11], v[18:19], 0, v[8:9]
	global_store_dwordx4 v[18:19], v[150:153], off
	global_store_dwordx4 v[10:11], v[86:89], off
	v_cvt_pk_f16_f32 v154, v154, v155
	v_cvt_pk_f16_f32 v155, v156, v157
	v_cvt_pk_f16_f32 v156, v138, v139
	v_cvt_pk_f16_f32 v157, v140, v141
	v_cvt_pk_f16_f32 v90, v90, v91
	v_cvt_pk_f16_f32 v91, v92, v93
	v_cvt_pk_f16_f32 v92, v74, v75
	v_cvt_pk_f16_f32 v93, v76, v77
	v_mov_b32_dpp v0, v154 row_ror:8 row_mask:0xf bank_mask:0xf
	v_mov_b32_dpp v1, v155 row_ror:8 row_mask:0xf bank_mask:0xf
	v_mov_b32_dpp v2, v156 row_ror:8 row_mask:0xf bank_mask:0xf
	v_mov_b32_dpp v3, v157 row_ror:8 row_mask:0xf bank_mask:0xf
	v_mov_b32_dpp v4, v90 row_ror:8 row_mask:0xf bank_mask:0xf
	v_mov_b32_dpp v5, v91 row_ror:8 row_mask:0xf bank_mask:0xf
	v_mov_b32_dpp v6, v92 row_ror:8 row_mask:0xf bank_mask:0xf
	v_mov_b32_dpp v7, v93 row_ror:8 row_mask:0xf bank_mask:0xf
	v_cndmask_b32_e32 v154, v154, v4, vcc
	v_cndmask_b32_e32 v155, v155, v5, vcc
	v_cndmask_b32_e32 v156, v156, v6, vcc
	v_cndmask_b32_e32 v157, v157, v7, vcc
	v_cndmask_b32_e32 v90, v0, v90, vcc
	v_cndmask_b32_e32 v91, v1, v91, vcc
	v_cndmask_b32_e32 v92, v2, v92, vcc
	v_cndmask_b32_e32 v93, v3, v93, vcc
	v_lshl_add_u64 v[10:11], v[20:21], 0, v[8:9]
	global_store_dwordx4 v[20:21], v[154:157], off
	global_store_dwordx4 v[10:11], v[90:93], off
	v_cvt_pk_f16_f32 v146, v146, v147
	v_cvt_pk_f16_f32 v147, v148, v149
	v_cvt_pk_f16_f32 v148, v130, v131
	v_cvt_pk_f16_f32 v149, v132, v133
	v_cvt_pk_f16_f32 v82, v82, v83
	v_cvt_pk_f16_f32 v83, v84, v85
	v_cvt_pk_f16_f32 v84, v66, v67
	v_cvt_pk_f16_f32 v85, v68, v69
	v_mov_b32_dpp v0, v146 row_ror:8 row_mask:0xf bank_mask:0xf
	v_mov_b32_dpp v1, v147 row_ror:8 row_mask:0xf bank_mask:0xf
	v_mov_b32_dpp v2, v148 row_ror:8 row_mask:0xf bank_mask:0xf
	v_mov_b32_dpp v3, v149 row_ror:8 row_mask:0xf bank_mask:0xf
	v_mov_b32_dpp v4, v82 row_ror:8 row_mask:0xf bank_mask:0xf
	v_mov_b32_dpp v5, v83 row_ror:8 row_mask:0xf bank_mask:0xf
	v_mov_b32_dpp v6, v84 row_ror:8 row_mask:0xf bank_mask:0xf
	v_mov_b32_dpp v7, v85 row_ror:8 row_mask:0xf bank_mask:0xf
	v_cndmask_b32_e32 v146, v146, v4, vcc
	v_cndmask_b32_e32 v147, v147, v5, vcc
	v_cndmask_b32_e32 v148, v148, v6, vcc
	v_cndmask_b32_e32 v149, v149, v7, vcc
	v_cndmask_b32_e32 v82, v0, v82, vcc
	v_cndmask_b32_e32 v83, v1, v83, vcc
	v_cndmask_b32_e32 v84, v2, v84, vcc
	v_cndmask_b32_e32 v85, v3, v85, vcc
	v_lshl_add_u64 v[10:11], v[22:23], 0, v[8:9]
	global_store_dwordx4 v[22:23], v[146:149], off
	global_store_dwordx4 v[10:11], v[82:85], off
	v_cvt_pk_f16_f32 v126, v126, v127
	v_cvt_pk_f16_f32 v127, v128, v129
	v_cvt_pk_f16_f32 v128, v110, v111
	v_cvt_pk_f16_f32 v129, v112, v113
	v_cvt_pk_f16_f32 v62, v62, v63
	v_cvt_pk_f16_f32 v63, v64, v65
	v_cvt_pk_f16_f32 v64, v46, v47
	v_cvt_pk_f16_f32 v65, v48, v49
	v_mov_b32_dpp v0, v126 row_ror:8 row_mask:0xf bank_mask:0xf
	v_mov_b32_dpp v1, v127 row_ror:8 row_mask:0xf bank_mask:0xf
	v_mov_b32_dpp v2, v128 row_ror:8 row_mask:0xf bank_mask:0xf
	v_mov_b32_dpp v3, v129 row_ror:8 row_mask:0xf bank_mask:0xf
	v_mov_b32_dpp v4, v62 row_ror:8 row_mask:0xf bank_mask:0xf
	v_mov_b32_dpp v5, v63 row_ror:8 row_mask:0xf bank_mask:0xf
	v_mov_b32_dpp v6, v64 row_ror:8 row_mask:0xf bank_mask:0xf
	v_mov_b32_dpp v7, v65 row_ror:8 row_mask:0xf bank_mask:0xf
	v_cndmask_b32_e32 v126, v126, v4, vcc
	v_cndmask_b32_e32 v127, v127, v5, vcc
	v_cndmask_b32_e32 v128, v128, v6, vcc
	v_cndmask_b32_e32 v129, v129, v7, vcc
	v_cndmask_b32_e32 v62, v0, v62, vcc
	v_cndmask_b32_e32 v63, v1, v63, vcc
	v_cndmask_b32_e32 v64, v2, v64, vcc
	v_cndmask_b32_e32 v65, v3, v65, vcc
	v_lshl_add_u64 v[10:11], v[24:25], 0, v[8:9]
	global_store_dwordx4 v[24:25], v[126:129], off
	global_store_dwordx4 v[10:11], v[62:65], off
	v_cvt_pk_f16_f32 v118, v118, v119
	v_cvt_pk_f16_f32 v119, v120, v121
	v_cvt_pk_f16_f32 v120, v102, v103
	v_cvt_pk_f16_f32 v121, v104, v105
	v_cvt_pk_f16_f32 v54, v54, v55
	v_cvt_pk_f16_f32 v55, v56, v57
	v_cvt_pk_f16_f32 v56, v38, v39
	v_cvt_pk_f16_f32 v57, v40, v41
	v_mov_b32_dpp v0, v118 row_ror:8 row_mask:0xf bank_mask:0xf
	v_mov_b32_dpp v1, v119 row_ror:8 row_mask:0xf bank_mask:0xf
	v_mov_b32_dpp v2, v120 row_ror:8 row_mask:0xf bank_mask:0xf
	v_mov_b32_dpp v3, v121 row_ror:8 row_mask:0xf bank_mask:0xf
	v_mov_b32_dpp v4, v54 row_ror:8 row_mask:0xf bank_mask:0xf
	v_mov_b32_dpp v5, v55 row_ror:8 row_mask:0xf bank_mask:0xf
	v_mov_b32_dpp v6, v56 row_ror:8 row_mask:0xf bank_mask:0xf
	v_mov_b32_dpp v7, v57 row_ror:8 row_mask:0xf bank_mask:0xf
	v_cndmask_b32_e32 v118, v118, v4, vcc
	v_cndmask_b32_e32 v119, v119, v5, vcc
	v_cndmask_b32_e32 v120, v120, v6, vcc
	v_cndmask_b32_e32 v121, v121, v7, vcc
	v_cndmask_b32_e32 v54, v0, v54, vcc
	v_cndmask_b32_e32 v55, v1, v55, vcc
	v_cndmask_b32_e32 v56, v2, v56, vcc
	v_cndmask_b32_e32 v57, v3, v57, vcc
	v_lshl_add_u64 v[10:11], v[26:27], 0, v[8:9]
	global_store_dwordx4 v[26:27], v[118:121], off
	global_store_dwordx4 v[10:11], v[54:57], off
	v_cvt_pk_f16_f32 v122, v122, v123
	v_cvt_pk_f16_f32 v123, v124, v125
	v_cvt_pk_f16_f32 v124, v106, v107
	v_cvt_pk_f16_f32 v125, v108, v109
	v_cvt_pk_f16_f32 v58, v58, v59
	v_cvt_pk_f16_f32 v59, v60, v61
	v_cvt_pk_f16_f32 v60, v42, v43
	v_cvt_pk_f16_f32 v61, v44, v45
	v_mov_b32_dpp v0, v122 row_ror:8 row_mask:0xf bank_mask:0xf
	v_mov_b32_dpp v1, v123 row_ror:8 row_mask:0xf bank_mask:0xf
	v_mov_b32_dpp v2, v124 row_ror:8 row_mask:0xf bank_mask:0xf
	v_mov_b32_dpp v3, v125 row_ror:8 row_mask:0xf bank_mask:0xf
	v_mov_b32_dpp v4, v58 row_ror:8 row_mask:0xf bank_mask:0xf
	v_mov_b32_dpp v5, v59 row_ror:8 row_mask:0xf bank_mask:0xf
	v_mov_b32_dpp v6, v60 row_ror:8 row_mask:0xf bank_mask:0xf
	v_mov_b32_dpp v7, v61 row_ror:8 row_mask:0xf bank_mask:0xf
	v_cndmask_b32_e32 v122, v122, v4, vcc
	v_cndmask_b32_e32 v123, v123, v5, vcc
	v_cndmask_b32_e32 v124, v124, v6, vcc
	v_cndmask_b32_e32 v125, v125, v7, vcc
	v_cndmask_b32_e32 v58, v0, v58, vcc
	v_cndmask_b32_e32 v59, v1, v59, vcc
	v_cndmask_b32_e32 v60, v2, v60, vcc
	v_cndmask_b32_e32 v61, v3, v61, vcc
	v_lshl_add_u64 v[10:11], v[28:29], 0, v[8:9]
	global_store_dwordx4 v[28:29], v[122:125], off
	global_store_dwordx4 v[10:11], v[58:61], off
	v_cvt_pk_f16_f32 v114, v114, v115
	v_cvt_pk_f16_f32 v115, v116, v117
	v_cvt_pk_f16_f32 v116, v98, v99
	v_cvt_pk_f16_f32 v117, v100, v101
	v_cvt_pk_f16_f32 v50, v50, v51
	v_cvt_pk_f16_f32 v51, v52, v53
	v_cvt_pk_f16_f32 v52, v34, v35
	v_cvt_pk_f16_f32 v53, v36, v37
	v_mov_b32_dpp v0, v114 row_ror:8 row_mask:0xf bank_mask:0xf
	v_mov_b32_dpp v1, v115 row_ror:8 row_mask:0xf bank_mask:0xf
	v_mov_b32_dpp v2, v116 row_ror:8 row_mask:0xf bank_mask:0xf
	v_mov_b32_dpp v3, v117 row_ror:8 row_mask:0xf bank_mask:0xf
	v_mov_b32_dpp v4, v50 row_ror:8 row_mask:0xf bank_mask:0xf
	v_mov_b32_dpp v5, v51 row_ror:8 row_mask:0xf bank_mask:0xf
	v_mov_b32_dpp v6, v52 row_ror:8 row_mask:0xf bank_mask:0xf
	v_mov_b32_dpp v7, v53 row_ror:8 row_mask:0xf bank_mask:0xf
	v_cndmask_b32_e32 v114, v114, v4, vcc
	v_cndmask_b32_e32 v115, v115, v5, vcc
	v_cndmask_b32_e32 v116, v116, v6, vcc
	v_cndmask_b32_e32 v117, v117, v7, vcc
	v_cndmask_b32_e32 v50, v0, v50, vcc
	v_cndmask_b32_e32 v51, v1, v51, vcc
	v_cndmask_b32_e32 v52, v2, v52, vcc
	v_cndmask_b32_e32 v53, v3, v53, vcc
	v_lshl_add_u64 v[10:11], v[30:31], 0, v[8:9]
	global_store_dwordx4 v[30:31], v[114:117], off
	global_store_dwordx4 v[10:11], v[50:53], off
	s_mov_b64 s[4:5], 0

.LBB0_940:
	s_add_u32 s20, s14, 0x100
	s_addc_u32 s21, s15, 0
	s_add_i32 s40, 0, 0x10000
	v_add_u32_e32 v32, s40, v209
	ds_read_b128 v[132:135], v32
	ds_read_b128 v[140:143], v32 offset:2048
	ds_read_b128 v[136:139], v32 offset:1024
	ds_read_b128 v[144:147], v32 offset:3072
	s_cmp_eq_u32 s11, 12
	s_cselect_b32 s25, s17, s21
	s_cselect_b32 s24, s16, s20
	s_cselect_b32 s23, s19, s3
	s_cselect_b32 s22, s18, s1
	v_lshl_add_u64 v[34:35], s[14:15], 0, v[200:201]
	s_add_i32 m0, s30, 0xc000
	ds_read_b128 v[148:151], v211
	ds_read_b128 v[156:159], v211 offset:2048
	ds_read_b128 v[164:167], v211 offset:4096
	ds_read_b128 v[172:175], v211 offset:6144
	ds_read_b128 v[152:155], v211 offset:1024
	ds_read_b128 v[160:163], v211 offset:3072
	ds_read_b128 v[168:171], v211 offset:5120
	ds_read_b128 v[176:179], v211 offset:7168
	global_load_lds_dwordx4 v[34:35], off
	v_lshl_add_u64 v[34:35], s[14:15], 0, v[202:203]
	s_add_i32 m0, s30, 0xe000
	s_nop 0
	global_load_lds_dwordx4 v[34:35], off
	s_waitcnt lgkmcnt(8)
	s_barrier
	s_waitcnt lgkmcnt(4)
	s_setprio 1
	v_mfma_f32_16x16x32_f16 v[128:131], v[132:135], v[148:151], v[128:131]
	v_mfma_f32_16x16x32_f16 v[124:127], v[140:143], v[148:151], v[124:127]
	v_mfma_f32_16x16x32_f16 v[120:123], v[132:135], v[156:159], v[120:123]
	v_mfma_f32_16x16x32_f16 v[116:119], v[140:143], v[156:159], v[116:119]
	v_mfma_f32_16x16x32_f16 v[112:115], v[132:135], v[164:167], v[112:115]
	v_mfma_f32_16x16x32_f16 v[108:111], v[140:143], v[164:167], v[108:111]
	v_mfma_f32_16x16x32_f16 v[104:107], v[132:135], v[172:175], v[104:107]
	v_mfma_f32_16x16x32_f16 v[100:103], v[140:143], v[172:175], v[100:103]
	s_waitcnt lgkmcnt(0)
	v_mfma_f32_16x16x32_f16 v[128:131], v[136:139], v[152:155], v[128:131]
	v_mfma_f32_16x16x32_f16 v[124:127], v[144:147], v[152:155], v[124:127]
	v_mfma_f32_16x16x32_f16 v[120:123], v[136:139], v[160:163], v[120:123]
	v_mfma_f32_16x16x32_f16 v[116:119], v[144:147], v[160:163], v[116:119]
	v_mfma_f32_16x16x32_f16 v[112:115], v[136:139], v[168:171], v[112:115]
	v_mfma_f32_16x16x32_f16 v[108:111], v[144:147], v[168:171], v[108:111]
	v_mfma_f32_16x16x32_f16 v[104:107], v[136:139], v[176:179], v[104:107]
	v_mfma_f32_16x16x32_f16 v[100:103], v[144:147], v[176:179], v[100:103]
	s_setprio 0
	s_barrier
	s_add_i32 s41, 0, 0x14000
	s_add_i32 s14, s40, s29
	v_add_u32_e32 v32, s41, v209
	v_lshl_add_u64 v[204:205], s[22:23], 0, v[196:197]
	s_mov_b32 m0, s14
	ds_read_b128 v[180:183], v32
	ds_read_b128 v[188:191], v32 offset:2048
	ds_read_b128 v[184:187], v32 offset:1024
	ds_read_b128 v[192:195], v32 offset:3072
	global_load_lds_dwordx4 v[204:205], off
	v_lshl_add_u64 v[206:207], s[22:23], 0, v[198:199]
	s_add_i32 m0, s14, 0x2000
	s_nop 0
	global_load_lds_dwordx4 v[206:207], off
	s_barrier
	s_waitcnt lgkmcnt(2)
	s_setprio 1
	v_mfma_f32_16x16x32_f16 v[96:99], v[180:183], v[148:151], v[96:99]
	v_mfma_f32_16x16x32_f16 v[92:95], v[188:191], v[148:151], v[92:95]
	v_mfma_f32_16x16x32_f16 v[88:91], v[180:183], v[156:159], v[88:91]
	v_mfma_f32_16x16x32_f16 v[84:87], v[188:191], v[156:159], v[84:87]
	v_mfma_f32_16x16x32_f16 v[80:83], v[180:183], v[164:167], v[80:83]
	v_mfma_f32_16x16x32_f16 v[76:79], v[188:191], v[164:167], v[76:79]
	v_mfma_f32_16x16x32_f16 v[72:75], v[180:183], v[172:175], v[72:75]
	v_mfma_f32_16x16x32_f16 v[68:71], v[188:191], v[172:175], v[68:71]
	s_waitcnt lgkmcnt(0)
	v_mfma_f32_16x16x32_f16 v[96:99], v[184:187], v[152:155], v[96:99]
	v_mfma_f32_16x16x32_f16 v[92:95], v[192:195], v[152:155], v[92:95]
	v_mfma_f32_16x16x32_f16 v[88:91], v[184:187], v[160:163], v[88:91]
	v_mfma_f32_16x16x32_f16 v[84:87], v[192:195], v[160:163], v[84:87]
	v_mfma_f32_16x16x32_f16 v[80:83], v[184:187], v[168:171], v[80:83]
	v_mfma_f32_16x16x32_f16 v[76:79], v[192:195], v[168:171], v[76:79]
	v_mfma_f32_16x16x32_f16 v[72:75], v[184:187], v[176:179], v[72:75]
	v_mfma_f32_16x16x32_f16 v[68:71], v[192:195], v[176:179], v[68:71]
	s_setprio 0
	s_mov_b32 m0, s30
	v_lshl_add_u64 v[212:213], s[24:25], 0, v[196:197]
	s_barrier
	ds_read_b128 v[148:151], v211 offset:16384
	ds_read_b128 v[156:159], v211 offset:18432
	ds_read_b128 v[164:167], v211 offset:20480
	ds_read_b128 v[172:175], v211 offset:22528
	ds_read_b128 v[152:155], v211 offset:17408
	ds_read_b128 v[160:163], v211 offset:19456
	ds_read_b128 v[168:171], v211 offset:21504
	ds_read_b128 v[176:179], v211 offset:23552
	global_load_lds_dwordx4 v[212:213], off
	v_lshl_add_u64 v[214:215], s[24:25], 0, v[198:199]
	s_mov_b32 m0, s31
	s_nop 0
	global_load_lds_dwordx4 v[214:215], off
	s_barrier
	s_waitcnt lgkmcnt(4)
	s_setprio 1
	v_mfma_f32_16x16x32_f16 v[64:67], v[132:135], v[148:151], v[64:67]
	v_mfma_f32_16x16x32_f16 v[60:63], v[140:143], v[148:151], v[60:63]
	v_mfma_f32_16x16x32_f16 v[56:59], v[132:135], v[156:159], v[56:59]
	v_mfma_f32_16x16x32_f16 v[52:55], v[140:143], v[156:159], v[52:55]
	v_mfma_f32_16x16x32_f16 v[48:51], v[132:135], v[164:167], v[48:51]
	v_mfma_f32_16x16x32_f16 v[44:47], v[140:143], v[164:167], v[44:47]
	v_mfma_f32_16x16x32_f16 v[40:43], v[132:135], v[172:175], v[40:43]
	v_mfma_f32_16x16x32_f16 v[34:37], v[140:143], v[172:175], v[36:39]
	s_waitcnt lgkmcnt(0)
	v_mfma_f32_16x16x32_f16 v[64:67], v[136:139], v[152:155], v[64:67]
	v_mfma_f32_16x16x32_f16 v[60:63], v[144:147], v[152:155], v[60:63]
	v_mfma_f32_16x16x32_f16 v[56:59], v[136:139], v[160:163], v[56:59]
	v_mfma_f32_16x16x32_f16 v[52:55], v[144:147], v[160:163], v[52:55]
	v_mfma_f32_16x16x32_f16 v[48:51], v[136:139], v[168:171], v[48:51]
	v_mfma_f32_16x16x32_f16 v[44:47], v[144:147], v[168:171], v[44:47]
	v_mfma_f32_16x16x32_f16 v[40:43], v[136:139], v[176:179], v[40:43]
	v_mfma_f32_16x16x32_f16 v[34:37], v[144:147], v[176:179], v[34:37]
	s_setprio 0
	s_barrier
	s_add_u32 s14, s22, 0x40000
	s_addc_u32 s15, s23, 0
	s_add_i32 s40, s41, s29
	v_lshl_add_u64 v[38:39], s[14:15], 0, v[196:197]
	s_mov_b32 m0, s40
	s_nop 0
	global_load_lds_dwordx4 v[38:39], off
	v_lshl_add_u64 v[38:39], s[14:15], 0, v[198:199]
	s_add_i32 m0, s40, 0x2000
	s_nop 0
	global_load_lds_dwordx4 v[38:39], off
	s_waitcnt vmcnt(6)
	s_barrier
	s_setprio 1
	v_mfma_f32_16x16x32_f16 v[28:31], v[180:183], v[148:151], v[28:31]
	v_mfma_f32_16x16x32_f16 v[24:27], v[188:191], v[148:151], v[24:27]
	v_mfma_f32_16x16x32_f16 v[20:23], v[180:183], v[156:159], v[20:23]
	v_mfma_f32_16x16x32_f16 v[16:19], v[188:191], v[156:159], v[16:19]
	v_mfma_f32_16x16x32_f16 v[12:15], v[180:183], v[164:167], v[12:15]
	v_mfma_f32_16x16x32_f16 v[8:11], v[188:191], v[164:167], v[8:11]
	v_mfma_f32_16x16x32_f16 v[4:7], v[180:183], v[172:175], v[4:7]
	v_mfma_f32_16x16x32_f16 v[0:3], v[188:191], v[172:175], v[0:3]
	v_mfma_f32_16x16x32_f16 v[28:31], v[184:187], v[152:155], v[28:31]
	v_mfma_f32_16x16x32_f16 v[24:27], v[192:195], v[152:155], v[24:27]
	v_mfma_f32_16x16x32_f16 v[20:23], v[184:187], v[160:163], v[20:23]
	v_mfma_f32_16x16x32_f16 v[16:19], v[192:195], v[160:163], v[16:19]
	v_mfma_f32_16x16x32_f16 v[12:15], v[184:187], v[168:171], v[12:15]
	v_mfma_f32_16x16x32_f16 v[8:11], v[192:195], v[168:171], v[8:11]
	v_mfma_f32_16x16x32_f16 v[4:7], v[184:187], v[176:179], v[4:7]
	v_mfma_f32_16x16x32_f16 v[0:3], v[192:195], v[176:179], v[0:3]
	s_setprio 0
	s_add_i32 s40, 0, 0x18000
	v_add_u32_e32 v32, s40, v209
	s_barrier
	ds_read_b128 v[132:135], v32
	ds_read_b128 v[140:143], v32 offset:2048
	ds_read_b128 v[136:139], v32 offset:1024
	ds_read_b128 v[144:147], v32 offset:3072
	s_add_u32 s14, s24, 0x40000
	s_addc_u32 s15, s25, 0
	s_mov_b32 m0, s34
	v_lshl_add_u64 v[38:39], s[14:15], 0, v[196:197]
	ds_read_b128 v[148:151], v211 offset:32768
	ds_read_b128 v[156:159], v211 offset:34816
	ds_read_b128 v[164:167], v211 offset:36864
	ds_read_b128 v[172:175], v211 offset:38912
	ds_read_b128 v[152:155], v211 offset:33792
	ds_read_b128 v[160:163], v211 offset:35840
	ds_read_b128 v[168:171], v211 offset:37888
	ds_read_b128 v[176:179], v211 offset:39936
	global_load_lds_dwordx4 v[38:39], off
	v_lshl_add_u64 v[38:39], s[14:15], 0, v[198:199]
	s_mov_b32 m0, s35
	s_nop 0
	global_load_lds_dwordx4 v[38:39], off
	s_waitcnt lgkmcnt(8)
	s_barrier
	s_waitcnt lgkmcnt(4)
	s_setprio 1
	v_mfma_f32_16x16x32_f16 v[128:131], v[132:135], v[148:151], v[128:131]
	v_mfma_f32_16x16x32_f16 v[124:127], v[140:143], v[148:151], v[124:127]
	v_mfma_f32_16x16x32_f16 v[120:123], v[132:135], v[156:159], v[120:123]
	v_mfma_f32_16x16x32_f16 v[116:119], v[140:143], v[156:159], v[116:119]
	v_mfma_f32_16x16x32_f16 v[112:115], v[132:135], v[164:167], v[112:115]
	v_mfma_f32_16x16x32_f16 v[108:111], v[140:143], v[164:167], v[108:111]
	v_mfma_f32_16x16x32_f16 v[104:107], v[132:135], v[172:175], v[104:107]
	v_mfma_f32_16x16x32_f16 v[100:103], v[140:143], v[172:175], v[100:103]
	s_waitcnt lgkmcnt(0)
	v_mfma_f32_16x16x32_f16 v[128:131], v[136:139], v[152:155], v[128:131]
	v_mfma_f32_16x16x32_f16 v[124:127], v[144:147], v[152:155], v[124:127]
	v_mfma_f32_16x16x32_f16 v[120:123], v[136:139], v[160:163], v[120:123]
	v_mfma_f32_16x16x32_f16 v[116:119], v[144:147], v[160:163], v[116:119]
	v_mfma_f32_16x16x32_f16 v[112:115], v[136:139], v[168:171], v[112:115]
	v_mfma_f32_16x16x32_f16 v[108:111], v[144:147], v[168:171], v[108:111]
	v_mfma_f32_16x16x32_f16 v[104:107], v[136:139], v[176:179], v[104:107]
	v_mfma_f32_16x16x32_f16 v[100:103], v[144:147], v[176:179], v[100:103]
	s_setprio 0
	s_barrier
	s_add_i32 s24, 0, 0x1c000
	s_add_i32 s14, s40, s29
	v_add_u32_e32 v32, s24, v209
	v_lshl_add_u64 v[38:39], v[204:205], 0, s[84:85]
	s_mov_b32 m0, s14
	ds_read_b128 v[180:183], v32
	ds_read_b128 v[188:191], v32 offset:2048
	ds_read_b128 v[184:187], v32 offset:1024
	ds_read_b128 v[192:195], v32 offset:3072
	global_load_lds_dwordx4 v[38:39], off
	v_lshl_add_u64 v[38:39], v[206:207], 0, s[84:85]
	s_add_i32 m0, s14, 0x2000
	s_nop 0
	global_load_lds_dwordx4 v[38:39], off
	s_barrier
	s_waitcnt lgkmcnt(2)
	s_setprio 1
	v_mfma_f32_16x16x32_f16 v[96:99], v[180:183], v[148:151], v[96:99]
	v_mfma_f32_16x16x32_f16 v[92:95], v[188:191], v[148:151], v[92:95]
	v_mfma_f32_16x16x32_f16 v[88:91], v[180:183], v[156:159], v[88:91]
	v_mfma_f32_16x16x32_f16 v[84:87], v[188:191], v[156:159], v[84:87]
	v_mfma_f32_16x16x32_f16 v[80:83], v[180:183], v[164:167], v[80:83]
	v_mfma_f32_16x16x32_f16 v[76:79], v[188:191], v[164:167], v[76:79]
	v_mfma_f32_16x16x32_f16 v[72:75], v[180:183], v[172:175], v[72:75]
	v_mfma_f32_16x16x32_f16 v[68:71], v[188:191], v[172:175], v[68:71]
	s_waitcnt lgkmcnt(0)
	v_mfma_f32_16x16x32_f16 v[96:99], v[184:187], v[152:155], v[96:99]
	v_mfma_f32_16x16x32_f16 v[92:95], v[192:195], v[152:155], v[92:95]
	v_mfma_f32_16x16x32_f16 v[88:91], v[184:187], v[160:163], v[88:91]
	v_mfma_f32_16x16x32_f16 v[84:87], v[192:195], v[160:163], v[84:87]
	v_mfma_f32_16x16x32_f16 v[80:83], v[184:187], v[168:171], v[80:83]
	v_mfma_f32_16x16x32_f16 v[76:79], v[192:195], v[168:171], v[76:79]
	v_mfma_f32_16x16x32_f16 v[72:75], v[184:187], v[176:179], v[72:75]
	v_mfma_f32_16x16x32_f16 v[68:71], v[192:195], v[176:179], v[68:71]
	s_setprio 0
	s_mov_b32 m0, s36
	v_lshl_add_u64 v[38:39], v[212:213], 0, s[84:85]
	s_barrier
	ds_read_b128 v[148:151], v211 offset:49152
	ds_read_b128 v[156:159], v211 offset:51200
	ds_read_b128 v[164:167], v211 offset:53248
	ds_read_b128 v[172:175], v211 offset:55296
	ds_read_b128 v[152:155], v211 offset:50176
	ds_read_b128 v[160:163], v211 offset:52224
	ds_read_b128 v[168:171], v211 offset:54272
	ds_read_b128 v[176:179], v211 offset:56320
	global_load_lds_dwordx4 v[38:39], off
	v_lshl_add_u64 v[38:39], v[214:215], 0, s[84:85]
	s_mov_b32 m0, s37
	s_nop 0
	global_load_lds_dwordx4 v[38:39], off
	s_barrier
	s_waitcnt lgkmcnt(4)
	s_setprio 1
	v_mfma_f32_16x16x32_f16 v[64:67], v[132:135], v[148:151], v[64:67]
	v_mfma_f32_16x16x32_f16 v[60:63], v[140:143], v[148:151], v[60:63]
	v_mfma_f32_16x16x32_f16 v[56:59], v[132:135], v[156:159], v[56:59]
	v_mfma_f32_16x16x32_f16 v[52:55], v[140:143], v[156:159], v[52:55]
	v_mfma_f32_16x16x32_f16 v[48:51], v[132:135], v[164:167], v[48:51]
	v_mfma_f32_16x16x32_f16 v[44:47], v[140:143], v[164:167], v[44:47]
	v_mfma_f32_16x16x32_f16 v[38:41], v[132:135], v[172:175], v[40:43]
	v_mfma_f32_16x16x32_f16 v[34:37], v[140:143], v[172:175], v[34:37]
	s_waitcnt lgkmcnt(0)
	v_mfma_f32_16x16x32_f16 v[64:67], v[136:139], v[152:155], v[64:67]
	v_mfma_f32_16x16x32_f16 v[60:63], v[144:147], v[152:155], v[60:63]
	v_mfma_f32_16x16x32_f16 v[56:59], v[136:139], v[160:163], v[56:59]
	v_mfma_f32_16x16x32_f16 v[52:55], v[144:147], v[160:163], v[52:55]
	v_mfma_f32_16x16x32_f16 v[48:51], v[136:139], v[168:171], v[48:51]
	v_mfma_f32_16x16x32_f16 v[44:47], v[144:147], v[168:171], v[44:47]
	v_mfma_f32_16x16x32_f16 v[40:43], v[136:139], v[176:179], v[38:41]
	v_mfma_f32_16x16x32_f16 v[36:39], v[144:147], v[176:179], v[34:37]
	s_setprio 0
	s_barrier
	s_add_u32 s14, s22, 0x40080
	s_addc_u32 s15, s23, 0
	s_add_i32 s22, s24, s29
	v_lshl_add_u64 v[34:35], s[14:15], 0, v[196:197]
	s_mov_b32 m0, s22
	s_nop 0
	global_load_lds_dwordx4 v[34:35], off
	v_lshl_add_u64 v[34:35], s[14:15], 0, v[198:199]
	s_add_i32 m0, s22, 0x2000
	s_nop 0
	global_load_lds_dwordx4 v[34:35], off
	s_waitcnt vmcnt(6)
	s_barrier
	s_setprio 1
	v_mfma_f32_16x16x32_f16 v[28:31], v[180:183], v[148:151], v[28:31]
	v_mfma_f32_16x16x32_f16 v[24:27], v[188:191], v[148:151], v[24:27]
	v_mfma_f32_16x16x32_f16 v[20:23], v[180:183], v[156:159], v[20:23]
	v_mfma_f32_16x16x32_f16 v[16:19], v[188:191], v[156:159], v[16:19]
	v_mfma_f32_16x16x32_f16 v[12:15], v[180:183], v[164:167], v[12:15]
	v_mfma_f32_16x16x32_f16 v[8:11], v[188:191], v[164:167], v[8:11]
	v_mfma_f32_16x16x32_f16 v[4:7], v[180:183], v[172:175], v[4:7]
	v_mfma_f32_16x16x32_f16 v[0:3], v[188:191], v[172:175], v[0:3]
	v_mfma_f32_16x16x32_f16 v[28:31], v[184:187], v[152:155], v[28:31]
	v_mfma_f32_16x16x32_f16 v[24:27], v[192:195], v[152:155], v[24:27]
	v_mfma_f32_16x16x32_f16 v[20:23], v[184:187], v[160:163], v[20:23]
	v_mfma_f32_16x16x32_f16 v[16:19], v[192:195], v[160:163], v[16:19]
	v_mfma_f32_16x16x32_f16 v[12:15], v[184:187], v[168:171], v[12:15]
	v_mfma_f32_16x16x32_f16 v[8:11], v[192:195], v[168:171], v[8:11]
	v_mfma_f32_16x16x32_f16 v[4:7], v[184:187], v[176:179], v[4:7]
	v_mfma_f32_16x16x32_f16 v[0:3], v[192:195], v[176:179], v[0:3]
	s_setprio 0
	s_add_i32 s11, s11, 2
	s_add_u32 s1, s1, 0x100
	s_addc_u32 s3, s3, 0
	s_cmp_gt_u32 s11, 13
	s_mov_b64 s[14:15], s[20:21]
	s_barrier
	s_cbranch_scc0 .LBB0_940
	v_lshl_add_u32 v34, s12, 8, v208
	v_lshl_or_b32 v156, s10, 8, v210
	s_cmp_lg_u32 s13, 0
	s_cselect_b64 s[10:11], -1, 0
	s_cmp_eq_u32 s13, 0
	v_ashrrev_i32_e32 v157, 31, v156
	v_ashrrev_i32_e32 v35, 31, v34
	v_mad_i64_i32 v[158:159], s[12:13], v34, s33, 0
	v_or_b32_e32 v160, 16, v34
	v_or_b32_e32 v162, 32, v34
	v_or_b32_e32 v164, 48, v34
	s_cbranch_scc1 .LBB0_946
	v_lshl_add_u64 v[132:133], s[70:71], 0, v[158:159]
	v_lshlrev_b64 v[166:167], 1, v[156:157]
	v_lshl_add_u64 v[132:133], v[132:133], 0, v[166:167]
	s_mov_b64 s[16:17], 0x2800
	v_mov_b64_e32 v[168:169], s[70:71]
	s_movk_i32 s1, 0x2000
	v_lshl_add_u64 v[134:135], v[132:133], 0, s[16:17]
	v_mad_i64_i32 v[136:137], s[12:13], v160, s33, v[168:169]
	v_add_co_u32_e32 v132, vcc, s1, v132
	v_lshl_add_u64 v[136:137], v[136:137], 0, v[166:167]
	s_nop 0
	v_addc_co_u32_e32 v133, vcc, 0, v133, vcc
	v_lshl_add_u64 v[138:139], v[136:137], 0, s[16:17]
	v_mad_i64_i32 v[140:141], s[12:13], v162, s33, v[168:169]
	v_add_co_u32_e32 v136, vcc, s1, v136
	v_lshl_add_u64 v[140:141], v[140:141], 0, v[166:167]
	s_nop 0
	v_addc_co_u32_e32 v137, vcc, 0, v137, vcc
	v_mad_i64_i32 v[144:145], s[12:13], v164, s33, v[168:169]
	global_load_dwordx4 v[170:173], v[132:133], off offset:2048
	global_load_dwordx4 v[152:155], v[136:137], off offset:2048
	global_load_dwordx4 v[174:177], v[134:135], off offset:256
	global_load_dwordx4 v[148:151], v[138:139], off offset:256
	v_add_co_u32_e32 v132, vcc, s1, v140
	v_lshl_add_u64 v[144:145], v[144:145], 0, v[166:167]
	s_nop 0
	v_addc_co_u32_e32 v133, vcc, 0, v141, vcc
	v_add_co_u32_e32 v134, vcc, s1, v144
	v_lshl_add_u64 v[142:143], v[140:141], 0, s[16:17]
	s_nop 0
	v_addc_co_u32_e32 v135, vcc, 0, v145, vcc
	v_lshl_add_u64 v[178:179], v[144:145], 0, s[16:17]
	global_load_dwordx4 v[144:147], v[132:133], off offset:2048
	global_load_dwordx4 v[136:139], v[134:135], off offset:2048
	s_nop 0
	global_load_dwordx4 v[140:143], v[142:143], off offset:256
	s_nop 0
	global_load_dwordx4 v[132:135], v[178:179], off offset:256
	v_ashrrev_i32_e32 v161, 31, v160
	v_ashrrev_i32_e32 v163, 31, v162
	v_ashrrev_i32_e32 v165, 31, v164
	s_waitcnt vmcnt(0)
	v_cvt_f32_f16_e32 v32, v170
	v_cvt_f32_f16_sdwa v170, v170 dst_sel:DWORD dst_unused:UNUSED_PAD src0_sel:WORD_1
	v_lshlrev_b64 v[178:179], 11, v[34:35]
	v_readlane_b32 s14, v252, 9
	v_max_f32_e32 v32, 0xc1f00000, v32
	v_max_f32_e32 v35, 0xc1f00000, v170
	v_cvt_f32_f16_e32 v170, v171
	v_cvt_f32_f16_sdwa v171, v171 dst_sel:DWORD dst_unused:UNUSED_PAD src0_sel:WORD_1
	v_mul_f32_e32 v35, 0xbfb8aa3b, v35
	v_exp_f32_e32 v35, v35
	v_max_f32_e32 v170, 0xc1f00000, v170
	v_mul_f32_e32 v170, 0xbfb8aa3b, v170
	v_exp_f32_e32 v180, v170
	v_max_f32_e32 v170, 0xc1f00000, v171
	v_mul_f32_e32 v170, 0xbfb8aa3b, v170
	v_cvt_f32_f16_e32 v171, v172
	v_exp_f32_e32 v181, v170
	v_cvt_f32_f16_sdwa v170, v172 dst_sel:DWORD dst_unused:UNUSED_PAD src0_sel:WORD_1
	v_mul_f32_e32 v32, 0xbfb8aa3b, v32
	v_max_f32_e32 v171, 0xc1f00000, v171
	v_mul_f32_e32 v171, 0xbfb8aa3b, v171
	v_max_f32_e32 v170, 0xc1f00000, v170
	v_mul_f32_e32 v170, 0xbfb8aa3b, v170
	v_exp_f32_e32 v182, v171
	v_cvt_f32_f16_e32 v171, v173
	v_exp_f32_e32 v183, v170
	v_cvt_f32_f16_sdwa v170, v173 dst_sel:DWORD dst_unused:UNUSED_PAD src0_sel:WORD_1
	v_exp_f32_e32 v32, v32
	v_max_f32_e32 v171, 0xc1f00000, v171
	v_mul_f32_e32 v171, 0xbfb8aa3b, v171
	v_max_f32_e32 v170, 0xc1f00000, v170
	v_mul_f32_e32 v170, 0xbfb8aa3b, v170
	v_add_f32_e32 v35, 1.0, v35
	v_exp_f32_e32 v184, v171
	v_exp_f32_e32 v185, v170
	v_rcp_f32_e32 v170, v35
	v_add_f32_e32 v35, 1.0, v180
	v_rcp_f32_e32 v171, v35
	v_add_f32_e32 v35, 1.0, v181
	v_add_f32_e32 v32, 1.0, v32
	v_rcp_f32_e32 v172, v35
	v_add_f32_e32 v35, 1.0, v182
	v_rcp_f32_e32 v32, v32
	v_rcp_f32_e32 v173, v35
	v_add_f32_e32 v35, 1.0, v183
	v_rcp_f32_e32 v180, v35
	v_add_f32_e32 v35, 1.0, v184
	v_rcp_f32_e32 v181, v35
	v_mov_b32_e32 v182, v129
	v_mov_b32_e32 v183, v130
	v_pk_mul_f32 v[170:171], v[182:183], v[170:171]
	v_pk_mov_b32 v[182:183], v[130:131], v[124:125] op_sel:[1,0]
	v_add_f32_e32 v35, 1.0, v185
	v_fma_mixlo_f16 v32, v128, v32, 0
	v_cvt_pk_f16_f32 v171, v170, v171
	v_pk_mul_f32 v[172:173], v[182:183], v[172:173]
	v_rcp_f32_e32 v35, v35
	v_pack_b32_f16 v170, v32, v171
	v_cvt_pk_f16_f32 v32, v172, v173
	v_mov_b32_e32 v172, v125
	v_mov_b32_e32 v173, v126
	v_pk_mul_f32 v[172:173], v[172:173], v[180:181]
	v_readlane_b32 s15, v252, 10
	v_cvt_pk_f16_f32 v173, v172, v173
	v_alignbit_b32 v172, v173, v32, 16
	v_lshrrev_b32_e32 v173, 16, v173
	v_lshl_add_u64 v[178:179], s[14:15], 0, v[178:179]
	v_alignbit_b32 v171, v32, v171, 16
	v_fma_mixhi_f16 v173, v127, v35, 0
	v_lshl_add_u64 v[178:179], v[178:179], 0, v[166:167]
	global_store_dwordx4 v[178:179], v[170:173], off
	v_cvt_f32_f16_sdwa v35, v174 dst_sel:DWORD dst_unused:UNUSED_PAD src0_sel:WORD_1
	v_cvt_f32_f16_e32 v32, v174
	v_cvt_f32_f16_e32 v170, v175
	v_cvt_f32_f16_sdwa v171, v175 dst_sel:DWORD dst_unused:UNUSED_PAD src0_sel:WORD_1
	v_max_f32_e32 v35, 0xc1f00000, v35
	v_mul_f32_e32 v35, 0xbfb8aa3b, v35
	v_max_f32_e32 v170, 0xc1f00000, v170
	v_mul_f32_e32 v170, 0xbfb8aa3b, v170
	v_exp_f32_e32 v172, v170
	v_max_f32_e32 v170, 0xc1f00000, v171
	v_mul_f32_e32 v170, 0xbfb8aa3b, v170
	v_cvt_f32_f16_e32 v171, v176
	v_exp_f32_e32 v173, v170
	v_cvt_f32_f16_sdwa v170, v176 dst_sel:DWORD dst_unused:UNUSED_PAD src0_sel:WORD_1
	v_exp_f32_e32 v35, v35
	v_max_f32_e32 v171, 0xc1f00000, v171
	v_mul_f32_e32 v171, 0xbfb8aa3b, v171
	v_max_f32_e32 v170, 0xc1f00000, v170
	v_mul_f32_e32 v170, 0xbfb8aa3b, v170
	v_exp_f32_e32 v174, v171
	v_cvt_f32_f16_e32 v171, v177
	v_exp_f32_e32 v175, v170
	v_cvt_f32_f16_sdwa v170, v177 dst_sel:DWORD dst_unused:UNUSED_PAD src0_sel:WORD_1
	v_max_f32_e32 v32, 0xc1f00000, v32
	v_mul_f32_e32 v32, 0xbfb8aa3b, v32
	v_exp_f32_e32 v32, v32
	v_max_f32_e32 v171, 0xc1f00000, v171
	v_max_f32_e32 v170, 0xc1f00000, v170
	v_mul_f32_e32 v171, 0xbfb8aa3b, v171
	v_mul_f32_e32 v170, 0xbfb8aa3b, v170
	v_add_f32_e32 v35, 1.0, v35
	v_exp_f32_e32 v176, v171
	v_exp_f32_e32 v177, v170
	v_rcp_f32_e32 v170, v35
	v_add_f32_e32 v35, 1.0, v172
	v_rcp_f32_e32 v171, v35
	v_add_f32_e32 v35, 1.0, v173
	v_add_f32_e32 v32, 1.0, v32
	v_rcp_f32_e32 v172, v35
	v_add_f32_e32 v35, 1.0, v174
	v_rcp_f32_e32 v32, v32
	v_rcp_f32_e32 v173, v35
	v_add_f32_e32 v35, 1.0, v175
	v_rcp_f32_e32 v174, v35
	v_add_f32_e32 v35, 1.0, v176
	v_rcp_f32_e32 v175, v35
	v_add_f32_e32 v35, 1.0, v177
	v_mov_b32_e32 v176, v97
	v_mov_b32_e32 v177, v98
	v_pk_mul_f32 v[170:171], v[176:177], v[170:171]
	v_pk_mov_b32 v[176:177], v[98:99], v[92:93] op_sel:[1,0]
	v_fma_mixlo_f16 v32, v96, v32, 0
	v_cvt_pk_f16_f32 v171, v170, v171
	v_pk_mul_f32 v[172:173], v[176:177], v[172:173]
	v_rcp_f32_e32 v35, v35
	v_pack_b32_f16 v170, v32, v171
	v_cvt_pk_f16_f32 v32, v172, v173
	v_mov_b32_e32 v172, v93
	v_mov_b32_e32 v173, v94
	v_pk_mul_f32 v[172:173], v[172:173], v[174:175]
	v_alignbit_b32 v171, v32, v171, 16
	v_cvt_pk_f16_f32 v173, v172, v173
	v_alignbit_b32 v172, v173, v32, 16
	v_lshrrev_b32_e32 v173, 16, v173
	v_fma_mixhi_f16 v173, v95, v35, 0
	v_cvt_f32_f16_e32 v32, v152
	v_cvt_f32_f16_sdwa v35, v152 dst_sel:DWORD dst_unused:UNUSED_PAD src0_sel:WORD_1
	v_cvt_f32_f16_e32 v152, v153
	v_cvt_f32_f16_sdwa v153, v153 dst_sel:DWORD dst_unused:UNUSED_PAD src0_sel:WORD_1
	global_store_dwordx4 v[178:179], v[170:173], off offset:256
	v_max_f32_e32 v35, 0xc1f00000, v35
	v_max_f32_e32 v152, 0xc1f00000, v152
	v_mul_f32_e32 v152, 0xbfb8aa3b, v152
	v_lshlrev_b64 v[170:171], 11, v[160:161]
	v_exp_f32_e32 v161, v152
	v_max_f32_e32 v152, 0xc1f00000, v153
	v_mul_f32_e32 v152, 0xbfb8aa3b, v152
	v_cvt_f32_f16_e32 v153, v154
	v_exp_f32_e32 v172, v152
	v_cvt_f32_f16_sdwa v152, v154 dst_sel:DWORD dst_unused:UNUSED_PAD src0_sel:WORD_1
	v_mul_f32_e32 v35, 0xbfb8aa3b, v35
	v_max_f32_e32 v153, 0xc1f00000, v153
	v_mul_f32_e32 v153, 0xbfb8aa3b, v153
	v_max_f32_e32 v152, 0xc1f00000, v152
	v_mul_f32_e32 v152, 0xbfb8aa3b, v152
	v_exp_f32_e32 v173, v153
	v_cvt_f32_f16_e32 v153, v155
	v_exp_f32_e32 v174, v152
	v_cvt_f32_f16_sdwa v152, v155 dst_sel:DWORD dst_unused:UNUSED_PAD src0_sel:WORD_1
	v_exp_f32_e32 v35, v35
	v_max_f32_e32 v32, 0xc1f00000, v32
	v_mul_f32_e32 v32, 0xbfb8aa3b, v32
	v_exp_f32_e32 v32, v32
	v_max_f32_e32 v153, 0xc1f00000, v153
	v_max_f32_e32 v152, 0xc1f00000, v152
	v_mul_f32_e32 v153, 0xbfb8aa3b, v153
	v_mul_f32_e32 v152, 0xbfb8aa3b, v152
	v_add_f32_e32 v35, 1.0, v35
	v_exp_f32_e32 v175, v153
	v_exp_f32_e32 v176, v152
	v_rcp_f32_e32 v152, v35
	v_add_f32_e32 v35, 1.0, v161
	v_rcp_f32_e32 v153, v35
	v_add_f32_e32 v35, 1.0, v172
	v_add_f32_e32 v32, 1.0, v32
	v_rcp_f32_e32 v154, v35
	v_add_f32_e32 v35, 1.0, v173
	v_rcp_f32_e32 v32, v32
	v_rcp_f32_e32 v155, v35
	v_add_f32_e32 v35, 1.0, v174
	v_rcp_f32_e32 v172, v35
	v_add_f32_e32 v35, 1.0, v175
	v_rcp_f32_e32 v173, v35
	v_mov_b32_e32 v174, v121
	v_mov_b32_e32 v175, v122
	v_pk_mul_f32 v[152:153], v[174:175], v[152:153]
	v_pk_mov_b32 v[174:175], v[122:123], v[116:117] op_sel:[1,0]
	v_add_f32_e32 v35, 1.0, v176
	v_fma_mixlo_f16 v32, v120, v32, 0
	v_cvt_pk_f16_f32 v153, v152, v153
	v_pk_mul_f32 v[154:155], v[174:175], v[154:155]
	v_rcp_f32_e32 v35, v35
	v_pack_b32_f16 v152, v32, v153
	v_cvt_pk_f16_f32 v32, v154, v155
	v_mov_b32_e32 v154, v117
	v_mov_b32_e32 v155, v118
	v_pk_mul_f32 v[154:155], v[154:155], v[172:173]
	v_alignbit_b32 v153, v32, v153, 16
	v_cvt_pk_f16_f32 v155, v154, v155
	v_alignbit_b32 v154, v155, v32, 16
	v_lshrrev_b32_e32 v155, 16, v155
	v_fma_mixhi_f16 v155, v119, v35, 0
	v_cvt_f32_f16_e32 v32, v148
	v_cvt_f32_f16_sdwa v35, v148 dst_sel:DWORD dst_unused:UNUSED_PAD src0_sel:WORD_1
	v_cvt_f32_f16_e32 v148, v149
	v_cvt_f32_f16_sdwa v149, v149 dst_sel:DWORD dst_unused:UNUSED_PAD src0_sel:WORD_1
	v_lshl_add_u64 v[170:171], s[14:15], 0, v[170:171]
	v_lshl_add_u64 v[170:171], v[170:171], 0, v[166:167]
	v_max_f32_e32 v148, 0xc1f00000, v148
	v_mul_f32_e32 v148, 0xbfb8aa3b, v148
	global_store_dwordx4 v[170:171], v[152:155], off
	v_max_f32_e32 v35, 0xc1f00000, v35
	v_mul_f32_e32 v35, 0xbfb8aa3b, v35
	v_exp_f32_e32 v152, v148
	v_max_f32_e32 v148, 0xc1f00000, v149
	v_mul_f32_e32 v148, 0xbfb8aa3b, v148
	v_cvt_f32_f16_e32 v149, v150
	v_exp_f32_e32 v153, v148
	v_cvt_f32_f16_sdwa v148, v150 dst_sel:DWORD dst_unused:UNUSED_PAD src0_sel:WORD_1
	v_exp_f32_e32 v35, v35
	v_max_f32_e32 v149, 0xc1f00000, v149
	v_mul_f32_e32 v149, 0xbfb8aa3b, v149
	v_max_f32_e32 v148, 0xc1f00000, v148
	v_mul_f32_e32 v148, 0xbfb8aa3b, v148
	v_exp_f32_e32 v154, v149
	v_cvt_f32_f16_e32 v149, v151
	v_exp_f32_e32 v155, v148
	v_cvt_f32_f16_sdwa v148, v151 dst_sel:DWORD dst_unused:UNUSED_PAD src0_sel:WORD_1
	v_max_f32_e32 v32, 0xc1f00000, v32
	v_mul_f32_e32 v32, 0xbfb8aa3b, v32
	v_exp_f32_e32 v32, v32
	v_max_f32_e32 v149, 0xc1f00000, v149
	v_max_f32_e32 v148, 0xc1f00000, v148
	v_mul_f32_e32 v149, 0xbfb8aa3b, v149
	v_mul_f32_e32 v148, 0xbfb8aa3b, v148
	v_add_f32_e32 v35, 1.0, v35
	v_exp_f32_e32 v161, v149
	v_exp_f32_e32 v172, v148
	v_rcp_f32_e32 v148, v35
	v_add_f32_e32 v35, 1.0, v152
	v_rcp_f32_e32 v149, v35
	v_add_f32_e32 v35, 1.0, v153
	v_add_f32_e32 v32, 1.0, v32
	v_rcp_f32_e32 v150, v35
	v_add_f32_e32 v35, 1.0, v154
	v_rcp_f32_e32 v32, v32
	v_rcp_f32_e32 v151, v35
	v_add_f32_e32 v35, 1.0, v155
	v_rcp_f32_e32 v152, v35
	v_add_f32_e32 v35, 1.0, v161
	v_rcp_f32_e32 v153, v35
	v_mov_b32_e32 v154, v89
	v_mov_b32_e32 v155, v90
	v_pk_mul_f32 v[148:149], v[154:155], v[148:149]
	v_pk_mov_b32 v[154:155], v[90:91], v[84:85] op_sel:[1,0]
	v_add_f32_e32 v35, 1.0, v172
	v_fma_mixlo_f16 v32, v88, v32, 0
	v_cvt_pk_f16_f32 v149, v148, v149
	v_pk_mul_f32 v[150:151], v[154:155], v[150:151]
	v_rcp_f32_e32 v35, v35
	v_pack_b32_f16 v148, v32, v149
	v_cvt_pk_f16_f32 v32, v150, v151
	v_mov_b32_e32 v150, v85
	v_mov_b32_e32 v151, v86
	v_pk_mul_f32 v[150:151], v[150:151], v[152:153]
	v_alignbit_b32 v149, v32, v149, 16
	v_cvt_pk_f16_f32 v151, v150, v151
	v_alignbit_b32 v150, v151, v32, 16
	v_lshrrev_b32_e32 v151, 16, v151
	v_fma_mixhi_f16 v151, v87, v35, 0
	v_cvt_f32_f16_e32 v32, v144
	v_cvt_f32_f16_sdwa v35, v144 dst_sel:DWORD dst_unused:UNUSED_PAD src0_sel:WORD_1
	v_cvt_f32_f16_e32 v144, v145
	v_cvt_f32_f16_sdwa v145, v145 dst_sel:DWORD dst_unused:UNUSED_PAD src0_sel:WORD_1
	global_store_dwordx4 v[170:171], v[148:151], off offset:256
	v_max_f32_e32 v35, 0xc1f00000, v35
	v_max_f32_e32 v144, 0xc1f00000, v144
	v_mul_f32_e32 v144, 0xbfb8aa3b, v144
	v_exp_f32_e32 v150, v144
	v_max_f32_e32 v144, 0xc1f00000, v145
	v_mul_f32_e32 v144, 0xbfb8aa3b, v144
	v_cvt_f32_f16_e32 v145, v146
	v_exp_f32_e32 v151, v144
	v_cvt_f32_f16_sdwa v144, v146 dst_sel:DWORD dst_unused:UNUSED_PAD src0_sel:WORD_1
	v_mul_f32_e32 v35, 0xbfb8aa3b, v35
	v_max_f32_e32 v145, 0xc1f00000, v145
	v_mul_f32_e32 v145, 0xbfb8aa3b, v145
	v_max_f32_e32 v144, 0xc1f00000, v144
	v_mul_f32_e32 v144, 0xbfb8aa3b, v144
	v_exp_f32_e32 v152, v145
	v_cvt_f32_f16_e32 v145, v147
	v_exp_f32_e32 v153, v144
	v_cvt_f32_f16_sdwa v144, v147 dst_sel:DWORD dst_unused:UNUSED_PAD src0_sel:WORD_1
	v_exp_f32_e32 v35, v35
	v_max_f32_e32 v32, 0xc1f00000, v32
	v_mul_f32_e32 v32, 0xbfb8aa3b, v32
	v_exp_f32_e32 v32, v32
	v_max_f32_e32 v145, 0xc1f00000, v145
	v_max_f32_e32 v144, 0xc1f00000, v144
	v_mul_f32_e32 v145, 0xbfb8aa3b, v145
	v_mul_f32_e32 v144, 0xbfb8aa3b, v144
	v_add_f32_e32 v35, 1.0, v35
	v_exp_f32_e32 v154, v145
	v_exp_f32_e32 v155, v144
	v_rcp_f32_e32 v144, v35
	v_add_f32_e32 v35, 1.0, v150
	v_rcp_f32_e32 v145, v35
	v_add_f32_e32 v35, 1.0, v151
	v_add_f32_e32 v32, 1.0, v32
	v_rcp_f32_e32 v146, v35
	v_add_f32_e32 v35, 1.0, v152
	v_rcp_f32_e32 v32, v32
	v_rcp_f32_e32 v147, v35
	v_add_f32_e32 v35, 1.0, v153
	v_rcp_f32_e32 v150, v35
	v_add_f32_e32 v35, 1.0, v154
	v_rcp_f32_e32 v151, v35
	v_mov_b32_e32 v152, v113
	v_mov_b32_e32 v153, v114
	v_pk_mul_f32 v[144:145], v[152:153], v[144:145]
	v_pk_mov_b32 v[152:153], v[114:115], v[108:109] op_sel:[1,0]
	v_add_f32_e32 v35, 1.0, v155
	v_fma_mixlo_f16 v32, v112, v32, 0
	v_cvt_pk_f16_f32 v145, v144, v145
	v_pk_mul_f32 v[146:147], v[152:153], v[146:147]
	v_rcp_f32_e32 v35, v35
	v_pack_b32_f16 v144, v32, v145
	v_cvt_pk_f16_f32 v32, v146, v147
	v_mov_b32_e32 v146, v109
	v_mov_b32_e32 v147, v110
	v_pk_mul_f32 v[146:147], v[146:147], v[150:151]
	v_alignbit_b32 v145, v32, v145, 16
	v_cvt_pk_f16_f32 v147, v146, v147
	v_alignbit_b32 v146, v147, v32, 16
	v_lshrrev_b32_e32 v147, 16, v147
	v_fma_mixhi_f16 v147, v111, v35, 0
	v_cvt_f32_f16_e32 v32, v140
	v_cvt_f32_f16_sdwa v35, v140 dst_sel:DWORD dst_unused:UNUSED_PAD src0_sel:WORD_1
	v_cvt_f32_f16_e32 v140, v141
	v_cvt_f32_f16_sdwa v141, v141 dst_sel:DWORD dst_unused:UNUSED_PAD src0_sel:WORD_1
	v_lshlrev_b64 v[148:149], 11, v[162:163]
	v_lshl_add_u64 v[148:149], s[14:15], 0, v[148:149]
	v_max_f32_e32 v140, 0xc1f00000, v140
	v_lshl_add_u64 v[148:149], v[148:149], 0, v[166:167]
	v_mul_f32_e32 v140, 0xbfb8aa3b, v140
	global_store_dwordx4 v[148:149], v[144:147], off
	v_max_f32_e32 v35, 0xc1f00000, v35
	v_mul_f32_e32 v35, 0xbfb8aa3b, v35
	v_exp_f32_e32 v144, v140
	v_max_f32_e32 v140, 0xc1f00000, v141
	v_mul_f32_e32 v140, 0xbfb8aa3b, v140
	v_cvt_f32_f16_e32 v141, v142
	v_exp_f32_e32 v145, v140
	v_cvt_f32_f16_sdwa v140, v142 dst_sel:DWORD dst_unused:UNUSED_PAD src0_sel:WORD_1
	v_exp_f32_e32 v35, v35
	v_max_f32_e32 v141, 0xc1f00000, v141
	v_mul_f32_e32 v141, 0xbfb8aa3b, v141
	v_max_f32_e32 v140, 0xc1f00000, v140
	v_mul_f32_e32 v140, 0xbfb8aa3b, v140
	v_exp_f32_e32 v146, v141
	v_cvt_f32_f16_e32 v141, v143
	v_exp_f32_e32 v147, v140
	v_cvt_f32_f16_sdwa v140, v143 dst_sel:DWORD dst_unused:UNUSED_PAD src0_sel:WORD_1
	v_max_f32_e32 v32, 0xc1f00000, v32
	v_mul_f32_e32 v32, 0xbfb8aa3b, v32
	v_exp_f32_e32 v32, v32
	v_max_f32_e32 v141, 0xc1f00000, v141
	v_max_f32_e32 v140, 0xc1f00000, v140
	v_mul_f32_e32 v141, 0xbfb8aa3b, v141
	v_mul_f32_e32 v140, 0xbfb8aa3b, v140
	v_add_f32_e32 v35, 1.0, v35
	v_exp_f32_e32 v150, v141
	v_exp_f32_e32 v151, v140
	v_rcp_f32_e32 v140, v35
	v_add_f32_e32 v35, 1.0, v144
	v_rcp_f32_e32 v141, v35
	v_add_f32_e32 v35, 1.0, v145
	v_add_f32_e32 v32, 1.0, v32
	v_rcp_f32_e32 v142, v35
	v_add_f32_e32 v35, 1.0, v146
	v_rcp_f32_e32 v32, v32
	v_rcp_f32_e32 v143, v35
	v_add_f32_e32 v35, 1.0, v147
	v_rcp_f32_e32 v144, v35
	v_add_f32_e32 v35, 1.0, v150
	v_rcp_f32_e32 v145, v35
	v_mov_b32_e32 v146, v81
	v_mov_b32_e32 v147, v82
	v_pk_mul_f32 v[140:141], v[146:147], v[140:141]
	v_pk_mov_b32 v[146:147], v[82:83], v[76:77] op_sel:[1,0]
	v_add_f32_e32 v35, 1.0, v151
	v_fma_mixlo_f16 v32, v80, v32, 0
	v_cvt_pk_f16_f32 v141, v140, v141
	v_pk_mul_f32 v[142:143], v[146:147], v[142:143]
	v_rcp_f32_e32 v35, v35
	v_pack_b32_f16 v140, v32, v141
	v_cvt_pk_f16_f32 v32, v142, v143
	v_mov_b32_e32 v142, v77
	v_mov_b32_e32 v143, v78
	v_pk_mul_f32 v[142:143], v[142:143], v[144:145]
	v_alignbit_b32 v141, v32, v141, 16
	v_cvt_pk_f16_f32 v143, v142, v143
	v_alignbit_b32 v142, v143, v32, 16
	v_lshrrev_b32_e32 v143, 16, v143
	v_fma_mixhi_f16 v143, v79, v35, 0
	v_cvt_f32_f16_e32 v32, v136
	v_cvt_f32_f16_sdwa v35, v136 dst_sel:DWORD dst_unused:UNUSED_PAD src0_sel:WORD_1
	v_cvt_f32_f16_e32 v136, v137
	v_cvt_f32_f16_sdwa v137, v137 dst_sel:DWORD dst_unused:UNUSED_PAD src0_sel:WORD_1
	global_store_dwordx4 v[148:149], v[140:143], off offset:256
	v_max_f32_e32 v35, 0xc1f00000, v35
	v_max_f32_e32 v136, 0xc1f00000, v136
	v_mul_f32_e32 v136, 0xbfb8aa3b, v136
	v_exp_f32_e32 v142, v136
	v_max_f32_e32 v136, 0xc1f00000, v137
	v_mul_f32_e32 v136, 0xbfb8aa3b, v136
	v_cvt_f32_f16_e32 v137, v138
	v_exp_f32_e32 v143, v136
	v_cvt_f32_f16_sdwa v136, v138 dst_sel:DWORD dst_unused:UNUSED_PAD src0_sel:WORD_1
	v_mul_f32_e32 v35, 0xbfb8aa3b, v35
	v_max_f32_e32 v137, 0xc1f00000, v137
	v_mul_f32_e32 v137, 0xbfb8aa3b, v137
	v_max_f32_e32 v136, 0xc1f00000, v136
	v_mul_f32_e32 v136, 0xbfb8aa3b, v136
	v_exp_f32_e32 v144, v137
	v_cvt_f32_f16_e32 v137, v139
	v_exp_f32_e32 v145, v136
	v_cvt_f32_f16_sdwa v136, v139 dst_sel:DWORD dst_unused:UNUSED_PAD src0_sel:WORD_1
	v_exp_f32_e32 v35, v35
	v_max_f32_e32 v32, 0xc1f00000, v32
	v_mul_f32_e32 v32, 0xbfb8aa3b, v32
	v_exp_f32_e32 v32, v32
	v_max_f32_e32 v137, 0xc1f00000, v137
	v_max_f32_e32 v136, 0xc1f00000, v136
	v_mul_f32_e32 v137, 0xbfb8aa3b, v137
	v_mul_f32_e32 v136, 0xbfb8aa3b, v136
	v_add_f32_e32 v35, 1.0, v35
	v_exp_f32_e32 v146, v137
	v_exp_f32_e32 v147, v136
	v_rcp_f32_e32 v136, v35
	v_add_f32_e32 v35, 1.0, v142
	v_rcp_f32_e32 v137, v35
	v_add_f32_e32 v35, 1.0, v143
	v_add_f32_e32 v32, 1.0, v32
	v_rcp_f32_e32 v138, v35
	v_add_f32_e32 v35, 1.0, v144
	v_rcp_f32_e32 v32, v32
	v_rcp_f32_e32 v139, v35
	v_add_f32_e32 v35, 1.0, v145
	v_rcp_f32_e32 v142, v35
	v_add_f32_e32 v35, 1.0, v146
	v_rcp_f32_e32 v143, v35
	v_mov_b32_e32 v144, v105
	v_mov_b32_e32 v145, v106
	v_pk_mul_f32 v[136:137], v[144:145], v[136:137]
	v_pk_mov_b32 v[144:145], v[106:107], v[100:101] op_sel:[1,0]
	v_add_f32_e32 v35, 1.0, v147
	v_fma_mixlo_f16 v32, v104, v32, 0
	v_cvt_pk_f16_f32 v137, v136, v137
	v_pk_mul_f32 v[138:139], v[144:145], v[138:139]
	v_rcp_f32_e32 v35, v35
	v_pack_b32_f16 v136, v32, v137
	v_cvt_pk_f16_f32 v32, v138, v139
	v_mov_b32_e32 v138, v101
	v_mov_b32_e32 v139, v102
	v_pk_mul_f32 v[138:139], v[138:139], v[142:143]
	v_alignbit_b32 v137, v32, v137, 16
	v_cvt_pk_f16_f32 v139, v138, v139
	v_alignbit_b32 v138, v139, v32, 16
	v_lshrrev_b32_e32 v139, 16, v139
	v_fma_mixhi_f16 v139, v103, v35, 0
	v_cvt_f32_f16_e32 v32, v132
	v_cvt_f32_f16_sdwa v35, v132 dst_sel:DWORD dst_unused:UNUSED_PAD src0_sel:WORD_1
	v_cvt_f32_f16_e32 v132, v133
	v_cvt_f32_f16_sdwa v133, v133 dst_sel:DWORD dst_unused:UNUSED_PAD src0_sel:WORD_1
	v_lshlrev_b64 v[140:141], 11, v[164:165]
	v_lshl_add_u64 v[140:141], s[14:15], 0, v[140:141]
	v_max_f32_e32 v132, 0xc1f00000, v132
	v_lshl_add_u64 v[140:141], v[140:141], 0, v[166:167]
	v_mul_f32_e32 v132, 0xbfb8aa3b, v132
	global_store_dwordx4 v[140:141], v[136:139], off
	v_max_f32_e32 v35, 0xc1f00000, v35
	v_mul_f32_e32 v35, 0xbfb8aa3b, v35
	v_exp_f32_e32 v136, v132
	v_max_f32_e32 v132, 0xc1f00000, v133
	v_mul_f32_e32 v132, 0xbfb8aa3b, v132
	v_cvt_f32_f16_e32 v133, v134
	v_exp_f32_e32 v137, v132
	v_cvt_f32_f16_sdwa v132, v134 dst_sel:DWORD dst_unused:UNUSED_PAD src0_sel:WORD_1
	v_exp_f32_e32 v35, v35
	v_max_f32_e32 v133, 0xc1f00000, v133
	v_mul_f32_e32 v133, 0xbfb8aa3b, v133
	v_max_f32_e32 v132, 0xc1f00000, v132
	v_mul_f32_e32 v132, 0xbfb8aa3b, v132
	v_exp_f32_e32 v138, v133
	v_cvt_f32_f16_e32 v133, v135
	v_exp_f32_e32 v139, v132
	v_cvt_f32_f16_sdwa v132, v135 dst_sel:DWORD dst_unused:UNUSED_PAD src0_sel:WORD_1
	v_max_f32_e32 v32, 0xc1f00000, v32
	v_mul_f32_e32 v32, 0xbfb8aa3b, v32
	v_exp_f32_e32 v32, v32
	v_max_f32_e32 v133, 0xc1f00000, v133
	v_max_f32_e32 v132, 0xc1f00000, v132
	v_mul_f32_e32 v133, 0xbfb8aa3b, v133
	v_mul_f32_e32 v132, 0xbfb8aa3b, v132
	v_add_f32_e32 v35, 1.0, v35
	v_exp_f32_e32 v142, v133
	v_exp_f32_e32 v143, v132
	v_rcp_f32_e32 v132, v35
	v_add_f32_e32 v35, 1.0, v136
	v_rcp_f32_e32 v133, v35
	v_add_f32_e32 v35, 1.0, v137
	v_add_f32_e32 v32, 1.0, v32
	v_rcp_f32_e32 v134, v35
	v_add_f32_e32 v35, 1.0, v138
	v_rcp_f32_e32 v32, v32
	v_rcp_f32_e32 v135, v35
	v_add_f32_e32 v35, 1.0, v139
	v_rcp_f32_e32 v136, v35
	v_add_f32_e32 v35, 1.0, v142
	v_rcp_f32_e32 v137, v35
	v_mov_b32_e32 v138, v73
	v_mov_b32_e32 v139, v74
	v_pk_mul_f32 v[132:133], v[138:139], v[132:133]
	v_pk_mov_b32 v[138:139], v[74:75], v[68:69] op_sel:[1,0]
	v_add_f32_e32 v35, 1.0, v143
	v_fma_mixlo_f16 v32, v72, v32, 0
	v_cvt_pk_f16_f32 v133, v132, v133
	v_pk_mul_f32 v[134:135], v[138:139], v[134:135]
	v_rcp_f32_e32 v35, v35
	v_pack_b32_f16 v132, v32, v133
	v_cvt_pk_f16_f32 v32, v134, v135
	v_mov_b32_e32 v134, v69
	v_mov_b32_e32 v135, v70
	v_pk_mul_f32 v[134:135], v[134:135], v[136:137]
	v_alignbit_b32 v133, v32, v133, 16
	v_cvt_pk_f16_f32 v135, v134, v135
	v_alignbit_b32 v134, v135, v32, 16
	v_lshrrev_b32_e32 v135, 16, v135
	v_fma_mixhi_f16 v135, v71, v35, 0
	global_store_dwordx4 v[140:141], v[132:135], off offset:256
	v_add_u32_e32 v184, 0x80, v34
	s_nop 0
	v_mad_i64_i32 v[132:133], s[12:13], v184, s33, v[168:169]
	v_lshl_add_u64 v[132:133], v[132:133], 0, v[166:167]
	v_add_u32_e32 v174, 0x90, v34
	v_lshl_add_u64 v[134:135], v[132:133], 0, s[16:17]
	v_mad_i64_i32 v[136:137], s[12:13], v174, s33, v[168:169]
	v_add_co_u32_e32 v132, vcc, s1, v132
	v_lshl_add_u64 v[136:137], v[136:137], 0, v[166:167]
	v_add_u32_e32 v172, 0xa0, v34
	v_addc_co_u32_e32 v133, vcc, 0, v133, vcc
	v_lshl_add_u64 v[138:139], v[136:137], 0, s[16:17]
	v_mad_i64_i32 v[140:141], s[12:13], v172, s33, v[168:169]
	v_add_co_u32_e32 v136, vcc, s1, v136
	v_lshl_add_u64 v[140:141], v[140:141], 0, v[166:167]
	v_add_u32_e32 v170, 0xb0, v34
	v_addc_co_u32_e32 v137, vcc, 0, v137, vcc
	v_mad_i64_i32 v[144:145], s[12:13], v170, s33, v[168:169]
	global_load_dwordx4 v[176:179], v[132:133], off offset:2048
	global_load_dwordx4 v[152:155], v[136:137], off offset:2048
	global_load_dwordx4 v[180:183], v[134:135], off offset:256
	global_load_dwordx4 v[148:151], v[138:139], off offset:256
	v_add_co_u32_e32 v132, vcc, s1, v140
	v_lshl_add_u64 v[144:145], v[144:145], 0, v[166:167]
	s_nop 0
	v_addc_co_u32_e32 v133, vcc, 0, v141, vcc
	v_add_co_u32_e32 v134, vcc, s1, v144
	v_lshl_add_u64 v[142:143], v[140:141], 0, s[16:17]
	s_nop 0
	v_addc_co_u32_e32 v135, vcc, 0, v145, vcc
	v_lshl_add_u64 v[168:169], v[144:145], 0, s[16:17]
	global_load_dwordx4 v[144:147], v[132:133], off offset:2048
	global_load_dwordx4 v[136:139], v[134:135], off offset:2048
	s_nop 0
	global_load_dwordx4 v[140:143], v[142:143], off offset:256
	s_nop 0
	global_load_dwordx4 v[132:135], v[168:169], off offset:256
	v_ashrrev_i32_e32 v185, 31, v184
	v_ashrrev_i32_e32 v175, 31, v174
	v_ashrrev_i32_e32 v173, 31, v172
	v_ashrrev_i32_e32 v171, 31, v170
	s_waitcnt vmcnt(0)
	v_cvt_f32_f16_e32 v32, v176
	v_cvt_f32_f16_sdwa v35, v176 dst_sel:DWORD dst_unused:UNUSED_PAD src0_sel:WORD_1
	v_cvt_f32_f16_sdwa v176, v178 dst_sel:DWORD dst_unused:UNUSED_PAD src0_sel:WORD_1
	v_cvt_f32_f16_e32 v161, v177
	v_cvt_f32_f16_sdwa v163, v177 dst_sel:DWORD dst_unused:UNUSED_PAD src0_sel:WORD_1
	v_cvt_f32_f16_e32 v165, v178
	v_max_f32_e32 v176, 0xc1f00000, v176
	v_max_f32_e32 v35, 0xc1f00000, v35
	v_mul_f32_e32 v176, 0xbfb8aa3b, v176
	v_lshlrev_b64 v[168:169], 11, v[184:185]
	v_mul_f32_e32 v35, 0xbfb8aa3b, v35
	v_max_f32_e32 v161, 0xc1f00000, v161
	v_cvt_f32_f16_e32 v177, v179
	v_exp_f32_e32 v184, v176
	v_cvt_f32_f16_sdwa v176, v179 dst_sel:DWORD dst_unused:UNUSED_PAD src0_sel:WORD_1
	v_exp_f32_e32 v35, v35
	v_mul_f32_e32 v161, 0xbfb8aa3b, v161
	v_max_f32_e32 v163, 0xc1f00000, v163
	v_max_f32_e32 v32, 0xc1f00000, v32
	v_exp_f32_e32 v161, v161
	v_mul_f32_e32 v163, 0xbfb8aa3b, v163
	v_max_f32_e32 v165, 0xc1f00000, v165
	v_mul_f32_e32 v32, 0xbfb8aa3b, v32
	v_exp_f32_e32 v163, v163
	v_mul_f32_e32 v165, 0xbfb8aa3b, v165
	v_exp_f32_e32 v32, v32
	v_exp_f32_e32 v165, v165
	v_max_f32_e32 v177, 0xc1f00000, v177
	v_max_f32_e32 v176, 0xc1f00000, v176
	v_mul_f32_e32 v177, 0xbfb8aa3b, v177
	v_mul_f32_e32 v176, 0xbfb8aa3b, v176
	v_add_f32_e32 v35, 1.0, v35
	v_exp_f32_e32 v185, v177
	v_exp_f32_e32 v186, v176
	v_rcp_f32_e32 v176, v35
	v_add_f32_e32 v35, 1.0, v161
	v_rcp_f32_e32 v177, v35
	v_add_f32_e32 v35, 1.0, v163
	v_add_f32_e32 v32, 1.0, v32
	v_rcp_f32_e32 v178, v35
	v_add_f32_e32 v35, 1.0, v165
	v_rcp_f32_e32 v32, v32
	v_rcp_f32_e32 v179, v35
	v_add_f32_e32 v35, 1.0, v184
	v_rcp_f32_e32 v184, v35
	v_add_f32_e32 v35, 1.0, v185
	v_rcp_f32_e32 v185, v35
	v_add_f32_e32 v35, 1.0, v186
	v_mov_b32_e32 v186, v65
	v_mov_b32_e32 v187, v66
	v_pk_mul_f32 v[176:177], v[186:187], v[176:177]
	v_pk_mov_b32 v[186:187], v[66:67], v[60:61] op_sel:[1,0]
	v_fma_mixlo_f16 v32, v64, v32, 0
	v_cvt_pk_f16_f32 v161, v176, v177
	v_pk_mul_f32 v[178:179], v[186:187], v[178:179]
	v_rcp_f32_e32 v35, v35
	v_pack_b32_f16 v176, v32, v161
	v_cvt_pk_f16_f32 v32, v178, v179
	v_mov_b32_e32 v178, v61
	v_mov_b32_e32 v179, v62
	v_pk_mul_f32 v[178:179], v[178:179], v[184:185]
	v_alignbit_b32 v177, v32, v161, 16
	v_cvt_pk_f16_f32 v161, v178, v179
	v_lshrrev_b32_e32 v179, 16, v161
	v_lshl_add_u64 v[168:169], s[14:15], 0, v[168:169]
	v_alignbit_b32 v178, v161, v32, 16
	v_fma_mixhi_f16 v179, v63, v35, 0
	v_lshl_add_u64 v[168:169], v[168:169], 0, v[166:167]
	global_store_dwordx4 v[168:169], v[176:179], off
	v_cvt_f32_f16_sdwa v35, v180 dst_sel:DWORD dst_unused:UNUSED_PAD src0_sel:WORD_1
	v_cvt_f32_f16_e32 v161, v181
	v_cvt_f32_f16_sdwa v176, v182 dst_sel:DWORD dst_unused:UNUSED_PAD src0_sel:WORD_1
	v_cvt_f32_f16_sdwa v163, v181 dst_sel:DWORD dst_unused:UNUSED_PAD src0_sel:WORD_1
	v_cvt_f32_f16_e32 v32, v180
	v_cvt_f32_f16_e32 v165, v182
	v_max_f32_e32 v176, 0xc1f00000, v176
	v_max_f32_e32 v35, 0xc1f00000, v35
	v_mul_f32_e32 v176, 0xbfb8aa3b, v176
	v_mul_f32_e32 v35, 0xbfb8aa3b, v35
	v_max_f32_e32 v161, 0xc1f00000, v161
	v_cvt_f32_f16_e32 v177, v183
	v_exp_f32_e32 v180, v176
	v_cvt_f32_f16_sdwa v176, v183 dst_sel:DWORD dst_unused:UNUSED_PAD src0_sel:WORD_1
	v_exp_f32_e32 v35, v35
	v_mul_f32_e32 v161, 0xbfb8aa3b, v161
	v_max_f32_e32 v163, 0xc1f00000, v163
	v_max_f32_e32 v32, 0xc1f00000, v32
	v_exp_f32_e32 v161, v161
	v_mul_f32_e32 v163, 0xbfb8aa3b, v163
	v_max_f32_e32 v165, 0xc1f00000, v165
	v_mul_f32_e32 v32, 0xbfb8aa3b, v32
	v_exp_f32_e32 v163, v163
	v_mul_f32_e32 v165, 0xbfb8aa3b, v165
	v_exp_f32_e32 v32, v32
	v_exp_f32_e32 v165, v165
	v_max_f32_e32 v177, 0xc1f00000, v177
	v_max_f32_e32 v176, 0xc1f00000, v176
	v_mul_f32_e32 v177, 0xbfb8aa3b, v177
	v_mul_f32_e32 v176, 0xbfb8aa3b, v176
	v_add_f32_e32 v35, 1.0, v35
	v_exp_f32_e32 v181, v177
	v_exp_f32_e32 v182, v176
	v_rcp_f32_e32 v176, v35
	v_add_f32_e32 v35, 1.0, v161
	v_rcp_f32_e32 v177, v35
	v_add_f32_e32 v35, 1.0, v163
	v_add_f32_e32 v32, 1.0, v32
	v_rcp_f32_e32 v178, v35
	v_add_f32_e32 v35, 1.0, v165
	v_rcp_f32_e32 v32, v32
	v_rcp_f32_e32 v179, v35
	v_add_f32_e32 v35, 1.0, v180
	v_rcp_f32_e32 v180, v35
	v_add_f32_e32 v35, 1.0, v181
	v_rcp_f32_e32 v181, v35
	v_add_f32_e32 v35, 1.0, v182
	v_mov_b32_e32 v182, v29
	v_mov_b32_e32 v183, v30
	v_pk_mul_f32 v[176:177], v[182:183], v[176:177]
	v_pk_mov_b32 v[182:183], v[30:31], v[24:25] op_sel:[1,0]
	v_fma_mixlo_f16 v32, v28, v32, 0
	v_cvt_pk_f16_f32 v161, v176, v177
	v_pk_mul_f32 v[178:179], v[182:183], v[178:179]
	v_rcp_f32_e32 v35, v35
	v_pack_b32_f16 v176, v32, v161
	v_cvt_pk_f16_f32 v32, v178, v179
	v_mov_b32_e32 v178, v25
	v_mov_b32_e32 v179, v26
	v_pk_mul_f32 v[178:179], v[178:179], v[180:181]
	v_alignbit_b32 v177, v32, v161, 16
	v_cvt_pk_f16_f32 v161, v178, v179
	v_lshrrev_b32_e32 v179, 16, v161
	v_alignbit_b32 v178, v161, v32, 16
	v_fma_mixhi_f16 v179, v27, v35, 0
	v_cvt_f32_f16_e32 v32, v152
	v_cvt_f32_f16_sdwa v35, v152 dst_sel:DWORD dst_unused:UNUSED_PAD src0_sel:WORD_1
	v_cvt_f32_f16_e32 v152, v153
	v_cvt_f32_f16_sdwa v153, v153 dst_sel:DWORD dst_unused:UNUSED_PAD src0_sel:WORD_1
	global_store_dwordx4 v[168:169], v[176:179], off offset:256
	v_max_f32_e32 v35, 0xc1f00000, v35
	v_max_f32_e32 v152, 0xc1f00000, v152
	v_mul_f32_e32 v152, 0xbfb8aa3b, v152
	v_exp_f32_e32 v161, v152
	v_max_f32_e32 v152, 0xc1f00000, v153
	v_mul_f32_e32 v152, 0xbfb8aa3b, v152
	v_cvt_f32_f16_e32 v153, v154
	v_exp_f32_e32 v163, v152
	v_cvt_f32_f16_sdwa v152, v154 dst_sel:DWORD dst_unused:UNUSED_PAD src0_sel:WORD_1
	v_lshlrev_b64 v[168:169], 11, v[174:175]
	v_max_f32_e32 v153, 0xc1f00000, v153
	v_mul_f32_e32 v153, 0xbfb8aa3b, v153
	v_max_f32_e32 v152, 0xc1f00000, v152
	v_mul_f32_e32 v152, 0xbfb8aa3b, v152
	v_mul_f32_e32 v35, 0xbfb8aa3b, v35
	v_exp_f32_e32 v165, v153
	v_cvt_f32_f16_e32 v153, v155
	v_exp_f32_e32 v174, v152
	v_cvt_f32_f16_sdwa v152, v155 dst_sel:DWORD dst_unused:UNUSED_PAD src0_sel:WORD_1
	v_exp_f32_e32 v35, v35
	v_max_f32_e32 v32, 0xc1f00000, v32
	v_mul_f32_e32 v32, 0xbfb8aa3b, v32
	v_exp_f32_e32 v32, v32
	v_max_f32_e32 v153, 0xc1f00000, v153
	v_max_f32_e32 v152, 0xc1f00000, v152
	v_mul_f32_e32 v153, 0xbfb8aa3b, v153
	v_mul_f32_e32 v152, 0xbfb8aa3b, v152
	v_add_f32_e32 v35, 1.0, v35
	v_exp_f32_e32 v175, v153
	v_exp_f32_e32 v176, v152
	v_rcp_f32_e32 v152, v35
	v_add_f32_e32 v35, 1.0, v161
	v_rcp_f32_e32 v153, v35
	v_add_f32_e32 v35, 1.0, v163
	v_add_f32_e32 v32, 1.0, v32
	v_rcp_f32_e32 v154, v35
	v_add_f32_e32 v35, 1.0, v165
	v_rcp_f32_e32 v32, v32
	v_rcp_f32_e32 v155, v35
	v_add_f32_e32 v35, 1.0, v174
	v_rcp_f32_e32 v174, v35
	v_add_f32_e32 v35, 1.0, v175
	v_rcp_f32_e32 v175, v35
	v_add_f32_e32 v35, 1.0, v176
	v_mov_b32_e32 v176, v57
	v_mov_b32_e32 v177, v58
	v_pk_mul_f32 v[152:153], v[176:177], v[152:153]
	v_pk_mov_b32 v[176:177], v[58:59], v[52:53] op_sel:[1,0]
	v_fma_mixlo_f16 v32, v56, v32, 0
	v_cvt_pk_f16_f32 v153, v152, v153
	v_pk_mul_f32 v[154:155], v[176:177], v[154:155]
	v_rcp_f32_e32 v35, v35
	v_pack_b32_f16 v152, v32, v153
	v_cvt_pk_f16_f32 v32, v154, v155
	v_mov_b32_e32 v154, v53
	v_mov_b32_e32 v155, v54
	v_pk_mul_f32 v[154:155], v[154:155], v[174:175]
	v_alignbit_b32 v153, v32, v153, 16
	v_cvt_pk_f16_f32 v155, v154, v155
	v_alignbit_b32 v154, v155, v32, 16
	v_lshrrev_b32_e32 v155, 16, v155
	v_fma_mixhi_f16 v155, v55, v35, 0
	v_cvt_f32_f16_e32 v32, v148
	v_cvt_f32_f16_sdwa v35, v148 dst_sel:DWORD dst_unused:UNUSED_PAD src0_sel:WORD_1
	v_cvt_f32_f16_e32 v148, v149
	v_cvt_f32_f16_sdwa v149, v149 dst_sel:DWORD dst_unused:UNUSED_PAD src0_sel:WORD_1
	v_lshl_add_u64 v[168:169], s[14:15], 0, v[168:169]
	v_lshl_add_u64 v[168:169], v[168:169], 0, v[166:167]
	v_max_f32_e32 v148, 0xc1f00000, v148
	v_mul_f32_e32 v148, 0xbfb8aa3b, v148
	global_store_dwordx4 v[168:169], v[152:155], off
	v_max_f32_e32 v35, 0xc1f00000, v35
	v_mul_f32_e32 v35, 0xbfb8aa3b, v35
	v_exp_f32_e32 v152, v148
	v_max_f32_e32 v148, 0xc1f00000, v149
	v_mul_f32_e32 v148, 0xbfb8aa3b, v148
	v_cvt_f32_f16_e32 v149, v150
	v_exp_f32_e32 v153, v148
	v_cvt_f32_f16_sdwa v148, v150 dst_sel:DWORD dst_unused:UNUSED_PAD src0_sel:WORD_1
	v_exp_f32_e32 v35, v35
	v_max_f32_e32 v149, 0xc1f00000, v149
	v_mul_f32_e32 v149, 0xbfb8aa3b, v149
	v_max_f32_e32 v148, 0xc1f00000, v148
	v_mul_f32_e32 v148, 0xbfb8aa3b, v148
	v_exp_f32_e32 v154, v149
	v_cvt_f32_f16_e32 v149, v151
	v_exp_f32_e32 v155, v148
	v_cvt_f32_f16_sdwa v148, v151 dst_sel:DWORD dst_unused:UNUSED_PAD src0_sel:WORD_1
	v_max_f32_e32 v32, 0xc1f00000, v32
	v_mul_f32_e32 v32, 0xbfb8aa3b, v32
	v_exp_f32_e32 v32, v32
	v_max_f32_e32 v149, 0xc1f00000, v149
	v_max_f32_e32 v148, 0xc1f00000, v148
	v_mul_f32_e32 v149, 0xbfb8aa3b, v149
	v_mul_f32_e32 v148, 0xbfb8aa3b, v148
	v_add_f32_e32 v35, 1.0, v35
	v_exp_f32_e32 v161, v149
	v_exp_f32_e32 v163, v148
	v_rcp_f32_e32 v148, v35
	v_add_f32_e32 v35, 1.0, v152
	v_rcp_f32_e32 v149, v35
	v_add_f32_e32 v35, 1.0, v153
	v_add_f32_e32 v32, 1.0, v32
	v_rcp_f32_e32 v150, v35
	v_add_f32_e32 v35, 1.0, v154
	v_rcp_f32_e32 v32, v32
	v_rcp_f32_e32 v151, v35
	v_add_f32_e32 v35, 1.0, v155
	v_rcp_f32_e32 v152, v35
	v_add_f32_e32 v35, 1.0, v161
	v_rcp_f32_e32 v153, v35
	v_mov_b32_e32 v154, v21
	v_mov_b32_e32 v155, v22
	v_pk_mul_f32 v[148:149], v[154:155], v[148:149]
	v_pk_mov_b32 v[154:155], v[22:23], v[16:17] op_sel:[1,0]
	v_add_f32_e32 v35, 1.0, v163
	v_fma_mixlo_f16 v32, v20, v32, 0
	v_cvt_pk_f16_f32 v149, v148, v149
	v_pk_mul_f32 v[150:151], v[154:155], v[150:151]
	v_rcp_f32_e32 v35, v35
	v_pack_b32_f16 v148, v32, v149
	v_cvt_pk_f16_f32 v32, v150, v151
	v_mov_b32_e32 v150, v17
	v_mov_b32_e32 v151, v18
	v_pk_mul_f32 v[150:151], v[150:151], v[152:153]
	v_alignbit_b32 v149, v32, v149, 16
	v_cvt_pk_f16_f32 v151, v150, v151
	v_alignbit_b32 v150, v151, v32, 16
	v_lshrrev_b32_e32 v151, 16, v151
	v_fma_mixhi_f16 v151, v19, v35, 0
	v_cvt_f32_f16_e32 v32, v144
	v_cvt_f32_f16_sdwa v35, v144 dst_sel:DWORD dst_unused:UNUSED_PAD src0_sel:WORD_1
	v_cvt_f32_f16_e32 v144, v145
	v_cvt_f32_f16_sdwa v145, v145 dst_sel:DWORD dst_unused:UNUSED_PAD src0_sel:WORD_1
	global_store_dwordx4 v[168:169], v[148:151], off offset:256
	v_max_f32_e32 v35, 0xc1f00000, v35
	v_max_f32_e32 v144, 0xc1f00000, v144
	v_mul_f32_e32 v144, 0xbfb8aa3b, v144
	v_exp_f32_e32 v150, v144
	v_max_f32_e32 v144, 0xc1f00000, v145
	v_mul_f32_e32 v144, 0xbfb8aa3b, v144
	v_cvt_f32_f16_e32 v145, v146
	v_exp_f32_e32 v151, v144
	v_cvt_f32_f16_sdwa v144, v146 dst_sel:DWORD dst_unused:UNUSED_PAD src0_sel:WORD_1
	v_mul_f32_e32 v35, 0xbfb8aa3b, v35
	v_max_f32_e32 v145, 0xc1f00000, v145
	v_mul_f32_e32 v145, 0xbfb8aa3b, v145
	v_max_f32_e32 v144, 0xc1f00000, v144
	v_mul_f32_e32 v144, 0xbfb8aa3b, v144
	v_exp_f32_e32 v152, v145
	v_cvt_f32_f16_e32 v145, v147
	v_exp_f32_e32 v153, v144
	v_cvt_f32_f16_sdwa v144, v147 dst_sel:DWORD dst_unused:UNUSED_PAD src0_sel:WORD_1
	v_exp_f32_e32 v35, v35
	v_max_f32_e32 v32, 0xc1f00000, v32
	v_mul_f32_e32 v32, 0xbfb8aa3b, v32
	v_exp_f32_e32 v32, v32
	v_max_f32_e32 v145, 0xc1f00000, v145
	v_max_f32_e32 v144, 0xc1f00000, v144
	v_mul_f32_e32 v145, 0xbfb8aa3b, v145
	v_mul_f32_e32 v144, 0xbfb8aa3b, v144
	v_add_f32_e32 v35, 1.0, v35
	v_exp_f32_e32 v154, v145
	v_exp_f32_e32 v155, v144
	v_rcp_f32_e32 v144, v35
	v_add_f32_e32 v35, 1.0, v150
	v_rcp_f32_e32 v145, v35
	v_add_f32_e32 v35, 1.0, v151
	v_add_f32_e32 v32, 1.0, v32
	v_rcp_f32_e32 v146, v35
	v_add_f32_e32 v35, 1.0, v152
	v_rcp_f32_e32 v32, v32
	v_rcp_f32_e32 v147, v35
	v_add_f32_e32 v35, 1.0, v153
	v_rcp_f32_e32 v150, v35
	v_add_f32_e32 v35, 1.0, v154
	v_rcp_f32_e32 v151, v35
	v_mov_b32_e32 v152, v49
	v_mov_b32_e32 v153, v50
	v_pk_mul_f32 v[144:145], v[152:153], v[144:145]
	v_pk_mov_b32 v[152:153], v[50:51], v[44:45] op_sel:[1,0]
	v_add_f32_e32 v35, 1.0, v155
	v_fma_mixlo_f16 v32, v48, v32, 0
	v_cvt_pk_f16_f32 v145, v144, v145
	v_pk_mul_f32 v[146:147], v[152:153], v[146:147]
	v_rcp_f32_e32 v35, v35
	v_pack_b32_f16 v144, v32, v145
	v_cvt_pk_f16_f32 v32, v146, v147
	v_mov_b32_e32 v146, v45
	v_mov_b32_e32 v147, v46
	v_pk_mul_f32 v[146:147], v[146:147], v[150:151]
	v_alignbit_b32 v145, v32, v145, 16
	v_cvt_pk_f16_f32 v147, v146, v147
	v_alignbit_b32 v146, v147, v32, 16
	v_lshrrev_b32_e32 v147, 16, v147
	v_fma_mixhi_f16 v147, v47, v35, 0
	v_cvt_f32_f16_e32 v32, v140
	v_cvt_f32_f16_sdwa v35, v140 dst_sel:DWORD dst_unused:UNUSED_PAD src0_sel:WORD_1
	v_cvt_f32_f16_e32 v140, v141
	v_cvt_f32_f16_sdwa v141, v141 dst_sel:DWORD dst_unused:UNUSED_PAD src0_sel:WORD_1
	v_lshlrev_b64 v[148:149], 11, v[172:173]
	v_lshl_add_u64 v[148:149], s[14:15], 0, v[148:149]
	v_max_f32_e32 v140, 0xc1f00000, v140
	v_lshl_add_u64 v[148:149], v[148:149], 0, v[166:167]
	v_mul_f32_e32 v140, 0xbfb8aa3b, v140
	global_store_dwordx4 v[148:149], v[144:147], off
	v_max_f32_e32 v35, 0xc1f00000, v35
	v_mul_f32_e32 v35, 0xbfb8aa3b, v35
	v_exp_f32_e32 v144, v140
	v_max_f32_e32 v140, 0xc1f00000, v141
	v_mul_f32_e32 v140, 0xbfb8aa3b, v140
	v_cvt_f32_f16_e32 v141, v142
	v_exp_f32_e32 v145, v140
	v_cvt_f32_f16_sdwa v140, v142 dst_sel:DWORD dst_unused:UNUSED_PAD src0_sel:WORD_1
	v_exp_f32_e32 v35, v35
	v_max_f32_e32 v141, 0xc1f00000, v141
	v_mul_f32_e32 v141, 0xbfb8aa3b, v141
	v_max_f32_e32 v140, 0xc1f00000, v140
	v_mul_f32_e32 v140, 0xbfb8aa3b, v140
	v_exp_f32_e32 v146, v141
	v_cvt_f32_f16_e32 v141, v143
	v_exp_f32_e32 v147, v140
	v_cvt_f32_f16_sdwa v140, v143 dst_sel:DWORD dst_unused:UNUSED_PAD src0_sel:WORD_1
	v_max_f32_e32 v32, 0xc1f00000, v32
	v_mul_f32_e32 v32, 0xbfb8aa3b, v32
	v_exp_f32_e32 v32, v32
	v_max_f32_e32 v141, 0xc1f00000, v141
	v_max_f32_e32 v140, 0xc1f00000, v140
	v_mul_f32_e32 v141, 0xbfb8aa3b, v141
	v_mul_f32_e32 v140, 0xbfb8aa3b, v140
	v_add_f32_e32 v35, 1.0, v35
	v_exp_f32_e32 v150, v141
	v_exp_f32_e32 v151, v140
	v_rcp_f32_e32 v140, v35
	v_add_f32_e32 v35, 1.0, v144
	v_rcp_f32_e32 v141, v35
	v_add_f32_e32 v35, 1.0, v145
	v_add_f32_e32 v32, 1.0, v32
	v_rcp_f32_e32 v142, v35
	v_add_f32_e32 v35, 1.0, v146
	v_rcp_f32_e32 v32, v32
	v_rcp_f32_e32 v143, v35
	v_add_f32_e32 v35, 1.0, v147
	v_rcp_f32_e32 v144, v35
	v_add_f32_e32 v35, 1.0, v150
	v_rcp_f32_e32 v145, v35
	v_mov_b32_e32 v146, v13
	v_mov_b32_e32 v147, v14
	v_pk_mul_f32 v[140:141], v[146:147], v[140:141]
	v_pk_mov_b32 v[146:147], v[14:15], v[8:9] op_sel:[1,0]
	v_add_f32_e32 v35, 1.0, v151
	v_fma_mixlo_f16 v32, v12, v32, 0
	v_cvt_pk_f16_f32 v141, v140, v141
	v_pk_mul_f32 v[142:143], v[146:147], v[142:143]
	v_rcp_f32_e32 v35, v35
	v_pack_b32_f16 v140, v32, v141
	v_cvt_pk_f16_f32 v32, v142, v143
	v_mov_b32_e32 v142, v9
	v_mov_b32_e32 v143, v10
	v_pk_mul_f32 v[142:143], v[142:143], v[144:145]
	v_alignbit_b32 v141, v32, v141, 16
	v_cvt_pk_f16_f32 v143, v142, v143
	v_alignbit_b32 v142, v143, v32, 16
	v_lshrrev_b32_e32 v143, 16, v143
	v_fma_mixhi_f16 v143, v11, v35, 0
	v_cvt_f32_f16_e32 v32, v136
	v_cvt_f32_f16_sdwa v35, v136 dst_sel:DWORD dst_unused:UNUSED_PAD src0_sel:WORD_1
	v_cvt_f32_f16_e32 v136, v137
	v_cvt_f32_f16_sdwa v137, v137 dst_sel:DWORD dst_unused:UNUSED_PAD src0_sel:WORD_1
	global_store_dwordx4 v[148:149], v[140:143], off offset:256
	v_max_f32_e32 v35, 0xc1f00000, v35
	v_max_f32_e32 v136, 0xc1f00000, v136
	v_mul_f32_e32 v136, 0xbfb8aa3b, v136
	v_exp_f32_e32 v142, v136
	v_max_f32_e32 v136, 0xc1f00000, v137
	v_mul_f32_e32 v136, 0xbfb8aa3b, v136
	v_cvt_f32_f16_e32 v137, v138
	v_exp_f32_e32 v143, v136
	v_cvt_f32_f16_sdwa v136, v138 dst_sel:DWORD dst_unused:UNUSED_PAD src0_sel:WORD_1
	v_mul_f32_e32 v35, 0xbfb8aa3b, v35
	v_max_f32_e32 v137, 0xc1f00000, v137
	v_mul_f32_e32 v137, 0xbfb8aa3b, v137
	v_max_f32_e32 v136, 0xc1f00000, v136
	v_mul_f32_e32 v136, 0xbfb8aa3b, v136
	v_exp_f32_e32 v144, v137
	v_cvt_f32_f16_e32 v137, v139
	v_exp_f32_e32 v145, v136
	v_cvt_f32_f16_sdwa v136, v139 dst_sel:DWORD dst_unused:UNUSED_PAD src0_sel:WORD_1
	v_exp_f32_e32 v35, v35
	v_max_f32_e32 v32, 0xc1f00000, v32
	v_mul_f32_e32 v32, 0xbfb8aa3b, v32
	v_exp_f32_e32 v32, v32
	v_max_f32_e32 v137, 0xc1f00000, v137
	v_max_f32_e32 v136, 0xc1f00000, v136
	v_mul_f32_e32 v137, 0xbfb8aa3b, v137
	v_mul_f32_e32 v136, 0xbfb8aa3b, v136
	v_add_f32_e32 v35, 1.0, v35
	v_exp_f32_e32 v146, v137
	v_exp_f32_e32 v147, v136
	v_rcp_f32_e32 v136, v35
	v_add_f32_e32 v35, 1.0, v142
	v_rcp_f32_e32 v137, v35
	v_add_f32_e32 v35, 1.0, v143
	v_add_f32_e32 v32, 1.0, v32
	v_rcp_f32_e32 v138, v35
	v_add_f32_e32 v35, 1.0, v144
	v_rcp_f32_e32 v32, v32
	v_rcp_f32_e32 v139, v35
	v_add_f32_e32 v35, 1.0, v145
	v_rcp_f32_e32 v142, v35
	v_add_f32_e32 v35, 1.0, v146
	v_rcp_f32_e32 v143, v35
	v_mov_b32_e32 v144, v41
	v_mov_b32_e32 v145, v42
	v_pk_mul_f32 v[136:137], v[144:145], v[136:137]
	v_pk_mov_b32 v[144:145], v[42:43], v[36:37] op_sel:[1,0]
	v_add_f32_e32 v35, 1.0, v147
	v_fma_mixlo_f16 v32, v40, v32, 0
	v_cvt_pk_f16_f32 v137, v136, v137
	v_pk_mul_f32 v[138:139], v[144:145], v[138:139]
	v_rcp_f32_e32 v35, v35
	v_pack_b32_f16 v136, v32, v137
	v_cvt_pk_f16_f32 v32, v138, v139
	v_mov_b32_e32 v138, v37
	v_mov_b32_e32 v139, v38
	v_pk_mul_f32 v[138:139], v[138:139], v[142:143]
	v_alignbit_b32 v137, v32, v137, 16
	v_cvt_pk_f16_f32 v139, v138, v139
	v_alignbit_b32 v138, v139, v32, 16
	v_lshrrev_b32_e32 v139, 16, v139
	v_fma_mixhi_f16 v139, v39, v35, 0
	v_cvt_f32_f16_e32 v32, v132
	v_cvt_f32_f16_sdwa v35, v132 dst_sel:DWORD dst_unused:UNUSED_PAD src0_sel:WORD_1
	v_cvt_f32_f16_e32 v132, v133
	v_cvt_f32_f16_sdwa v133, v133 dst_sel:DWORD dst_unused:UNUSED_PAD src0_sel:WORD_1
	v_lshlrev_b64 v[140:141], 11, v[170:171]
	v_lshl_add_u64 v[140:141], s[14:15], 0, v[140:141]
	v_max_f32_e32 v132, 0xc1f00000, v132
	v_lshl_add_u64 v[140:141], v[140:141], 0, v[166:167]
	v_mul_f32_e32 v132, 0xbfb8aa3b, v132
	global_store_dwordx4 v[140:141], v[136:139], off
	v_max_f32_e32 v35, 0xc1f00000, v35
	v_mul_f32_e32 v35, 0xbfb8aa3b, v35
	v_exp_f32_e32 v136, v132
	v_max_f32_e32 v132, 0xc1f00000, v133
	v_mul_f32_e32 v132, 0xbfb8aa3b, v132
	v_cvt_f32_f16_e32 v133, v134
	v_exp_f32_e32 v137, v132
	v_cvt_f32_f16_sdwa v132, v134 dst_sel:DWORD dst_unused:UNUSED_PAD src0_sel:WORD_1
	v_exp_f32_e32 v35, v35
	v_max_f32_e32 v133, 0xc1f00000, v133
	v_mul_f32_e32 v133, 0xbfb8aa3b, v133
	v_max_f32_e32 v132, 0xc1f00000, v132
	v_mul_f32_e32 v132, 0xbfb8aa3b, v132
	v_exp_f32_e32 v138, v133
	v_cvt_f32_f16_e32 v133, v135
	v_exp_f32_e32 v139, v132
	v_cvt_f32_f16_sdwa v132, v135 dst_sel:DWORD dst_unused:UNUSED_PAD src0_sel:WORD_1
	v_max_f32_e32 v32, 0xc1f00000, v32
	v_mul_f32_e32 v32, 0xbfb8aa3b, v32
	v_exp_f32_e32 v32, v32
	v_max_f32_e32 v133, 0xc1f00000, v133
	v_max_f32_e32 v132, 0xc1f00000, v132
	v_mul_f32_e32 v133, 0xbfb8aa3b, v133
	v_mul_f32_e32 v132, 0xbfb8aa3b, v132
	v_add_f32_e32 v35, 1.0, v35
	v_exp_f32_e32 v142, v133
	v_exp_f32_e32 v143, v132
	v_rcp_f32_e32 v132, v35
	v_add_f32_e32 v35, 1.0, v136
	v_rcp_f32_e32 v133, v35
	v_add_f32_e32 v35, 1.0, v137
	v_add_f32_e32 v32, 1.0, v32
	v_rcp_f32_e32 v134, v35
	v_add_f32_e32 v35, 1.0, v138
	v_rcp_f32_e32 v32, v32
	v_rcp_f32_e32 v135, v35
	v_add_f32_e32 v35, 1.0, v139
	v_rcp_f32_e32 v136, v35
	v_add_f32_e32 v35, 1.0, v142
	v_rcp_f32_e32 v137, v35
	v_mov_b32_e32 v138, v5
	v_mov_b32_e32 v139, v6
	v_pk_mul_f32 v[132:133], v[138:139], v[132:133]
	v_pk_mov_b32 v[138:139], v[6:7], v[0:1] op_sel:[1,0]
	v_add_f32_e32 v35, 1.0, v143
	v_fma_mixlo_f16 v32, v4, v32, 0
	v_cvt_pk_f16_f32 v133, v132, v133
	v_pk_mul_f32 v[134:135], v[138:139], v[134:135]
	v_rcp_f32_e32 v35, v35
	v_pack_b32_f16 v132, v32, v133
	v_cvt_pk_f16_f32 v32, v134, v135
	v_mov_b32_e32 v134, v1
	v_mov_b32_e32 v135, v2
	v_pk_mul_f32 v[134:135], v[134:135], v[136:137]
	v_alignbit_b32 v133, v32, v133, 16
	v_cvt_pk_f16_f32 v135, v134, v135
	v_alignbit_b32 v134, v135, v32, 16
	v_lshrrev_b32_e32 v135, 16, v135
	v_fma_mixhi_f16 v135, v3, v35, 0
	global_store_dwordx4 v[140:141], v[132:135], off offset:256
	s_cbranch_execnz .LBB0_944

.LBB0_958:
	s_add_u32 s12, s10, 0x100
	s_addc_u32 s13, s11, 0
	s_add_i32 s38, 0, 0x10000
	v_add_u32_e32 v142, s38, v196
	ds_read_b128 v[122:125], v142
	ds_read_b128 v[138:141], v142 offset:2048
	ds_read_b128 v[130:133], v142 offset:1024
	ds_read_b128 v[142:145], v142 offset:3072
	s_cmp_eq_u32 s37, 12
	s_cselect_b32 s17, s7, s13
	s_cselect_b32 s16, s6, s12
	s_cselect_b32 s15, s9, s36
	s_cselect_b32 s14, s8, s35
	v_lshl_add_u64 v[230:231], s[10:11], 0, v[188:189]
	s_add_i32 m0, s21, 0xc000
	ds_read_b128 v[146:149], v198
	ds_read_b128 v[192:195], v198 offset:2048
	ds_read_b128 v[204:207], v198 offset:4096
	ds_read_b128 v[212:215], v198 offset:6144
	ds_read_b128 v[150:153], v198 offset:1024
	ds_read_b128 v[200:203], v198 offset:3072
	ds_read_b128 v[208:211], v198 offset:5120
	ds_read_b128 v[216:219], v198 offset:7168
	global_load_lds_dwordx4 v[230:231], off
	v_lshl_add_u64 v[230:231], s[10:11], 0, v[190:191]
	s_add_i32 m0, s21, 0xe000
	s_nop 0
	global_load_lds_dwordx4 v[230:231], off
	s_waitcnt lgkmcnt(8)
	s_barrier
	s_waitcnt lgkmcnt(4)
	s_setprio 1
	v_mfma_f32_16x16x32_f16 v[134:137], v[122:125], v[146:149], v[134:137]
	v_mfma_f32_16x16x32_f16 v[126:129], v[138:141], v[146:149], v[126:129]
	v_mfma_f32_16x16x32_f16 v[110:113], v[122:125], v[192:195], v[110:113]
	v_mfma_f32_16x16x32_f16 v[106:109], v[138:141], v[192:195], v[106:109]
	v_mfma_f32_16x16x32_f16 v[94:97], v[122:125], v[204:207], v[94:97]
	v_mfma_f32_16x16x32_f16 v[90:93], v[138:141], v[204:207], v[90:93]
	v_mfma_f32_16x16x32_f16 v[78:81], v[122:125], v[212:215], v[78:81]
	v_mfma_f32_16x16x32_f16 v[74:77], v[138:141], v[212:215], v[74:77]
	s_waitcnt lgkmcnt(0)
	v_mfma_f32_16x16x32_f16 v[134:137], v[130:133], v[150:153], v[134:137]
	v_mfma_f32_16x16x32_f16 v[126:129], v[142:145], v[150:153], v[126:129]
	v_mfma_f32_16x16x32_f16 v[110:113], v[130:133], v[200:203], v[110:113]
	v_mfma_f32_16x16x32_f16 v[106:109], v[142:145], v[200:203], v[106:109]
	v_mfma_f32_16x16x32_f16 v[94:97], v[130:133], v[208:211], v[94:97]
	v_mfma_f32_16x16x32_f16 v[90:93], v[142:145], v[208:211], v[90:93]
	v_mfma_f32_16x16x32_f16 v[78:81], v[130:133], v[216:219], v[78:81]
	v_mfma_f32_16x16x32_f16 v[74:77], v[142:145], v[216:219], v[74:77]
	s_setprio 0
	s_barrier
	s_add_i32 s39, 0, 0x14000
	s_add_i32 s10, s38, s20
	v_add_u32_e32 v199, s39, v196
	v_lshl_add_u64 v[246:247], s[14:15], 0, v[32:33]
	s_mov_b32 m0, s10
	ds_read_b128 v[230:233], v199
	ds_read_b128 v[238:241], v199 offset:2048
	ds_read_b128 v[234:237], v199 offset:1024
	ds_read_b128 v[242:245], v199 offset:3072
	global_load_lds_dwordx4 v[246:247], off
	v_lshl_add_u64 v[248:249], s[14:15], 0, v[154:155]
	s_add_i32 m0, s10, 0x2000
	s_nop 0
	global_load_lds_dwordx4 v[248:249], off
	s_barrier
	s_waitcnt lgkmcnt(2)
	s_setprio 1
	v_mfma_f32_16x16x32_f16 v[118:121], v[230:233], v[146:149], v[118:121]
	v_mfma_f32_16x16x32_f16 v[114:117], v[238:241], v[146:149], v[114:117]
	v_mfma_f32_16x16x32_f16 v[102:105], v[230:233], v[192:195], v[102:105]
	v_mfma_f32_16x16x32_f16 v[98:101], v[238:241], v[192:195], v[98:101]
	v_mfma_f32_16x16x32_f16 v[86:89], v[230:233], v[204:207], v[86:89]
	v_mfma_f32_16x16x32_f16 v[82:85], v[238:241], v[204:207], v[82:85]
	v_mfma_f32_16x16x32_f16 v[70:73], v[230:233], v[212:215], v[70:73]
	v_mfma_f32_16x16x32_f16 v[66:69], v[238:241], v[212:215], v[66:69]
	s_waitcnt lgkmcnt(0)
	v_mfma_f32_16x16x32_f16 v[118:121], v[234:237], v[150:153], v[118:121]
	v_mfma_f32_16x16x32_f16 v[114:117], v[242:245], v[150:153], v[114:117]
	v_mfma_f32_16x16x32_f16 v[102:105], v[234:237], v[200:203], v[102:105]
	v_mfma_f32_16x16x32_f16 v[98:101], v[242:245], v[200:203], v[98:101]
	v_mfma_f32_16x16x32_f16 v[86:89], v[234:237], v[208:211], v[86:89]
	v_mfma_f32_16x16x32_f16 v[82:85], v[242:245], v[208:211], v[82:85]
	v_mfma_f32_16x16x32_f16 v[70:73], v[234:237], v[216:219], v[70:73]
	v_mfma_f32_16x16x32_f16 v[66:69], v[242:245], v[216:219], v[66:69]
	s_setprio 0
	s_mov_b32 m0, s21
	v_lshl_add_u64 v[228:229], s[16:17], 0, v[32:33]
	s_barrier
	ds_read_b128 v[146:149], v198 offset:16384
	ds_read_b128 v[192:195], v198 offset:18432
	ds_read_b128 v[204:207], v198 offset:20480
	ds_read_b128 v[212:215], v198 offset:22528
	ds_read_b128 v[150:153], v198 offset:17408
	ds_read_b128 v[200:203], v198 offset:19456
	ds_read_b128 v[208:211], v198 offset:21504
	ds_read_b128 v[216:219], v198 offset:23552
	global_load_lds_dwordx4 v[228:229], off
	v_lshl_add_u64 v[222:223], s[16:17], 0, v[154:155]
	s_mov_b32 m0, s22
	s_nop 0
	global_load_lds_dwordx4 v[222:223], off
	s_barrier
	s_waitcnt lgkmcnt(4)
	s_setprio 1
	v_mfma_f32_16x16x32_f16 v[62:65], v[122:125], v[146:149], v[62:65]
	v_mfma_f32_16x16x32_f16 v[58:61], v[138:141], v[146:149], v[58:61]
	v_mfma_f32_16x16x32_f16 v[46:49], v[122:125], v[192:195], v[46:49]
	v_mfma_f32_16x16x32_f16 v[42:45], v[138:141], v[192:195], v[42:45]
	v_mfma_f32_16x16x32_f16 v[28:31], v[122:125], v[204:207], v[28:31]
	v_mfma_f32_16x16x32_f16 v[24:27], v[138:141], v[204:207], v[24:27]
	v_mfma_f32_16x16x32_f16 v[12:15], v[122:125], v[212:215], v[12:15]
	v_mfma_f32_16x16x32_f16 v[8:11], v[138:141], v[212:215], v[8:11]
	s_waitcnt lgkmcnt(0)
	v_mfma_f32_16x16x32_f16 v[62:65], v[130:133], v[150:153], v[62:65]
	v_mfma_f32_16x16x32_f16 v[58:61], v[142:145], v[150:153], v[58:61]
	v_mfma_f32_16x16x32_f16 v[46:49], v[130:133], v[200:203], v[46:49]
	v_mfma_f32_16x16x32_f16 v[42:45], v[142:145], v[200:203], v[42:45]
	v_mfma_f32_16x16x32_f16 v[28:31], v[130:133], v[208:211], v[28:31]
	v_mfma_f32_16x16x32_f16 v[24:27], v[142:145], v[208:211], v[24:27]
	v_mfma_f32_16x16x32_f16 v[12:15], v[130:133], v[216:219], v[12:15]
	v_mfma_f32_16x16x32_f16 v[8:11], v[142:145], v[216:219], v[8:11]
	s_setprio 0
	s_barrier
	s_add_u32 s10, s14, 0x40000
	s_addc_u32 s11, s15, 0
	s_add_i32 s38, s39, s20
	v_lshl_add_u64 v[122:123], s[10:11], 0, v[32:33]
	s_mov_b32 m0, s38
	s_nop 0
	global_load_lds_dwordx4 v[122:123], off
	v_lshl_add_u64 v[122:123], s[10:11], 0, v[154:155]
	s_add_i32 m0, s38, 0x2000
	s_nop 0
	global_load_lds_dwordx4 v[122:123], off
	s_waitcnt vmcnt(6)
	s_barrier
	s_setprio 1
	v_mfma_f32_16x16x32_f16 v[54:57], v[230:233], v[146:149], v[54:57]
	v_mfma_f32_16x16x32_f16 v[50:53], v[238:241], v[146:149], v[50:53]
	v_mfma_f32_16x16x32_f16 v[38:41], v[230:233], v[192:195], v[38:41]
	v_mfma_f32_16x16x32_f16 v[34:37], v[238:241], v[192:195], v[34:37]
	v_mfma_f32_16x16x32_f16 v[20:23], v[230:233], v[204:207], v[20:23]
	v_mfma_f32_16x16x32_f16 v[16:19], v[238:241], v[204:207], v[16:19]
	v_mfma_f32_16x16x32_f16 v[4:7], v[230:233], v[212:215], v[4:7]
	v_mfma_f32_16x16x32_f16 v[0:3], v[238:241], v[212:215], v[0:3]
	v_mfma_f32_16x16x32_f16 v[54:57], v[234:237], v[150:153], v[54:57]
	v_mfma_f32_16x16x32_f16 v[50:53], v[242:245], v[150:153], v[50:53]
	v_mfma_f32_16x16x32_f16 v[38:41], v[234:237], v[200:203], v[38:41]
	v_mfma_f32_16x16x32_f16 v[34:37], v[242:245], v[200:203], v[34:37]
	v_mfma_f32_16x16x32_f16 v[20:23], v[234:237], v[208:211], v[20:23]
	v_mfma_f32_16x16x32_f16 v[16:19], v[242:245], v[208:211], v[16:19]
	v_mfma_f32_16x16x32_f16 v[4:7], v[234:237], v[216:219], v[4:7]
	v_mfma_f32_16x16x32_f16 v[0:3], v[242:245], v[216:219], v[0:3]
	s_setprio 0
	s_add_i32 s38, 0, 0x18000
	v_add_u32_e32 v142, s38, v196
	s_barrier
	ds_read_b128 v[122:125], v142
	ds_read_b128 v[138:141], v142 offset:2048
	ds_read_b128 v[130:133], v142 offset:1024
	ds_read_b128 v[142:145], v142 offset:3072
	s_add_u32 s10, s16, 0x40000
	s_addc_u32 s11, s17, 0
	s_mov_b32 m0, s23
	v_lshl_add_u64 v[230:231], s[10:11], 0, v[32:33]
	ds_read_b128 v[146:149], v198 offset:32768
	ds_read_b128 v[192:195], v198 offset:34816
	ds_read_b128 v[204:207], v198 offset:36864
	ds_read_b128 v[212:215], v198 offset:38912
	ds_read_b128 v[150:153], v198 offset:33792
	ds_read_b128 v[200:203], v198 offset:35840
	ds_read_b128 v[208:211], v198 offset:37888
	ds_read_b128 v[216:219], v198 offset:39936
	global_load_lds_dwordx4 v[230:231], off
	v_lshl_add_u64 v[230:231], s[10:11], 0, v[154:155]
	s_mov_b32 m0, s24
	s_nop 0
	global_load_lds_dwordx4 v[230:231], off
	s_waitcnt lgkmcnt(8)
	s_barrier
	s_waitcnt lgkmcnt(4)
	s_setprio 1
	v_mfma_f32_16x16x32_f16 v[134:137], v[122:125], v[146:149], v[134:137]
	v_mfma_f32_16x16x32_f16 v[126:129], v[138:141], v[146:149], v[126:129]
	v_mfma_f32_16x16x32_f16 v[110:113], v[122:125], v[192:195], v[110:113]
	v_mfma_f32_16x16x32_f16 v[106:109], v[138:141], v[192:195], v[106:109]
	v_mfma_f32_16x16x32_f16 v[94:97], v[122:125], v[204:207], v[94:97]
	v_mfma_f32_16x16x32_f16 v[90:93], v[138:141], v[204:207], v[90:93]
	v_mfma_f32_16x16x32_f16 v[78:81], v[122:125], v[212:215], v[78:81]
	v_mfma_f32_16x16x32_f16 v[74:77], v[138:141], v[212:215], v[74:77]
	s_waitcnt lgkmcnt(0)
	v_mfma_f32_16x16x32_f16 v[134:137], v[130:133], v[150:153], v[134:137]
	v_mfma_f32_16x16x32_f16 v[126:129], v[142:145], v[150:153], v[126:129]
	v_mfma_f32_16x16x32_f16 v[110:113], v[130:133], v[200:203], v[110:113]
	v_mfma_f32_16x16x32_f16 v[106:109], v[142:145], v[200:203], v[106:109]
	v_mfma_f32_16x16x32_f16 v[94:97], v[130:133], v[208:211], v[94:97]
	v_mfma_f32_16x16x32_f16 v[90:93], v[142:145], v[208:211], v[90:93]
	v_mfma_f32_16x16x32_f16 v[78:81], v[130:133], v[216:219], v[78:81]
	v_mfma_f32_16x16x32_f16 v[74:77], v[142:145], v[216:219], v[74:77]
	s_setprio 0
	s_barrier
	s_add_i32 s16, 0, 0x1c000
	s_add_i32 s10, s38, s20
	v_add_u32_e32 v199, s16, v196
	v_lshl_add_u64 v[246:247], v[246:247], 0, s[84:85]
	s_mov_b32 m0, s10
	ds_read_b128 v[230:233], v199
	ds_read_b128 v[238:241], v199 offset:2048
	ds_read_b128 v[234:237], v199 offset:1024
	ds_read_b128 v[242:245], v199 offset:3072
	global_load_lds_dwordx4 v[246:247], off
	v_lshl_add_u64 v[246:247], v[248:249], 0, s[84:85]
	s_add_i32 m0, s10, 0x2000
	s_nop 0
	global_load_lds_dwordx4 v[246:247], off
	s_barrier
	s_waitcnt lgkmcnt(2)
	s_setprio 1
	v_mfma_f32_16x16x32_f16 v[118:121], v[230:233], v[146:149], v[118:121]
	v_mfma_f32_16x16x32_f16 v[114:117], v[238:241], v[146:149], v[114:117]
	v_mfma_f32_16x16x32_f16 v[102:105], v[230:233], v[192:195], v[102:105]
	v_mfma_f32_16x16x32_f16 v[98:101], v[238:241], v[192:195], v[98:101]
	v_mfma_f32_16x16x32_f16 v[86:89], v[230:233], v[204:207], v[86:89]
	v_mfma_f32_16x16x32_f16 v[82:85], v[238:241], v[204:207], v[82:85]
	v_mfma_f32_16x16x32_f16 v[70:73], v[230:233], v[212:215], v[70:73]
	v_mfma_f32_16x16x32_f16 v[66:69], v[238:241], v[212:215], v[66:69]
	s_waitcnt lgkmcnt(0)
	v_mfma_f32_16x16x32_f16 v[118:121], v[234:237], v[150:153], v[118:121]
	v_mfma_f32_16x16x32_f16 v[114:117], v[242:245], v[150:153], v[114:117]
	v_mfma_f32_16x16x32_f16 v[102:105], v[234:237], v[200:203], v[102:105]
	v_mfma_f32_16x16x32_f16 v[98:101], v[242:245], v[200:203], v[98:101]
	v_mfma_f32_16x16x32_f16 v[86:89], v[234:237], v[208:211], v[86:89]
	v_mfma_f32_16x16x32_f16 v[82:85], v[242:245], v[208:211], v[82:85]
	v_mfma_f32_16x16x32_f16 v[70:73], v[234:237], v[216:219], v[70:73]
	v_mfma_f32_16x16x32_f16 v[66:69], v[242:245], v[216:219], v[66:69]
	s_setprio 0
	s_mov_b32 m0, s25
	v_lshl_add_u64 v[228:229], v[228:229], 0, s[84:85]
	s_barrier
	ds_read_b128 v[146:149], v198 offset:49152
	ds_read_b128 v[192:195], v198 offset:51200
	ds_read_b128 v[204:207], v198 offset:53248
	ds_read_b128 v[212:215], v198 offset:55296
	ds_read_b128 v[150:153], v198 offset:50176
	ds_read_b128 v[200:203], v198 offset:52224
	ds_read_b128 v[208:211], v198 offset:54272
	ds_read_b128 v[216:219], v198 offset:56320
	global_load_lds_dwordx4 v[228:229], off
	v_lshl_add_u64 v[222:223], v[222:223], 0, s[84:85]
	s_mov_b32 m0, s27
	s_nop 0
	global_load_lds_dwordx4 v[222:223], off
	s_barrier
	s_waitcnt lgkmcnt(4)
	s_setprio 1
	v_mfma_f32_16x16x32_f16 v[62:65], v[122:125], v[146:149], v[62:65]
	v_mfma_f32_16x16x32_f16 v[58:61], v[138:141], v[146:149], v[58:61]
	v_mfma_f32_16x16x32_f16 v[46:49], v[122:125], v[192:195], v[46:49]
	v_mfma_f32_16x16x32_f16 v[42:45], v[138:141], v[192:195], v[42:45]
	v_mfma_f32_16x16x32_f16 v[28:31], v[122:125], v[204:207], v[28:31]
	v_mfma_f32_16x16x32_f16 v[24:27], v[138:141], v[204:207], v[24:27]
	v_mfma_f32_16x16x32_f16 v[12:15], v[122:125], v[212:215], v[12:15]
	v_mfma_f32_16x16x32_f16 v[8:11], v[138:141], v[212:215], v[8:11]
	s_waitcnt lgkmcnt(0)
	v_mfma_f32_16x16x32_f16 v[62:65], v[130:133], v[150:153], v[62:65]
	v_mfma_f32_16x16x32_f16 v[58:61], v[142:145], v[150:153], v[58:61]
	v_mfma_f32_16x16x32_f16 v[46:49], v[130:133], v[200:203], v[46:49]
	v_mfma_f32_16x16x32_f16 v[42:45], v[142:145], v[200:203], v[42:45]
	v_mfma_f32_16x16x32_f16 v[28:31], v[130:133], v[208:211], v[28:31]
	v_mfma_f32_16x16x32_f16 v[24:27], v[142:145], v[208:211], v[24:27]
	v_mfma_f32_16x16x32_f16 v[12:15], v[130:133], v[216:219], v[12:15]
	v_mfma_f32_16x16x32_f16 v[8:11], v[142:145], v[216:219], v[8:11]
	s_setprio 0
	s_barrier
	s_add_u32 s10, s14, 0x40080
	s_addc_u32 s11, s15, 0
	s_add_i32 s14, s16, s20
	v_lshl_add_u64 v[122:123], s[10:11], 0, v[32:33]
	s_mov_b32 m0, s14
	s_nop 0
	global_load_lds_dwordx4 v[122:123], off
	v_lshl_add_u64 v[122:123], s[10:11], 0, v[154:155]
	s_add_i32 m0, s14, 0x2000
	s_nop 0
	global_load_lds_dwordx4 v[122:123], off
	s_waitcnt vmcnt(6)
	s_barrier
	s_setprio 1
	v_mfma_f32_16x16x32_f16 v[54:57], v[230:233], v[146:149], v[54:57]
	v_mfma_f32_16x16x32_f16 v[50:53], v[238:241], v[146:149], v[50:53]
	v_mfma_f32_16x16x32_f16 v[38:41], v[230:233], v[192:195], v[38:41]
	v_mfma_f32_16x16x32_f16 v[34:37], v[238:241], v[192:195], v[34:37]
	v_mfma_f32_16x16x32_f16 v[20:23], v[230:233], v[204:207], v[20:23]
	v_mfma_f32_16x16x32_f16 v[16:19], v[238:241], v[204:207], v[16:19]
	v_mfma_f32_16x16x32_f16 v[4:7], v[230:233], v[212:215], v[4:7]
	v_mfma_f32_16x16x32_f16 v[0:3], v[238:241], v[212:215], v[0:3]
	v_mfma_f32_16x16x32_f16 v[54:57], v[234:237], v[150:153], v[54:57]
	v_mfma_f32_16x16x32_f16 v[50:53], v[242:245], v[150:153], v[50:53]
	v_mfma_f32_16x16x32_f16 v[38:41], v[234:237], v[200:203], v[38:41]
	v_mfma_f32_16x16x32_f16 v[34:37], v[242:245], v[200:203], v[34:37]
	v_mfma_f32_16x16x32_f16 v[20:23], v[234:237], v[208:211], v[20:23]
	v_mfma_f32_16x16x32_f16 v[16:19], v[242:245], v[208:211], v[16:19]
	v_mfma_f32_16x16x32_f16 v[4:7], v[234:237], v[216:219], v[4:7]
	v_mfma_f32_16x16x32_f16 v[0:3], v[242:245], v[216:219], v[0:3]
	s_setprio 0
	s_add_i32 s37, s37, 2
	s_add_u32 s35, s35, 0x100
	s_addc_u32 s36, s36, 0
	s_cmp_gt_u32 s37, 13
	s_mov_b64 s[10:11], s[12:13]
	s_barrier
	s_cbranch_scc0 .LBB0_958
	s_cmp_eq_u32 s34, 2
	s_movk_i32 s6, 0x2800
	v_lshl_or_b32 v122, s31, 8, v197
	s_cselect_b32 s6, 0x2000, s6
	s_mov_b32 s7, 0x23a3c000
	s_cselect_b32 s8, s7, 0x23abc000
	s_add_u32 s6, s70, s6
	v_ashrrev_i32_e32 v123, 31, v122
	s_addc_u32 s7, s71, 0
	v_lshlrev_b64 v[192:193], 1, v[122:123]
	v_lshl_add_u64 v[194:195], s[6:7], 0, v[192:193]
	v_lshl_add_u64 v[122:123], v[194:195], 0, v[156:157]
	v_lshl_add_u64 v[124:125], v[194:195], 0, v[158:159]
	v_lshl_add_u64 v[130:131], v[194:195], 0, v[160:161]
	v_lshl_add_u64 v[208:209], v[194:195], 0, v[162:163]
	global_load_dwordx4 v[200:203], v[122:123], off
	global_load_dwordx4 v[204:207], v[122:123], off offset:256
	global_load_dwordx4 v[150:153], v[124:125], off
	global_load_dwordx4 v[146:149], v[124:125], off offset:256
	global_load_dwordx4 v[142:145], v[130:131], off
	global_load_dwordx4 v[138:141], v[130:131], off offset:256
	s_nop 0
	global_load_dwordx4 v[130:133], v[208:209], off
	global_load_dwordx4 v[122:125], v[208:209], off offset:256
	v_readlane_b32 s36, v252, 26
	v_readlane_b32 s42, v252, 32
	v_readlane_b32 s43, v252, 33
	s_add_u32 s6, s42, s8
	s_addc_u32 s7, s43, 0
	v_readlane_b32 s37, v252, 27
	v_readlane_b32 s38, v252, 28
	v_readlane_b32 s39, v252, 29
	v_readlane_b32 s40, v252, 30
	v_readlane_b32 s41, v252, 31
	v_lshl_add_u64 v[192:193], s[6:7], 0, v[192:193]
	s_waitcnt vmcnt(0)
	v_cvt_f32_f16_e32 v199, v200
	v_cvt_f32_f16_sdwa v200, v200 dst_sel:DWORD dst_unused:UNUSED_PAD src0_sel:WORD_1
	v_cvt_f32_f16_e32 v210, v201
	v_lshl_add_u64 v[208:209], v[192:193], 0, v[164:165]
	v_max_f32_e32 v199, 0xc1f00000, v199
	v_mul_f32_e32 v199, 0xbfb8aa3b, v199
	v_exp_f32_e32 v199, v199
	v_max_f32_e32 v200, 0xc1f00000, v200
	v_max_f32_e32 v210, 0xc1f00000, v210
	v_mul_f32_e32 v200, 0xbfb8aa3b, v200
	v_add_f32_e32 v199, 1.0, v199
	v_rcp_f32_e32 v199, v199
	v_exp_f32_e32 v200, v200
	v_mul_f32_e32 v210, 0xbfb8aa3b, v210
	v_exp_f32_e32 v211, v210
	v_fma_mixlo_f16 v199, v134, v199, 0
	v_add_f32_e32 v134, 1.0, v200
	v_rcp_f32_e32 v210, v134
	v_add_f32_e32 v134, 1.0, v211
	v_cvt_f32_f16_sdwa v200, v201 dst_sel:DWORD dst_unused:UNUSED_PAD src0_sel:WORD_1
	v_rcp_f32_e32 v211, v134
	v_mov_b32_e32 v134, v135
	v_mov_b32_e32 v135, v136
	v_cvt_f32_f16_e32 v136, v202
	v_max_f32_e32 v200, 0xc1f00000, v200
	v_mul_f32_e32 v200, 0xbfb8aa3b, v200
	v_exp_f32_e32 v200, v200
	v_max_f32_e32 v136, 0xc1f00000, v136
	v_mul_f32_e32 v136, 0xbfb8aa3b, v136
	v_exp_f32_e32 v136, v136
	v_pk_mul_f32 v[134:135], v[134:135], v[210:211]
	s_nop 0
	v_cvt_pk_f16_f32 v135, v134, v135
	v_add_f32_e32 v134, 1.0, v200
	v_rcp_f32_e32 v200, v134
	v_add_f32_e32 v134, 1.0, v136
	v_rcp_f32_e32 v201, v134
	v_pk_mov_b32 v[136:137], v[136:137], v[126:127] op_sel:[1,0]
	v_cvt_f32_f16_sdwa v126, v202 dst_sel:DWORD dst_unused:UNUSED_PAD src0_sel:WORD_1
	v_pack_b32_f16 v134, v199, v135
	v_pk_mul_f32 v[136:137], v[136:137], v[200:201]
	v_cvt_f32_f16_sdwa v200, v203 dst_sel:DWORD dst_unused:UNUSED_PAD src0_sel:WORD_1
	v_cvt_pk_f16_f32 v199, v136, v137
	v_cvt_f32_f16_e32 v136, v203
	v_max_f32_e32 v126, 0xc1f00000, v126
	v_mul_f32_e32 v126, 0xbfb8aa3b, v126
	v_exp_f32_e32 v126, v126
	v_max_f32_e32 v136, 0xc1f00000, v136
	v_mul_f32_e32 v136, 0xbfb8aa3b, v136
	v_exp_f32_e32 v137, v136
	v_add_f32_e32 v126, 1.0, v126
	v_rcp_f32_e32 v136, v126
	v_alignbit_b32 v135, v199, v135, 16
	v_add_f32_e32 v126, 1.0, v137
	v_rcp_f32_e32 v137, v126
	v_mov_b32_e32 v126, v127
	v_mov_b32_e32 v127, v128
	v_cvt_f32_f16_e32 v128, v204
	v_pk_mul_f32 v[126:127], v[126:127], v[136:137]
	s_nop 0
	v_cvt_pk_f16_f32 v126, v126, v127
	v_max_f32_e32 v127, 0xc1f00000, v200
	v_mul_f32_e32 v127, 0xbfb8aa3b, v127
	v_exp_f32_e32 v127, v127
	v_alignbit_b32 v136, v126, v199, 16
	v_lshrrev_b32_e32 v137, 16, v126
	v_add_f32_e32 v126, 1.0, v127
	v_rcp_f32_e32 v126, v126
	v_max_f32_e32 v127, 0xc1f00000, v128
	v_mul_f32_e32 v127, 0xbfb8aa3b, v127
	v_exp_f32_e32 v127, v127
	v_fma_mixhi_f16 v137, v129, v126, 0
	v_cvt_f32_f16_sdwa v126, v204 dst_sel:DWORD dst_unused:UNUSED_PAD src0_sel:WORD_1
	v_cvt_f32_f16_e32 v128, v205
	v_add_f32_e32 v127, 1.0, v127
	v_rcp_f32_e32 v127, v127
	v_max_f32_e32 v126, 0xc1f00000, v126
	v_mul_f32_e32 v126, 0xbfb8aa3b, v126
	v_max_f32_e32 v128, 0xc1f00000, v128
	v_exp_f32_e32 v126, v126
	v_mul_f32_e32 v128, 0xbfb8aa3b, v128
	v_exp_f32_e32 v128, v128
	v_fma_mixlo_f16 v129, v118, v127, 0
	v_add_f32_e32 v118, 1.0, v126
	v_rcp_f32_e32 v126, v118
	v_add_f32_e32 v118, 1.0, v128
	v_rcp_f32_e32 v127, v118
	v_cvt_f32_f16_sdwa v128, v205 dst_sel:DWORD dst_unused:UNUSED_PAD src0_sel:WORD_1
	v_mov_b32_e32 v118, v119
	v_mov_b32_e32 v119, v120
	v_cvt_f32_f16_e32 v120, v206
	v_max_f32_e32 v128, 0xc1f00000, v128
	v_mul_f32_e32 v128, 0xbfb8aa3b, v128
	v_exp_f32_e32 v128, v128
	v_max_f32_e32 v120, 0xc1f00000, v120
	v_mul_f32_e32 v120, 0xbfb8aa3b, v120
	v_exp_f32_e32 v120, v120
	v_pk_mul_f32 v[118:119], v[118:119], v[126:127]
	v_add_f32_e32 v126, 1.0, v128
	v_rcp_f32_e32 v126, v126
	v_add_f32_e32 v120, 1.0, v120
	v_rcp_f32_e32 v127, v120
	v_pk_mov_b32 v[120:121], v[120:121], v[114:115] op_sel:[1,0]
	v_cvt_f32_f16_sdwa v114, v206 dst_sel:DWORD dst_unused:UNUSED_PAD src0_sel:WORD_1
	v_cvt_pk_f16_f32 v119, v118, v119
	v_pk_mul_f32 v[120:121], v[120:121], v[126:127]
	v_cvt_f32_f16_sdwa v127, v207 dst_sel:DWORD dst_unused:UNUSED_PAD src0_sel:WORD_1
	v_cvt_pk_f16_f32 v126, v120, v121
	v_cvt_f32_f16_e32 v120, v207
	v_max_f32_e32 v114, 0xc1f00000, v114
	v_mul_f32_e32 v114, 0xbfb8aa3b, v114
	v_exp_f32_e32 v114, v114
	v_max_f32_e32 v120, 0xc1f00000, v120
	v_mul_f32_e32 v120, 0xbfb8aa3b, v120
	v_exp_f32_e32 v121, v120
	v_add_f32_e32 v114, 1.0, v114
	v_rcp_f32_e32 v120, v114
	v_pack_b32_f16 v118, v129, v119
	v_add_f32_e32 v114, 1.0, v121
	v_rcp_f32_e32 v121, v114
	v_mov_b32_e32 v114, v115
	v_max_f32_e32 v115, 0xc1f00000, v127
	v_mul_f32_e32 v115, 0xbfb8aa3b, v115
	v_exp_f32_e32 v127, v115
	v_mov_b32_e32 v115, v116
	v_pk_mul_f32 v[114:115], v[114:115], v[120:121]
	v_cvt_f32_f16_e32 v116, v150
	v_cvt_pk_f16_f32 v114, v114, v115
	v_add_f32_e32 v115, 1.0, v127
	v_rcp_f32_e32 v115, v115
	v_alignbit_b32 v120, v114, v126, 16
	v_lshrrev_b32_e32 v121, 16, v114
	v_max_f32_e32 v114, 0xc1f00000, v116
	v_alignbit_b32 v119, v126, v119, 16
	v_fma_mixhi_f16 v121, v117, v115, 0
	v_mul_f32_e32 v114, 0xbfb8aa3b, v114
	v_cvt_f32_f16_sdwa v117, v150 dst_sel:DWORD dst_unused:UNUSED_PAD src0_sel:WORD_1
	v_exp_f32_e32 v116, v114
	global_store_dwordx4 v[208:209], v[118:121], off offset:256
	v_lshl_add_u64 v[114:115], v[192:193], 0, v[166:167]
	v_max_f32_e32 v117, 0xc1f00000, v117
	v_cvt_f32_f16_e32 v118, v151
	v_add_f32_e32 v116, 1.0, v116
	v_mul_f32_e32 v117, 0xbfb8aa3b, v117
	v_rcp_f32_e32 v116, v116
	v_max_f32_e32 v118, 0xc1f00000, v118
	v_exp_f32_e32 v117, v117
	v_mul_f32_e32 v118, 0xbfb8aa3b, v118
	v_exp_f32_e32 v118, v118
	v_fma_mixlo_f16 v119, v110, v116, 0
	v_add_f32_e32 v110, 1.0, v117
	v_rcp_f32_e32 v116, v110
	v_add_f32_e32 v110, 1.0, v118
	v_rcp_f32_e32 v117, v110
	v_cvt_f32_f16_sdwa v118, v151 dst_sel:DWORD dst_unused:UNUSED_PAD src0_sel:WORD_1
	v_mov_b32_e32 v110, v111
	v_mov_b32_e32 v111, v112
	v_cvt_f32_f16_e32 v112, v152
	v_pk_mul_f32 v[110:111], v[110:111], v[116:117]
	v_max_f32_e32 v116, 0xc1f00000, v118
	v_mul_f32_e32 v116, 0xbfb8aa3b, v116
	v_max_f32_e32 v112, 0xc1f00000, v112
	v_exp_f32_e32 v116, v116
	v_mul_f32_e32 v112, 0xbfb8aa3b, v112
	v_exp_f32_e32 v112, v112
	v_cvt_pk_f16_f32 v111, v110, v111
	v_add_f32_e32 v110, 1.0, v116
	v_rcp_f32_e32 v116, v110
	v_add_f32_e32 v110, 1.0, v112
	v_rcp_f32_e32 v117, v110
	v_pk_mov_b32 v[112:113], v[112:113], v[106:107] op_sel:[1,0]
	v_cvt_f32_f16_sdwa v106, v152 dst_sel:DWORD dst_unused:UNUSED_PAD src0_sel:WORD_1
	v_pack_b32_f16 v110, v119, v111
	v_pk_mul_f32 v[112:113], v[112:113], v[116:117]
	v_cvt_f32_f16_sdwa v117, v153 dst_sel:DWORD dst_unused:UNUSED_PAD src0_sel:WORD_1
	v_cvt_pk_f16_f32 v116, v112, v113
	v_cvt_f32_f16_e32 v112, v153
	v_max_f32_e32 v106, 0xc1f00000, v106
	v_mul_f32_e32 v106, 0xbfb8aa3b, v106
	v_exp_f32_e32 v106, v106
	v_max_f32_e32 v112, 0xc1f00000, v112
	v_mul_f32_e32 v112, 0xbfb8aa3b, v112
	v_exp_f32_e32 v113, v112
	v_add_f32_e32 v106, 1.0, v106
	v_rcp_f32_e32 v112, v106
	v_alignbit_b32 v111, v116, v111, 16
	v_add_f32_e32 v106, 1.0, v113
	v_rcp_f32_e32 v113, v106
	v_mov_b32_e32 v106, v107
	v_mov_b32_e32 v107, v108
	v_cvt_f32_f16_e32 v108, v146
	v_pk_mul_f32 v[106:107], v[106:107], v[112:113]
	global_store_dwordx4 v[208:209], v[134:137], off
	v_cvt_pk_f16_f32 v106, v106, v107
	v_max_f32_e32 v107, 0xc1f00000, v117
	v_mul_f32_e32 v107, 0xbfb8aa3b, v107
	v_exp_f32_e32 v107, v107
	v_alignbit_b32 v112, v106, v116, 16
	v_lshrrev_b32_e32 v113, 16, v106
	v_add_f32_e32 v106, 1.0, v107
	v_rcp_f32_e32 v106, v106
	v_max_f32_e32 v107, 0xc1f00000, v108
	v_mul_f32_e32 v107, 0xbfb8aa3b, v107
	v_exp_f32_e32 v107, v107
	v_fma_mixhi_f16 v113, v109, v106, 0
	v_cvt_f32_f16_sdwa v106, v146 dst_sel:DWORD dst_unused:UNUSED_PAD src0_sel:WORD_1
	v_cvt_f32_f16_e32 v108, v147
	v_add_f32_e32 v107, 1.0, v107
	v_rcp_f32_e32 v107, v107
	v_max_f32_e32 v106, 0xc1f00000, v106
	v_mul_f32_e32 v106, 0xbfb8aa3b, v106
	v_max_f32_e32 v108, 0xc1f00000, v108
	v_exp_f32_e32 v106, v106
	v_mul_f32_e32 v108, 0xbfb8aa3b, v108
	v_exp_f32_e32 v108, v108
	v_fma_mixlo_f16 v109, v102, v107, 0
	v_add_f32_e32 v102, 1.0, v106
	v_rcp_f32_e32 v106, v102
	v_add_f32_e32 v102, 1.0, v108
	v_rcp_f32_e32 v107, v102
	v_cvt_f32_f16_sdwa v108, v147 dst_sel:DWORD dst_unused:UNUSED_PAD src0_sel:WORD_1
	v_mov_b32_e32 v102, v103
	v_mov_b32_e32 v103, v104
	v_cvt_f32_f16_e32 v104, v148
	v_max_f32_e32 v108, 0xc1f00000, v108
	v_mul_f32_e32 v108, 0xbfb8aa3b, v108
	v_exp_f32_e32 v108, v108
	v_max_f32_e32 v104, 0xc1f00000, v104
	v_mul_f32_e32 v104, 0xbfb8aa3b, v104
	v_exp_f32_e32 v104, v104
	v_pk_mul_f32 v[102:103], v[102:103], v[106:107]
	v_add_f32_e32 v106, 1.0, v108
	v_rcp_f32_e32 v106, v106
	v_add_f32_e32 v104, 1.0, v104
	v_rcp_f32_e32 v107, v104
	v_pk_mov_b32 v[104:105], v[104:105], v[98:99] op_sel:[1,0]
	v_cvt_f32_f16_sdwa v98, v148 dst_sel:DWORD dst_unused:UNUSED_PAD src0_sel:WORD_1
	v_cvt_pk_f16_f32 v103, v102, v103
	v_pk_mul_f32 v[104:105], v[104:105], v[106:107]
	v_cvt_f32_f16_sdwa v107, v149 dst_sel:DWORD dst_unused:UNUSED_PAD src0_sel:WORD_1
	v_cvt_pk_f16_f32 v106, v104, v105
	v_cvt_f32_f16_e32 v104, v149
	v_max_f32_e32 v98, 0xc1f00000, v98
	v_mul_f32_e32 v98, 0xbfb8aa3b, v98
	v_exp_f32_e32 v98, v98
	v_max_f32_e32 v104, 0xc1f00000, v104
	v_mul_f32_e32 v104, 0xbfb8aa3b, v104
	v_exp_f32_e32 v105, v104
	v_add_f32_e32 v98, 1.0, v98
	v_rcp_f32_e32 v104, v98
	v_pack_b32_f16 v102, v109, v103
	v_add_f32_e32 v98, 1.0, v105
	v_rcp_f32_e32 v105, v98
	v_mov_b32_e32 v98, v99
	v_max_f32_e32 v99, 0xc1f00000, v107
	v_mul_f32_e32 v99, 0xbfb8aa3b, v99
	v_exp_f32_e32 v107, v99
	v_mov_b32_e32 v99, v100
	v_pk_mul_f32 v[98:99], v[98:99], v[104:105]
	v_cvt_f32_f16_e32 v100, v142
	v_cvt_pk_f16_f32 v98, v98, v99
	v_add_f32_e32 v99, 1.0, v107
	v_rcp_f32_e32 v99, v99
	v_alignbit_b32 v104, v98, v106, 16
	v_lshrrev_b32_e32 v105, 16, v98
	v_max_f32_e32 v98, 0xc1f00000, v100
	v_alignbit_b32 v103, v106, v103, 16
	v_fma_mixhi_f16 v105, v101, v99, 0
	v_mul_f32_e32 v98, 0xbfb8aa3b, v98
	v_cvt_f32_f16_sdwa v101, v142 dst_sel:DWORD dst_unused:UNUSED_PAD src0_sel:WORD_1
	v_exp_f32_e32 v100, v98
	global_store_dwordx4 v[114:115], v[102:105], off offset:256
	v_lshl_add_u64 v[98:99], v[192:193], 0, v[168:169]
	v_max_f32_e32 v101, 0xc1f00000, v101
	v_cvt_f32_f16_e32 v102, v143
	v_add_f32_e32 v100, 1.0, v100
	v_mul_f32_e32 v101, 0xbfb8aa3b, v101
	v_rcp_f32_e32 v100, v100
	v_max_f32_e32 v102, 0xc1f00000, v102
	v_exp_f32_e32 v101, v101
	v_mul_f32_e32 v102, 0xbfb8aa3b, v102
	v_exp_f32_e32 v102, v102
	v_fma_mixlo_f16 v103, v94, v100, 0
	v_add_f32_e32 v94, 1.0, v101
	v_rcp_f32_e32 v100, v94
	v_add_f32_e32 v94, 1.0, v102
	v_rcp_f32_e32 v101, v94
	v_cvt_f32_f16_sdwa v102, v143 dst_sel:DWORD dst_unused:UNUSED_PAD src0_sel:WORD_1
	v_mov_b32_e32 v94, v95
	v_mov_b32_e32 v95, v96
	v_cvt_f32_f16_e32 v96, v144
	v_pk_mul_f32 v[94:95], v[94:95], v[100:101]
	v_max_f32_e32 v100, 0xc1f00000, v102
	v_mul_f32_e32 v100, 0xbfb8aa3b, v100
	v_max_f32_e32 v96, 0xc1f00000, v96
	v_exp_f32_e32 v100, v100
	v_mul_f32_e32 v96, 0xbfb8aa3b, v96
	v_exp_f32_e32 v96, v96
	v_cvt_pk_f16_f32 v95, v94, v95
	v_add_f32_e32 v94, 1.0, v100
	v_rcp_f32_e32 v100, v94
	v_add_f32_e32 v94, 1.0, v96
	v_rcp_f32_e32 v101, v94
	v_pk_mov_b32 v[96:97], v[96:97], v[90:91] op_sel:[1,0]
	v_cvt_f32_f16_sdwa v90, v144 dst_sel:DWORD dst_unused:UNUSED_PAD src0_sel:WORD_1
	v_pack_b32_f16 v94, v103, v95
	v_pk_mul_f32 v[96:97], v[96:97], v[100:101]
	v_cvt_f32_f16_sdwa v101, v145 dst_sel:DWORD dst_unused:UNUSED_PAD src0_sel:WORD_1
	v_cvt_pk_f16_f32 v100, v96, v97
	v_cvt_f32_f16_e32 v96, v145
	v_max_f32_e32 v90, 0xc1f00000, v90
	v_mul_f32_e32 v90, 0xbfb8aa3b, v90
	v_exp_f32_e32 v90, v90
	v_max_f32_e32 v96, 0xc1f00000, v96
	v_mul_f32_e32 v96, 0xbfb8aa3b, v96
	v_exp_f32_e32 v97, v96
	v_add_f32_e32 v90, 1.0, v90
	v_rcp_f32_e32 v96, v90
	v_alignbit_b32 v95, v100, v95, 16
	v_add_f32_e32 v90, 1.0, v97
	v_rcp_f32_e32 v97, v90
	v_mov_b32_e32 v90, v91
	v_mov_b32_e32 v91, v92
	v_cvt_f32_f16_e32 v92, v138
	v_pk_mul_f32 v[90:91], v[90:91], v[96:97]
	global_store_dwordx4 v[114:115], v[110:113], off
	v_cvt_pk_f16_f32 v90, v90, v91
	v_max_f32_e32 v91, 0xc1f00000, v101
	v_mul_f32_e32 v91, 0xbfb8aa3b, v91
	v_exp_f32_e32 v91, v91
	v_alignbit_b32 v96, v90, v100, 16
	v_lshrrev_b32_e32 v97, 16, v90
	v_add_f32_e32 v90, 1.0, v91
	v_rcp_f32_e32 v90, v90
	v_max_f32_e32 v91, 0xc1f00000, v92
	v_mul_f32_e32 v91, 0xbfb8aa3b, v91
	v_exp_f32_e32 v91, v91
	v_fma_mixhi_f16 v97, v93, v90, 0
	v_cvt_f32_f16_sdwa v90, v138 dst_sel:DWORD dst_unused:UNUSED_PAD src0_sel:WORD_1
	v_cvt_f32_f16_e32 v92, v139
	v_add_f32_e32 v91, 1.0, v91
	v_rcp_f32_e32 v91, v91
	v_max_f32_e32 v90, 0xc1f00000, v90
	v_mul_f32_e32 v90, 0xbfb8aa3b, v90
	v_max_f32_e32 v92, 0xc1f00000, v92
	v_exp_f32_e32 v90, v90
	v_mul_f32_e32 v92, 0xbfb8aa3b, v92
	v_exp_f32_e32 v92, v92
	v_fma_mixlo_f16 v93, v86, v91, 0
	v_add_f32_e32 v86, 1.0, v90
	v_rcp_f32_e32 v90, v86
	v_add_f32_e32 v86, 1.0, v92
	v_rcp_f32_e32 v91, v86
	v_cvt_f32_f16_sdwa v92, v139 dst_sel:DWORD dst_unused:UNUSED_PAD src0_sel:WORD_1
	v_mov_b32_e32 v86, v87
	v_mov_b32_e32 v87, v88
	v_cvt_f32_f16_e32 v88, v140
	v_max_f32_e32 v92, 0xc1f00000, v92
	v_mul_f32_e32 v92, 0xbfb8aa3b, v92
	v_exp_f32_e32 v92, v92
	v_max_f32_e32 v88, 0xc1f00000, v88
	v_mul_f32_e32 v88, 0xbfb8aa3b, v88
	v_exp_f32_e32 v88, v88
	v_pk_mul_f32 v[86:87], v[86:87], v[90:91]
	v_add_f32_e32 v90, 1.0, v92
	v_rcp_f32_e32 v90, v90
	v_add_f32_e32 v88, 1.0, v88
	v_rcp_f32_e32 v91, v88
	v_pk_mov_b32 v[88:89], v[88:89], v[82:83] op_sel:[1,0]
	v_cvt_f32_f16_sdwa v82, v140 dst_sel:DWORD dst_unused:UNUSED_PAD src0_sel:WORD_1
	v_cvt_pk_f16_f32 v87, v86, v87
	v_pk_mul_f32 v[88:89], v[88:89], v[90:91]
	v_cvt_f32_f16_sdwa v91, v141 dst_sel:DWORD dst_unused:UNUSED_PAD src0_sel:WORD_1
	v_cvt_pk_f16_f32 v90, v88, v89
	v_cvt_f32_f16_e32 v88, v141
	v_max_f32_e32 v82, 0xc1f00000, v82
	v_mul_f32_e32 v82, 0xbfb8aa3b, v82
	v_exp_f32_e32 v82, v82
	v_max_f32_e32 v88, 0xc1f00000, v88
	v_mul_f32_e32 v88, 0xbfb8aa3b, v88
	v_exp_f32_e32 v89, v88
	v_add_f32_e32 v82, 1.0, v82
	v_rcp_f32_e32 v88, v82
	v_pack_b32_f16 v86, v93, v87
	v_add_f32_e32 v82, 1.0, v89
	v_rcp_f32_e32 v89, v82
	v_mov_b32_e32 v82, v83
	v_max_f32_e32 v83, 0xc1f00000, v91
	v_mul_f32_e32 v83, 0xbfb8aa3b, v83
	v_exp_f32_e32 v91, v83
	v_mov_b32_e32 v83, v84
	v_pk_mul_f32 v[82:83], v[82:83], v[88:89]
	v_cvt_f32_f16_e32 v84, v130
	v_cvt_pk_f16_f32 v82, v82, v83
	v_add_f32_e32 v83, 1.0, v91
	v_rcp_f32_e32 v83, v83
	v_alignbit_b32 v88, v82, v90, 16
	v_lshrrev_b32_e32 v89, 16, v82
	v_max_f32_e32 v82, 0xc1f00000, v84
	v_alignbit_b32 v87, v90, v87, 16
	v_fma_mixhi_f16 v89, v85, v83, 0
	v_mul_f32_e32 v82, 0xbfb8aa3b, v82
	v_cvt_f32_f16_sdwa v85, v130 dst_sel:DWORD dst_unused:UNUSED_PAD src0_sel:WORD_1
	v_exp_f32_e32 v84, v82
	global_store_dwordx4 v[98:99], v[86:89], off offset:256
	v_lshl_add_u64 v[82:83], v[192:193], 0, v[170:171]
	v_max_f32_e32 v85, 0xc1f00000, v85
	v_cvt_f32_f16_e32 v86, v131
	v_add_f32_e32 v84, 1.0, v84
	v_mul_f32_e32 v85, 0xbfb8aa3b, v85
	v_rcp_f32_e32 v84, v84
	v_max_f32_e32 v86, 0xc1f00000, v86
	v_exp_f32_e32 v85, v85
	v_mul_f32_e32 v86, 0xbfb8aa3b, v86
	v_exp_f32_e32 v86, v86
	v_fma_mixlo_f16 v87, v78, v84, 0
	v_add_f32_e32 v78, 1.0, v85
	v_rcp_f32_e32 v84, v78
	v_add_f32_e32 v78, 1.0, v86
	v_rcp_f32_e32 v85, v78
	v_cvt_f32_f16_sdwa v86, v131 dst_sel:DWORD dst_unused:UNUSED_PAD src0_sel:WORD_1
	v_mov_b32_e32 v78, v79
	v_mov_b32_e32 v79, v80
	v_cvt_f32_f16_e32 v80, v132
	v_pk_mul_f32 v[78:79], v[78:79], v[84:85]
	v_max_f32_e32 v84, 0xc1f00000, v86
	v_mul_f32_e32 v84, 0xbfb8aa3b, v84
	v_max_f32_e32 v80, 0xc1f00000, v80
	v_exp_f32_e32 v84, v84
	v_mul_f32_e32 v80, 0xbfb8aa3b, v80
	v_exp_f32_e32 v80, v80
	v_cvt_pk_f16_f32 v79, v78, v79
	v_add_f32_e32 v78, 1.0, v84
	v_rcp_f32_e32 v84, v78
	v_add_f32_e32 v78, 1.0, v80
	v_rcp_f32_e32 v85, v78
	v_pk_mov_b32 v[80:81], v[80:81], v[74:75] op_sel:[1,0]
	v_cvt_f32_f16_sdwa v74, v132 dst_sel:DWORD dst_unused:UNUSED_PAD src0_sel:WORD_1
	v_pack_b32_f16 v78, v87, v79
	v_pk_mul_f32 v[80:81], v[80:81], v[84:85]
	v_cvt_f32_f16_sdwa v85, v133 dst_sel:DWORD dst_unused:UNUSED_PAD src0_sel:WORD_1
	v_cvt_pk_f16_f32 v84, v80, v81
	v_cvt_f32_f16_e32 v80, v133
	v_max_f32_e32 v74, 0xc1f00000, v74
	v_mul_f32_e32 v74, 0xbfb8aa3b, v74
	v_exp_f32_e32 v74, v74
	v_max_f32_e32 v80, 0xc1f00000, v80
	v_mul_f32_e32 v80, 0xbfb8aa3b, v80
	v_exp_f32_e32 v81, v80
	v_add_f32_e32 v74, 1.0, v74
	v_rcp_f32_e32 v80, v74
	v_alignbit_b32 v79, v84, v79, 16
	v_add_f32_e32 v74, 1.0, v81
	v_rcp_f32_e32 v81, v74
	v_mov_b32_e32 v74, v75
	v_mov_b32_e32 v75, v76
	v_cvt_f32_f16_e32 v76, v122
	v_pk_mul_f32 v[74:75], v[74:75], v[80:81]
	global_store_dwordx4 v[98:99], v[94:97], off
	v_cvt_pk_f16_f32 v74, v74, v75
	v_max_f32_e32 v75, 0xc1f00000, v85
	v_mul_f32_e32 v75, 0xbfb8aa3b, v75
	v_exp_f32_e32 v75, v75
	v_alignbit_b32 v80, v74, v84, 16
	v_lshrrev_b32_e32 v81, 16, v74
	v_add_f32_e32 v74, 1.0, v75
	v_rcp_f32_e32 v74, v74
	v_max_f32_e32 v75, 0xc1f00000, v76
	v_mul_f32_e32 v75, 0xbfb8aa3b, v75
	v_exp_f32_e32 v75, v75
	v_fma_mixhi_f16 v81, v77, v74, 0
	v_cvt_f32_f16_sdwa v74, v122 dst_sel:DWORD dst_unused:UNUSED_PAD src0_sel:WORD_1
	v_cvt_f32_f16_e32 v76, v123
	v_add_f32_e32 v75, 1.0, v75
	v_rcp_f32_e32 v75, v75
	v_max_f32_e32 v74, 0xc1f00000, v74
	v_mul_f32_e32 v74, 0xbfb8aa3b, v74
	v_max_f32_e32 v76, 0xc1f00000, v76
	v_exp_f32_e32 v74, v74
	v_mul_f32_e32 v76, 0xbfb8aa3b, v76
	v_exp_f32_e32 v76, v76
	v_fma_mixlo_f16 v77, v70, v75, 0
	v_add_f32_e32 v70, 1.0, v74
	v_rcp_f32_e32 v74, v70
	v_add_f32_e32 v70, 1.0, v76
	v_rcp_f32_e32 v75, v70
	v_cvt_f32_f16_sdwa v76, v123 dst_sel:DWORD dst_unused:UNUSED_PAD src0_sel:WORD_1
	v_mov_b32_e32 v70, v71
	v_mov_b32_e32 v71, v72
	v_cvt_f32_f16_e32 v72, v124
	v_max_f32_e32 v76, 0xc1f00000, v76
	v_mul_f32_e32 v76, 0xbfb8aa3b, v76
	v_exp_f32_e32 v76, v76
	v_max_f32_e32 v72, 0xc1f00000, v72
	v_mul_f32_e32 v72, 0xbfb8aa3b, v72
	v_exp_f32_e32 v72, v72
	v_pk_mul_f32 v[70:71], v[70:71], v[74:75]
	v_add_f32_e32 v74, 1.0, v76
	v_rcp_f32_e32 v74, v74
	v_add_f32_e32 v72, 1.0, v72
	v_rcp_f32_e32 v75, v72
	v_pk_mov_b32 v[72:73], v[72:73], v[66:67] op_sel:[1,0]
	v_cvt_f32_f16_sdwa v66, v124 dst_sel:DWORD dst_unused:UNUSED_PAD src0_sel:WORD_1
	v_cvt_pk_f16_f32 v71, v70, v71
	v_pk_mul_f32 v[72:73], v[72:73], v[74:75]
	v_cvt_f32_f16_sdwa v75, v125 dst_sel:DWORD dst_unused:UNUSED_PAD src0_sel:WORD_1
	v_cvt_pk_f16_f32 v74, v72, v73
	v_cvt_f32_f16_e32 v72, v125
	v_max_f32_e32 v66, 0xc1f00000, v66
	v_mul_f32_e32 v66, 0xbfb8aa3b, v66
	v_exp_f32_e32 v66, v66
	v_max_f32_e32 v72, 0xc1f00000, v72
	v_mul_f32_e32 v72, 0xbfb8aa3b, v72
	v_exp_f32_e32 v73, v72
	v_add_f32_e32 v66, 1.0, v66
	v_rcp_f32_e32 v72, v66
	v_pack_b32_f16 v70, v77, v71
	v_add_f32_e32 v66, 1.0, v73
	v_rcp_f32_e32 v73, v66
	v_max_f32_e32 v66, 0xc1f00000, v75
	v_mul_f32_e32 v66, 0xbfb8aa3b, v66
	v_exp_f32_e32 v75, v66
	v_mov_b32_e32 v66, v67
	v_mov_b32_e32 v67, v68
	v_pk_mul_f32 v[66:67], v[66:67], v[72:73]
	v_add_f32_e32 v68, 1.0, v75
	v_rcp_f32_e32 v68, v68
	v_cvt_pk_f16_f32 v66, v66, v67
	v_lshrrev_b32_e32 v73, 16, v66
	v_alignbit_b32 v71, v74, v71, 16
	v_alignbit_b32 v72, v66, v74, 16
	v_fma_mixhi_f16 v73, v69, v68, 0
	global_store_dwordx4 v[82:83], v[78:81], off
	global_store_dwordx4 v[82:83], v[70:73], off offset:256
	v_lshl_add_u64 v[66:67], v[194:195], 0, v[172:173]
	v_lshl_add_u64 v[68:69], v[194:195], 0, v[174:175]
	v_lshl_add_u64 v[70:71], v[194:195], 0, v[176:177]
	v_lshl_add_u64 v[98:99], v[194:195], 0, v[178:179]
	global_load_dwordx4 v[90:93], v[66:67], off
	global_load_dwordx4 v[94:97], v[66:67], off offset:256
	global_load_dwordx4 v[86:89], v[68:69], off
	global_load_dwordx4 v[82:85], v[68:69], off offset:256
	global_load_dwordx4 v[78:81], v[70:71], off
	global_load_dwordx4 v[74:77], v[70:71], off offset:256
	s_nop 0
	global_load_dwordx4 v[70:73], v[98:99], off
	global_load_dwordx4 v[66:69], v[98:99], off offset:256
	s_waitcnt vmcnt(0)
	v_cvt_f32_f16_e32 v100, v90
	v_cvt_f32_f16_sdwa v90, v90 dst_sel:DWORD dst_unused:UNUSED_PAD src0_sel:WORD_1
	v_cvt_f32_f16_e32 v101, v91
	v_lshl_add_u64 v[98:99], v[192:193], 0, v[180:181]
	v_max_f32_e32 v100, 0xc1f00000, v100
	v_mul_f32_e32 v100, 0xbfb8aa3b, v100
	v_exp_f32_e32 v100, v100
	v_max_f32_e32 v90, 0xc1f00000, v90
	v_max_f32_e32 v101, 0xc1f00000, v101
	v_mul_f32_e32 v90, 0xbfb8aa3b, v90
	v_add_f32_e32 v100, 1.0, v100
	v_rcp_f32_e32 v100, v100
	v_exp_f32_e32 v90, v90
	v_mul_f32_e32 v101, 0xbfb8aa3b, v101
	v_exp_f32_e32 v101, v101
	v_fma_mixlo_f16 v102, v62, v100, 0
	v_add_f32_e32 v62, 1.0, v90
	v_rcp_f32_e32 v100, v62
	v_add_f32_e32 v62, 1.0, v101
	v_cvt_f32_f16_sdwa v90, v91 dst_sel:DWORD dst_unused:UNUSED_PAD src0_sel:WORD_1
	v_rcp_f32_e32 v101, v62
	v_mov_b32_e32 v62, v63
	v_mov_b32_e32 v63, v64
	v_cvt_f32_f16_e32 v64, v92
	v_max_f32_e32 v90, 0xc1f00000, v90
	v_mul_f32_e32 v90, 0xbfb8aa3b, v90
	v_exp_f32_e32 v90, v90
	v_max_f32_e32 v64, 0xc1f00000, v64
	v_mul_f32_e32 v64, 0xbfb8aa3b, v64
	v_exp_f32_e32 v64, v64
	v_pk_mul_f32 v[62:63], v[62:63], v[100:101]
	s_nop 0
	v_cvt_pk_f16_f32 v63, v62, v63
	v_add_f32_e32 v62, 1.0, v90
	v_rcp_f32_e32 v90, v62
	v_add_f32_e32 v62, 1.0, v64
	v_rcp_f32_e32 v91, v62
	v_pk_mov_b32 v[64:65], v[64:65], v[58:59] op_sel:[1,0]
	v_cvt_f32_f16_sdwa v58, v92 dst_sel:DWORD dst_unused:UNUSED_PAD src0_sel:WORD_1
	v_pack_b32_f16 v62, v102, v63
	v_pk_mul_f32 v[64:65], v[64:65], v[90:91]
	v_cvt_f32_f16_sdwa v91, v93 dst_sel:DWORD dst_unused:UNUSED_PAD src0_sel:WORD_1
	v_cvt_pk_f16_f32 v90, v64, v65
	v_cvt_f32_f16_e32 v64, v93
	v_max_f32_e32 v58, 0xc1f00000, v58
	v_mul_f32_e32 v58, 0xbfb8aa3b, v58
	v_exp_f32_e32 v58, v58
	v_max_f32_e32 v64, 0xc1f00000, v64
	v_mul_f32_e32 v64, 0xbfb8aa3b, v64
	v_exp_f32_e32 v65, v64
	v_add_f32_e32 v58, 1.0, v58
	v_rcp_f32_e32 v64, v58
	v_alignbit_b32 v63, v90, v63, 16
	v_add_f32_e32 v58, 1.0, v65
	v_rcp_f32_e32 v65, v58
	v_mov_b32_e32 v58, v59
	v_mov_b32_e32 v59, v60
	v_cvt_f32_f16_e32 v60, v94
	v_pk_mul_f32 v[58:59], v[58:59], v[64:65]
	s_nop 0
	v_cvt_pk_f16_f32 v58, v58, v59
	v_max_f32_e32 v59, 0xc1f00000, v91
	v_mul_f32_e32 v59, 0xbfb8aa3b, v59
	v_exp_f32_e32 v59, v59
	v_alignbit_b32 v64, v58, v90, 16
	v_lshrrev_b32_e32 v65, 16, v58
	v_add_f32_e32 v58, 1.0, v59
	v_rcp_f32_e32 v58, v58
	v_max_f32_e32 v59, 0xc1f00000, v60
	v_mul_f32_e32 v59, 0xbfb8aa3b, v59
	v_exp_f32_e32 v59, v59
	v_fma_mixhi_f16 v65, v61, v58, 0
	v_cvt_f32_f16_sdwa v58, v94 dst_sel:DWORD dst_unused:UNUSED_PAD src0_sel:WORD_1
	v_cvt_f32_f16_e32 v60, v95
	v_add_f32_e32 v59, 1.0, v59
	v_rcp_f32_e32 v59, v59
	v_max_f32_e32 v58, 0xc1f00000, v58
	v_mul_f32_e32 v58, 0xbfb8aa3b, v58
	v_max_f32_e32 v60, 0xc1f00000, v60
	v_exp_f32_e32 v58, v58
	v_mul_f32_e32 v60, 0xbfb8aa3b, v60
	v_exp_f32_e32 v60, v60
	v_fma_mixlo_f16 v61, v54, v59, 0
	v_add_f32_e32 v54, 1.0, v58
	v_rcp_f32_e32 v58, v54
	v_add_f32_e32 v54, 1.0, v60
	v_rcp_f32_e32 v59, v54
	v_cvt_f32_f16_sdwa v60, v95 dst_sel:DWORD dst_unused:UNUSED_PAD src0_sel:WORD_1
	v_mov_b32_e32 v54, v55
	v_mov_b32_e32 v55, v56
	v_cvt_f32_f16_e32 v56, v96
	v_max_f32_e32 v60, 0xc1f00000, v60
	v_mul_f32_e32 v60, 0xbfb8aa3b, v60
	v_exp_f32_e32 v60, v60
	v_max_f32_e32 v56, 0xc1f00000, v56
	v_mul_f32_e32 v56, 0xbfb8aa3b, v56
	v_exp_f32_e32 v56, v56
	v_pk_mul_f32 v[54:55], v[54:55], v[58:59]
	v_add_f32_e32 v58, 1.0, v60
	v_rcp_f32_e32 v58, v58
	v_add_f32_e32 v56, 1.0, v56
	v_rcp_f32_e32 v59, v56
	v_pk_mov_b32 v[56:57], v[56:57], v[50:51] op_sel:[1,0]
	v_cvt_f32_f16_sdwa v50, v96 dst_sel:DWORD dst_unused:UNUSED_PAD src0_sel:WORD_1
	v_cvt_pk_f16_f32 v55, v54, v55
	v_pk_mul_f32 v[56:57], v[56:57], v[58:59]
	v_cvt_f32_f16_sdwa v59, v97 dst_sel:DWORD dst_unused:UNUSED_PAD src0_sel:WORD_1
	v_cvt_pk_f16_f32 v58, v56, v57
	v_cvt_f32_f16_e32 v56, v97
	v_max_f32_e32 v50, 0xc1f00000, v50
	v_mul_f32_e32 v50, 0xbfb8aa3b, v50
	v_exp_f32_e32 v50, v50
	v_max_f32_e32 v56, 0xc1f00000, v56
	v_mul_f32_e32 v56, 0xbfb8aa3b, v56
	v_exp_f32_e32 v57, v56
	v_add_f32_e32 v50, 1.0, v50
	v_rcp_f32_e32 v56, v50
	v_pack_b32_f16 v54, v61, v55
	v_add_f32_e32 v50, 1.0, v57
	v_rcp_f32_e32 v57, v50
	v_mov_b32_e32 v50, v51
	v_max_f32_e32 v51, 0xc1f00000, v59
	v_mul_f32_e32 v51, 0xbfb8aa3b, v51
	v_exp_f32_e32 v59, v51
	v_mov_b32_e32 v51, v52
	v_pk_mul_f32 v[50:51], v[50:51], v[56:57]
	v_cvt_f32_f16_e32 v52, v86
	v_cvt_pk_f16_f32 v50, v50, v51
	v_add_f32_e32 v51, 1.0, v59
	v_rcp_f32_e32 v51, v51
	v_alignbit_b32 v56, v50, v58, 16
	v_lshrrev_b32_e32 v57, 16, v50
	v_max_f32_e32 v50, 0xc1f00000, v52
	v_alignbit_b32 v55, v58, v55, 16
	v_fma_mixhi_f16 v57, v53, v51, 0
	v_mul_f32_e32 v50, 0xbfb8aa3b, v50
	v_cvt_f32_f16_sdwa v53, v86 dst_sel:DWORD dst_unused:UNUSED_PAD src0_sel:WORD_1
	v_exp_f32_e32 v52, v50
	global_store_dwordx4 v[98:99], v[54:57], off offset:256
	v_lshl_add_u64 v[50:51], v[192:193], 0, v[182:183]
	v_max_f32_e32 v53, 0xc1f00000, v53
	v_cvt_f32_f16_e32 v54, v87
	v_add_f32_e32 v52, 1.0, v52
	v_mul_f32_e32 v53, 0xbfb8aa3b, v53
	v_rcp_f32_e32 v52, v52
	v_max_f32_e32 v54, 0xc1f00000, v54
	v_exp_f32_e32 v53, v53
	v_mul_f32_e32 v54, 0xbfb8aa3b, v54
	v_exp_f32_e32 v54, v54
	v_fma_mixlo_f16 v55, v46, v52, 0
	v_add_f32_e32 v46, 1.0, v53
	v_rcp_f32_e32 v52, v46
	v_add_f32_e32 v46, 1.0, v54
	v_rcp_f32_e32 v53, v46
	v_cvt_f32_f16_sdwa v54, v87 dst_sel:DWORD dst_unused:UNUSED_PAD src0_sel:WORD_1
	v_mov_b32_e32 v46, v47
	v_mov_b32_e32 v47, v48
	v_cvt_f32_f16_e32 v48, v88
	v_pk_mul_f32 v[46:47], v[46:47], v[52:53]
	v_max_f32_e32 v52, 0xc1f00000, v54
	v_mul_f32_e32 v52, 0xbfb8aa3b, v52
	v_max_f32_e32 v48, 0xc1f00000, v48
	v_exp_f32_e32 v52, v52
	v_mul_f32_e32 v48, 0xbfb8aa3b, v48
	v_exp_f32_e32 v48, v48
	v_cvt_pk_f16_f32 v47, v46, v47
	v_add_f32_e32 v46, 1.0, v52
	v_rcp_f32_e32 v52, v46
	v_add_f32_e32 v46, 1.0, v48
	v_rcp_f32_e32 v53, v46
	v_pk_mov_b32 v[48:49], v[48:49], v[42:43] op_sel:[1,0]
	v_cvt_f32_f16_sdwa v42, v88 dst_sel:DWORD dst_unused:UNUSED_PAD src0_sel:WORD_1
	v_pack_b32_f16 v46, v55, v47
	v_pk_mul_f32 v[48:49], v[48:49], v[52:53]
	v_cvt_f32_f16_sdwa v53, v89 dst_sel:DWORD dst_unused:UNUSED_PAD src0_sel:WORD_1
	v_cvt_pk_f16_f32 v52, v48, v49
	v_cvt_f32_f16_e32 v48, v89
	v_max_f32_e32 v42, 0xc1f00000, v42
	v_mul_f32_e32 v42, 0xbfb8aa3b, v42
	v_exp_f32_e32 v42, v42
	v_max_f32_e32 v48, 0xc1f00000, v48
	v_mul_f32_e32 v48, 0xbfb8aa3b, v48
	v_exp_f32_e32 v49, v48
	v_add_f32_e32 v42, 1.0, v42
	v_rcp_f32_e32 v48, v42
	v_alignbit_b32 v47, v52, v47, 16
	v_add_f32_e32 v42, 1.0, v49
	v_rcp_f32_e32 v49, v42
	v_mov_b32_e32 v42, v43
	v_mov_b32_e32 v43, v44
	v_cvt_f32_f16_e32 v44, v82
	v_pk_mul_f32 v[42:43], v[42:43], v[48:49]
	global_store_dwordx4 v[98:99], v[62:65], off
	v_cvt_pk_f16_f32 v42, v42, v43
	v_max_f32_e32 v43, 0xc1f00000, v53
	v_mul_f32_e32 v43, 0xbfb8aa3b, v43
	v_exp_f32_e32 v43, v43
	v_alignbit_b32 v48, v42, v52, 16
	v_lshrrev_b32_e32 v49, 16, v42
	v_add_f32_e32 v42, 1.0, v43
	v_rcp_f32_e32 v42, v42
	v_max_f32_e32 v43, 0xc1f00000, v44
	v_mul_f32_e32 v43, 0xbfb8aa3b, v43
	v_exp_f32_e32 v43, v43
	v_fma_mixhi_f16 v49, v45, v42, 0
	v_cvt_f32_f16_sdwa v42, v82 dst_sel:DWORD dst_unused:UNUSED_PAD src0_sel:WORD_1
	v_cvt_f32_f16_e32 v44, v83
	v_add_f32_e32 v43, 1.0, v43
	v_rcp_f32_e32 v43, v43
	v_max_f32_e32 v42, 0xc1f00000, v42
	v_mul_f32_e32 v42, 0xbfb8aa3b, v42
	v_max_f32_e32 v44, 0xc1f00000, v44
	v_exp_f32_e32 v42, v42
	v_mul_f32_e32 v44, 0xbfb8aa3b, v44
	v_exp_f32_e32 v44, v44
	v_fma_mixlo_f16 v45, v38, v43, 0
	v_add_f32_e32 v38, 1.0, v42
	v_rcp_f32_e32 v42, v38
	v_add_f32_e32 v38, 1.0, v44
	v_rcp_f32_e32 v43, v38
	v_cvt_f32_f16_sdwa v44, v83 dst_sel:DWORD dst_unused:UNUSED_PAD src0_sel:WORD_1
	v_mov_b32_e32 v38, v39
	v_mov_b32_e32 v39, v40
	v_cvt_f32_f16_e32 v40, v84
	v_max_f32_e32 v44, 0xc1f00000, v44
	v_mul_f32_e32 v44, 0xbfb8aa3b, v44
	v_exp_f32_e32 v44, v44
	v_max_f32_e32 v40, 0xc1f00000, v40
	v_mul_f32_e32 v40, 0xbfb8aa3b, v40
	v_exp_f32_e32 v40, v40
	v_pk_mul_f32 v[38:39], v[38:39], v[42:43]
	v_add_f32_e32 v42, 1.0, v44
	v_rcp_f32_e32 v42, v42
	v_add_f32_e32 v40, 1.0, v40
	v_rcp_f32_e32 v43, v40
	v_pk_mov_b32 v[40:41], v[40:41], v[34:35] op_sel:[1,0]
	v_cvt_f32_f16_sdwa v34, v84 dst_sel:DWORD dst_unused:UNUSED_PAD src0_sel:WORD_1
	v_cvt_pk_f16_f32 v39, v38, v39
	v_pk_mul_f32 v[40:41], v[40:41], v[42:43]
	v_cvt_f32_f16_sdwa v43, v85 dst_sel:DWORD dst_unused:UNUSED_PAD src0_sel:WORD_1
	v_cvt_pk_f16_f32 v42, v40, v41
	v_cvt_f32_f16_e32 v40, v85
	v_max_f32_e32 v34, 0xc1f00000, v34
	v_mul_f32_e32 v34, 0xbfb8aa3b, v34
	v_exp_f32_e32 v34, v34
	v_max_f32_e32 v40, 0xc1f00000, v40
	v_mul_f32_e32 v40, 0xbfb8aa3b, v40
	v_exp_f32_e32 v41, v40
	v_add_f32_e32 v34, 1.0, v34
	v_rcp_f32_e32 v40, v34
	v_pack_b32_f16 v38, v45, v39
	v_add_f32_e32 v34, 1.0, v41
	v_rcp_f32_e32 v41, v34
	v_mov_b32_e32 v34, v35
	v_max_f32_e32 v35, 0xc1f00000, v43
	v_mul_f32_e32 v35, 0xbfb8aa3b, v35
	v_exp_f32_e32 v43, v35
	v_mov_b32_e32 v35, v36
	v_pk_mul_f32 v[34:35], v[34:35], v[40:41]
	v_cvt_f32_f16_e32 v36, v78
	v_cvt_pk_f16_f32 v34, v34, v35
	v_add_f32_e32 v35, 1.0, v43
	v_rcp_f32_e32 v35, v35
	v_alignbit_b32 v40, v34, v42, 16
	v_lshrrev_b32_e32 v41, 16, v34
	v_max_f32_e32 v34, 0xc1f00000, v36
	v_alignbit_b32 v39, v42, v39, 16
	v_fma_mixhi_f16 v41, v37, v35, 0
	v_mul_f32_e32 v34, 0xbfb8aa3b, v34
	v_cvt_f32_f16_sdwa v37, v78 dst_sel:DWORD dst_unused:UNUSED_PAD src0_sel:WORD_1
	v_exp_f32_e32 v36, v34
	global_store_dwordx4 v[50:51], v[38:41], off offset:256
	v_lshl_add_u64 v[34:35], v[192:193], 0, v[184:185]
	v_max_f32_e32 v37, 0xc1f00000, v37
	v_cvt_f32_f16_e32 v38, v79
	v_add_f32_e32 v36, 1.0, v36
	v_mul_f32_e32 v37, 0xbfb8aa3b, v37
	v_rcp_f32_e32 v36, v36
	v_max_f32_e32 v38, 0xc1f00000, v38
	v_exp_f32_e32 v37, v37
	v_mul_f32_e32 v38, 0xbfb8aa3b, v38
	v_exp_f32_e32 v38, v38
	v_fma_mixlo_f16 v39, v28, v36, 0
	v_add_f32_e32 v28, 1.0, v37
	v_rcp_f32_e32 v36, v28
	v_add_f32_e32 v28, 1.0, v38
	v_rcp_f32_e32 v37, v28
	v_cvt_f32_f16_sdwa v38, v79 dst_sel:DWORD dst_unused:UNUSED_PAD src0_sel:WORD_1
	v_mov_b32_e32 v28, v29
	v_mov_b32_e32 v29, v30
	v_cvt_f32_f16_e32 v30, v80
	v_pk_mul_f32 v[28:29], v[28:29], v[36:37]
	v_max_f32_e32 v36, 0xc1f00000, v38
	v_mul_f32_e32 v36, 0xbfb8aa3b, v36
	v_max_f32_e32 v30, 0xc1f00000, v30
	v_exp_f32_e32 v36, v36
	v_mul_f32_e32 v30, 0xbfb8aa3b, v30
	v_exp_f32_e32 v30, v30
	v_cvt_pk_f16_f32 v29, v28, v29
	v_add_f32_e32 v28, 1.0, v36
	v_rcp_f32_e32 v36, v28
	v_add_f32_e32 v28, 1.0, v30
	v_rcp_f32_e32 v37, v28
	v_pk_mov_b32 v[30:31], v[30:31], v[24:25] op_sel:[1,0]
	v_cvt_f32_f16_sdwa v24, v80 dst_sel:DWORD dst_unused:UNUSED_PAD src0_sel:WORD_1
	v_pack_b32_f16 v28, v39, v29
	v_pk_mul_f32 v[30:31], v[30:31], v[36:37]
	v_cvt_f32_f16_sdwa v37, v81 dst_sel:DWORD dst_unused:UNUSED_PAD src0_sel:WORD_1
	v_cvt_pk_f16_f32 v36, v30, v31
	v_cvt_f32_f16_e32 v30, v81
	v_max_f32_e32 v24, 0xc1f00000, v24
	v_mul_f32_e32 v24, 0xbfb8aa3b, v24
	v_exp_f32_e32 v24, v24
	v_max_f32_e32 v30, 0xc1f00000, v30
	v_mul_f32_e32 v30, 0xbfb8aa3b, v30
	v_exp_f32_e32 v31, v30
	v_add_f32_e32 v24, 1.0, v24
	v_rcp_f32_e32 v30, v24
	v_alignbit_b32 v29, v36, v29, 16
	v_add_f32_e32 v24, 1.0, v31
	v_rcp_f32_e32 v31, v24
	v_mov_b32_e32 v24, v25
	v_mov_b32_e32 v25, v26
	v_cvt_f32_f16_e32 v26, v74
	v_pk_mul_f32 v[24:25], v[24:25], v[30:31]
	global_store_dwordx4 v[50:51], v[46:49], off
	v_cvt_pk_f16_f32 v24, v24, v25
	v_max_f32_e32 v25, 0xc1f00000, v37
	v_mul_f32_e32 v25, 0xbfb8aa3b, v25
	v_exp_f32_e32 v25, v25
	v_alignbit_b32 v30, v24, v36, 16
	v_lshrrev_b32_e32 v31, 16, v24
	v_add_f32_e32 v24, 1.0, v25
	v_rcp_f32_e32 v24, v24
	v_max_f32_e32 v25, 0xc1f00000, v26
	v_mul_f32_e32 v25, 0xbfb8aa3b, v25
	v_exp_f32_e32 v25, v25
	v_fma_mixhi_f16 v31, v27, v24, 0
	v_cvt_f32_f16_sdwa v24, v74 dst_sel:DWORD dst_unused:UNUSED_PAD src0_sel:WORD_1
	v_cvt_f32_f16_e32 v26, v75
	v_add_f32_e32 v25, 1.0, v25
	v_rcp_f32_e32 v25, v25
	v_max_f32_e32 v24, 0xc1f00000, v24
	v_mul_f32_e32 v24, 0xbfb8aa3b, v24
	v_max_f32_e32 v26, 0xc1f00000, v26
	v_exp_f32_e32 v24, v24
	v_mul_f32_e32 v26, 0xbfb8aa3b, v26
	v_exp_f32_e32 v26, v26
	v_fma_mixlo_f16 v27, v20, v25, 0
	v_add_f32_e32 v20, 1.0, v24
	v_rcp_f32_e32 v24, v20
	v_add_f32_e32 v20, 1.0, v26
	v_rcp_f32_e32 v25, v20
	v_cvt_f32_f16_sdwa v26, v75 dst_sel:DWORD dst_unused:UNUSED_PAD src0_sel:WORD_1
	v_mov_b32_e32 v20, v21
	v_mov_b32_e32 v21, v22
	v_cvt_f32_f16_e32 v22, v76
	v_max_f32_e32 v26, 0xc1f00000, v26
	v_mul_f32_e32 v26, 0xbfb8aa3b, v26
	v_exp_f32_e32 v26, v26
	v_max_f32_e32 v22, 0xc1f00000, v22
	v_mul_f32_e32 v22, 0xbfb8aa3b, v22
	v_exp_f32_e32 v22, v22
	v_pk_mul_f32 v[20:21], v[20:21], v[24:25]
	v_add_f32_e32 v24, 1.0, v26
	v_rcp_f32_e32 v24, v24
	v_add_f32_e32 v22, 1.0, v22
	v_rcp_f32_e32 v25, v22
	v_pk_mov_b32 v[22:23], v[22:23], v[16:17] op_sel:[1,0]
	v_cvt_f32_f16_sdwa v16, v76 dst_sel:DWORD dst_unused:UNUSED_PAD src0_sel:WORD_1
	v_cvt_pk_f16_f32 v21, v20, v21
	v_pk_mul_f32 v[22:23], v[22:23], v[24:25]
	v_cvt_f32_f16_sdwa v25, v77 dst_sel:DWORD dst_unused:UNUSED_PAD src0_sel:WORD_1
	v_cvt_pk_f16_f32 v24, v22, v23
	v_cvt_f32_f16_e32 v22, v77
	v_max_f32_e32 v16, 0xc1f00000, v16
	v_mul_f32_e32 v16, 0xbfb8aa3b, v16
	v_exp_f32_e32 v16, v16
	v_max_f32_e32 v22, 0xc1f00000, v22
	v_mul_f32_e32 v22, 0xbfb8aa3b, v22
	v_exp_f32_e32 v23, v22
	v_add_f32_e32 v16, 1.0, v16
	v_rcp_f32_e32 v22, v16
	v_pack_b32_f16 v20, v27, v21
	v_add_f32_e32 v16, 1.0, v23
	v_rcp_f32_e32 v23, v16
	v_mov_b32_e32 v16, v17
	v_max_f32_e32 v17, 0xc1f00000, v25
	v_mul_f32_e32 v17, 0xbfb8aa3b, v17
	v_exp_f32_e32 v25, v17
	v_mov_b32_e32 v17, v18
	v_pk_mul_f32 v[16:17], v[16:17], v[22:23]
	v_cvt_f32_f16_e32 v18, v70
	v_cvt_pk_f16_f32 v16, v16, v17
	v_add_f32_e32 v17, 1.0, v25
	v_rcp_f32_e32 v17, v17
	v_alignbit_b32 v22, v16, v24, 16
	v_lshrrev_b32_e32 v23, 16, v16
	v_max_f32_e32 v16, 0xc1f00000, v18
	v_alignbit_b32 v21, v24, v21, 16
	v_fma_mixhi_f16 v23, v19, v17, 0
	v_mul_f32_e32 v16, 0xbfb8aa3b, v16
	v_cvt_f32_f16_sdwa v19, v70 dst_sel:DWORD dst_unused:UNUSED_PAD src0_sel:WORD_1
	v_exp_f32_e32 v18, v16
	global_store_dwordx4 v[34:35], v[20:23], off offset:256
	v_lshl_add_u64 v[16:17], v[192:193], 0, v[186:187]
	v_max_f32_e32 v19, 0xc1f00000, v19
	v_cvt_f32_f16_e32 v20, v71
	v_add_f32_e32 v18, 1.0, v18
	v_mul_f32_e32 v19, 0xbfb8aa3b, v19
	v_rcp_f32_e32 v18, v18
	v_max_f32_e32 v20, 0xc1f00000, v20
	v_exp_f32_e32 v19, v19
	v_mul_f32_e32 v20, 0xbfb8aa3b, v20
	v_exp_f32_e32 v20, v20
	v_fma_mixlo_f16 v21, v12, v18, 0
	v_add_f32_e32 v12, 1.0, v19
	v_rcp_f32_e32 v18, v12
	v_add_f32_e32 v12, 1.0, v20
	v_rcp_f32_e32 v19, v12
	v_cvt_f32_f16_sdwa v20, v71 dst_sel:DWORD dst_unused:UNUSED_PAD src0_sel:WORD_1
	v_mov_b32_e32 v12, v13
	v_mov_b32_e32 v13, v14
	v_cvt_f32_f16_e32 v14, v72
	v_pk_mul_f32 v[12:13], v[12:13], v[18:19]
	v_max_f32_e32 v18, 0xc1f00000, v20
	v_mul_f32_e32 v18, 0xbfb8aa3b, v18
	v_max_f32_e32 v14, 0xc1f00000, v14
	v_exp_f32_e32 v18, v18
	v_mul_f32_e32 v14, 0xbfb8aa3b, v14
	v_exp_f32_e32 v14, v14
	v_cvt_pk_f16_f32 v13, v12, v13
	v_add_f32_e32 v12, 1.0, v18
	v_rcp_f32_e32 v18, v12
	v_add_f32_e32 v12, 1.0, v14
	v_rcp_f32_e32 v19, v12
	v_pk_mov_b32 v[14:15], v[14:15], v[8:9] op_sel:[1,0]
	v_cvt_f32_f16_sdwa v8, v72 dst_sel:DWORD dst_unused:UNUSED_PAD src0_sel:WORD_1
	v_pack_b32_f16 v12, v21, v13
	v_pk_mul_f32 v[14:15], v[14:15], v[18:19]
	v_cvt_f32_f16_sdwa v19, v73 dst_sel:DWORD dst_unused:UNUSED_PAD src0_sel:WORD_1
	v_cvt_pk_f16_f32 v18, v14, v15
	v_cvt_f32_f16_e32 v14, v73
	v_max_f32_e32 v8, 0xc1f00000, v8
	v_mul_f32_e32 v8, 0xbfb8aa3b, v8
	v_exp_f32_e32 v8, v8
	v_max_f32_e32 v14, 0xc1f00000, v14
	v_mul_f32_e32 v14, 0xbfb8aa3b, v14
	v_exp_f32_e32 v15, v14
	v_add_f32_e32 v8, 1.0, v8
	v_rcp_f32_e32 v14, v8
	v_alignbit_b32 v13, v18, v13, 16
	v_add_f32_e32 v8, 1.0, v15
	v_rcp_f32_e32 v15, v8
	v_mov_b32_e32 v8, v9
	v_mov_b32_e32 v9, v10
	v_cvt_f32_f16_e32 v10, v66
	v_pk_mul_f32 v[8:9], v[8:9], v[14:15]
	global_store_dwordx4 v[34:35], v[28:31], off
	v_cvt_pk_f16_f32 v8, v8, v9
	v_max_f32_e32 v9, 0xc1f00000, v19
	v_mul_f32_e32 v9, 0xbfb8aa3b, v9
	v_exp_f32_e32 v9, v9
	v_alignbit_b32 v14, v8, v18, 16
	v_lshrrev_b32_e32 v15, 16, v8
	v_add_f32_e32 v8, 1.0, v9
	v_rcp_f32_e32 v8, v8
	v_max_f32_e32 v9, 0xc1f00000, v10
	v_mul_f32_e32 v9, 0xbfb8aa3b, v9
	v_exp_f32_e32 v9, v9
	v_fma_mixhi_f16 v15, v11, v8, 0
	v_cvt_f32_f16_sdwa v8, v66 dst_sel:DWORD dst_unused:UNUSED_PAD src0_sel:WORD_1
	v_cvt_f32_f16_e32 v10, v67
	v_add_f32_e32 v9, 1.0, v9
	v_rcp_f32_e32 v9, v9
	v_max_f32_e32 v8, 0xc1f00000, v8
	v_mul_f32_e32 v8, 0xbfb8aa3b, v8
	v_max_f32_e32 v10, 0xc1f00000, v10
	v_exp_f32_e32 v8, v8
	v_mul_f32_e32 v10, 0xbfb8aa3b, v10
	v_exp_f32_e32 v10, v10
	v_fma_mixlo_f16 v11, v4, v9, 0
	v_add_f32_e32 v4, 1.0, v8
	v_rcp_f32_e32 v8, v4
	v_add_f32_e32 v4, 1.0, v10
	v_rcp_f32_e32 v9, v4
	v_cvt_f32_f16_sdwa v10, v67 dst_sel:DWORD dst_unused:UNUSED_PAD src0_sel:WORD_1
	v_mov_b32_e32 v4, v5
	v_mov_b32_e32 v5, v6
	v_cvt_f32_f16_e32 v6, v68
	v_max_f32_e32 v10, 0xc1f00000, v10
	v_mul_f32_e32 v10, 0xbfb8aa3b, v10
	v_exp_f32_e32 v10, v10
	v_max_f32_e32 v6, 0xc1f00000, v6
	v_mul_f32_e32 v6, 0xbfb8aa3b, v6
	v_exp_f32_e32 v6, v6
	v_pk_mul_f32 v[4:5], v[4:5], v[8:9]
	v_add_f32_e32 v8, 1.0, v10
	v_rcp_f32_e32 v8, v8
	v_add_f32_e32 v6, 1.0, v6
	v_rcp_f32_e32 v9, v6
	v_pk_mov_b32 v[6:7], v[6:7], v[0:1] op_sel:[1,0]
	v_cvt_f32_f16_sdwa v0, v68 dst_sel:DWORD dst_unused:UNUSED_PAD src0_sel:WORD_1
	v_cvt_pk_f16_f32 v5, v4, v5
	v_pk_mul_f32 v[6:7], v[6:7], v[8:9]
	v_cvt_f32_f16_sdwa v9, v69 dst_sel:DWORD dst_unused:UNUSED_PAD src0_sel:WORD_1
	v_cvt_pk_f16_f32 v8, v6, v7
	v_cvt_f32_f16_e32 v6, v69
	v_max_f32_e32 v0, 0xc1f00000, v0
	v_mul_f32_e32 v0, 0xbfb8aa3b, v0
	v_exp_f32_e32 v0, v0
	v_max_f32_e32 v6, 0xc1f00000, v6
	v_mul_f32_e32 v6, 0xbfb8aa3b, v6
	v_exp_f32_e32 v7, v6
	v_add_f32_e32 v0, 1.0, v0
	v_rcp_f32_e32 v6, v0
	v_pack_b32_f16 v4, v11, v5
	v_add_f32_e32 v0, 1.0, v7
	v_rcp_f32_e32 v7, v0
	v_max_f32_e32 v0, 0xc1f00000, v9
	v_mul_f32_e32 v0, 0xbfb8aa3b, v0
	v_exp_f32_e32 v9, v0
	v_mov_b32_e32 v0, v1
	v_mov_b32_e32 v1, v2
	v_pk_mul_f32 v[0:1], v[0:1], v[6:7]
	v_add_f32_e32 v2, 1.0, v9
	v_rcp_f32_e32 v2, v2
	v_cvt_pk_f16_f32 v0, v0, v1
	v_lshrrev_b32_e32 v7, 16, v0
	v_alignbit_b32 v5, v8, v5, 16
	v_alignbit_b32 v6, v0, v8, 16
	v_fma_mixhi_f16 v7, v3, v2, 0
	global_store_dwordx4 v[16:17], v[12:15], off
	global_store_dwordx4 v[16:17], v[4:7], off offset:256
	s_and_b64 vcc, exec, s[4:5]
	s_mov_b32 s31, s30
	s_mov_b32 s34, s29
	s_mov_b64 s[12:13], s[0:1]
	s_mov_b64 s[10:11], s[2:3]
	s_cbranch_vccz .LBB0_955
	s_waitcnt vmcnt(0)
	s_cmpk_gt_u32 s19, 0xff
	s_cbranch_scc1 .LBB0_962
	s_barrier

.LBB0_1117:
	s_add_i32 s41, s22, 2
	s_add_u32 s20, s14, 0x100
	s_addc_u32 s21, s15, 0
	s_add_i32 s42, 0, 0x10000
	s_waitcnt vmcnt(0)
	v_add_u32_e32 v102, s42, v230
	ds_read_b128 v[78:81], v102
	ds_read_b128 v[94:97], v102 offset:2048
	ds_read_b128 v[86:89], v102 offset:1024
	ds_read_b128 v[102:105], v102 offset:3072
	s_cmp_eq_u32 s38, s22
	s_cselect_b32 s22, s18, s39
	s_cselect_b32 s25, s17, s21
	s_cselect_b32 s24, s16, s20
	s_cselect_b32 s23, s19, s40
	v_lshl_add_u64 v[178:179], s[14:15], 0, v[200:201]
	s_add_i32 m0, s28, 0xc000
	ds_read_b128 v[122:125], v232
	ds_read_b128 v[130:133], v232 offset:2048
	ds_read_b128 v[154:157], v232 offset:4096
	ds_read_b128 v[170:173], v232 offset:6144
	ds_read_b128 v[126:129], v232 offset:1024
	ds_read_b128 v[134:137], v232 offset:3072
	ds_read_b128 v[158:161], v232 offset:5120
	ds_read_b128 v[174:177], v232 offset:7168
	global_load_lds_dwordx4 v[178:179], off
	v_lshl_add_u64 v[178:179], s[14:15], 0, v[202:203]
	s_add_i32 m0, s28, 0xe000
	s_nop 0
	global_load_lds_dwordx4 v[178:179], off
	s_waitcnt lgkmcnt(8)
	s_barrier
	s_waitcnt lgkmcnt(4)
	s_setprio 1
	v_mfma_f32_16x16x32_f16 v[166:169], v[78:81], v[122:125], v[166:169]
	v_mfma_f32_16x16x32_f16 v[162:165], v[94:97], v[122:125], v[162:165]
	v_mfma_f32_16x16x32_f16 v[150:153], v[78:81], v[130:133], v[150:153]
	v_mfma_f32_16x16x32_f16 v[142:145], v[94:97], v[130:133], v[142:145]
	v_mfma_f32_16x16x32_f16 v[110:113], v[78:81], v[154:157], v[110:113]
	v_mfma_f32_16x16x32_f16 v[106:109], v[94:97], v[154:157], v[106:109]
	v_mfma_f32_16x16x32_f16 v[82:85], v[78:81], v[170:173], v[82:85]
	v_mfma_f32_16x16x32_f16 v[74:77], v[94:97], v[170:173], v[74:77]
	s_waitcnt lgkmcnt(0)
	v_mfma_f32_16x16x32_f16 v[166:169], v[86:89], v[126:129], v[166:169]
	v_mfma_f32_16x16x32_f16 v[162:165], v[102:105], v[126:129], v[162:165]
	v_mfma_f32_16x16x32_f16 v[150:153], v[86:89], v[134:137], v[150:153]
	v_mfma_f32_16x16x32_f16 v[142:145], v[102:105], v[134:137], v[142:145]
	v_mfma_f32_16x16x32_f16 v[110:113], v[86:89], v[158:161], v[110:113]
	v_mfma_f32_16x16x32_f16 v[106:109], v[102:105], v[158:161], v[106:109]
	v_mfma_f32_16x16x32_f16 v[82:85], v[86:89], v[174:177], v[82:85]
	v_mfma_f32_16x16x32_f16 v[74:77], v[102:105], v[174:177], v[74:77]
	s_setprio 0
	s_barrier
	s_add_i32 s43, 0, 0x14000
	s_add_i32 s14, s42, s13
	v_add_u32_e32 v190, s43, v230
	v_lshl_add_u64 v[204:205], s[22:23], 0, v[32:33]
	s_mov_b32 m0, s14
	ds_read_b128 v[178:181], v190
	ds_read_b128 v[186:189], v190 offset:2048
	ds_read_b128 v[182:185], v190 offset:1024
	ds_read_b128 v[190:193], v190 offset:3072
	global_load_lds_dwordx4 v[204:205], off
	v_lshl_add_u64 v[206:207], s[22:23], 0, v[198:199]
	s_add_i32 m0, s14, 0x2000
	s_nop 0
	global_load_lds_dwordx4 v[206:207], off
	s_barrier
	s_waitcnt lgkmcnt(1)
	s_setprio 1
	v_mfma_f32_16x16x32_f16 v[146:149], v[178:181], v[122:125], v[146:149]
	v_mfma_f32_16x16x32_f16 v[118:121], v[178:181], v[130:133], v[118:121]
	v_mfma_f32_16x16x32_f16 v[114:117], v[186:189], v[130:133], v[114:117]
	v_mfma_f32_16x16x32_f16 v[98:101], v[178:181], v[154:157], v[98:101]
	v_mfma_f32_16x16x32_f16 v[90:93], v[186:189], v[154:157], v[90:93]
	v_mfma_f32_16x16x32_f16 v[70:73], v[178:181], v[170:173], v[70:73]
	v_mfma_f32_16x16x32_f16 v[66:69], v[186:189], v[170:173], v[66:69]
	v_mfma_f32_16x16x32_f16 v[146:149], v[182:185], v[126:129], v[146:149]
	s_waitcnt lgkmcnt(0)
	v_mfma_f32_16x16x32_f16 v[122:125], v[186:189], v[122:125], v[138:141]
	v_mfma_f32_16x16x32_f16 v[118:121], v[182:185], v[134:137], v[118:121]
	v_mfma_f32_16x16x32_f16 v[114:117], v[190:193], v[134:137], v[114:117]
	v_mfma_f32_16x16x32_f16 v[98:101], v[182:185], v[158:161], v[98:101]
	v_mfma_f32_16x16x32_f16 v[90:93], v[190:193], v[158:161], v[90:93]
	v_mfma_f32_16x16x32_f16 v[70:73], v[182:185], v[174:177], v[70:73]
	v_mfma_f32_16x16x32_f16 v[66:69], v[190:193], v[174:177], v[66:69]
	v_mfma_f32_16x16x32_f16 v[122:125], v[190:193], v[126:129], v[122:125]
	s_setprio 0
	s_mov_b32 m0, s28
	v_lshl_add_u64 v[208:209], s[24:25], 0, v[32:33]
	s_barrier
	ds_read_b128 v[126:129], v232 offset:16384
	ds_read_b128 v[134:137], v232 offset:18432
	ds_read_b128 v[154:157], v232 offset:20480
	ds_read_b128 v[170:173], v232 offset:22528
	ds_read_b128 v[130:133], v232 offset:17408
	ds_read_b128 v[138:141], v232 offset:19456
	ds_read_b128 v[158:161], v232 offset:21504
	ds_read_b128 v[174:177], v232 offset:23552
	global_load_lds_dwordx4 v[208:209], off
	v_lshl_add_u64 v[210:211], s[24:25], 0, v[198:199]
	s_mov_b32 m0, s29
	s_nop 0
	global_load_lds_dwordx4 v[210:211], off
	s_barrier
	s_waitcnt lgkmcnt(4)
	s_setprio 1
	v_mfma_f32_16x16x32_f16 v[62:65], v[78:81], v[126:129], v[62:65]
	v_mfma_f32_16x16x32_f16 v[58:61], v[94:97], v[126:129], v[58:61]
	v_mfma_f32_16x16x32_f16 v[46:49], v[78:81], v[134:137], v[46:49]
	v_mfma_f32_16x16x32_f16 v[42:45], v[94:97], v[134:137], v[42:45]
	v_mfma_f32_16x16x32_f16 v[28:31], v[78:81], v[154:157], v[28:31]
	v_mfma_f32_16x16x32_f16 v[24:27], v[94:97], v[154:157], v[24:27]
	v_mfma_f32_16x16x32_f16 v[12:15], v[78:81], v[170:173], v[12:15]
	v_mfma_f32_16x16x32_f16 v[8:11], v[94:97], v[170:173], v[8:11]
	s_waitcnt lgkmcnt(0)
	v_mfma_f32_16x16x32_f16 v[62:65], v[86:89], v[130:133], v[62:65]
	v_mfma_f32_16x16x32_f16 v[58:61], v[102:105], v[130:133], v[58:61]
	v_mfma_f32_16x16x32_f16 v[46:49], v[86:89], v[138:141], v[46:49]
	v_mfma_f32_16x16x32_f16 v[42:45], v[102:105], v[138:141], v[42:45]
	v_mfma_f32_16x16x32_f16 v[28:31], v[86:89], v[158:161], v[28:31]
	v_mfma_f32_16x16x32_f16 v[24:27], v[102:105], v[158:161], v[24:27]
	v_mfma_f32_16x16x32_f16 v[12:15], v[86:89], v[174:177], v[12:15]
	v_mfma_f32_16x16x32_f16 v[8:11], v[102:105], v[174:177], v[8:11]
	s_setprio 0
	s_barrier
	s_add_u32 s14, s22, 0x40000
	s_addc_u32 s15, s23, 0
	s_add_i32 s42, s43, s13
	v_lshl_add_u64 v[78:79], s[14:15], 0, v[32:33]
	s_mov_b32 m0, s42
	s_nop 0
	global_load_lds_dwordx4 v[78:79], off
	v_lshl_add_u64 v[78:79], s[14:15], 0, v[198:199]
	s_add_i32 m0, s42, 0x2000
	s_nop 0
	global_load_lds_dwordx4 v[78:79], off
	s_waitcnt vmcnt(6)
	s_barrier
	s_setprio 1
	v_mfma_f32_16x16x32_f16 v[54:57], v[178:181], v[126:129], v[54:57]
	v_mfma_f32_16x16x32_f16 v[50:53], v[186:189], v[126:129], v[50:53]
	v_mfma_f32_16x16x32_f16 v[38:41], v[178:181], v[134:137], v[38:41]
	v_mfma_f32_16x16x32_f16 v[34:37], v[186:189], v[134:137], v[34:37]
	v_mfma_f32_16x16x32_f16 v[20:23], v[178:181], v[154:157], v[20:23]
	v_mfma_f32_16x16x32_f16 v[16:19], v[186:189], v[154:157], v[16:19]
	v_mfma_f32_16x16x32_f16 v[4:7], v[178:181], v[170:173], v[4:7]
	v_mfma_f32_16x16x32_f16 v[0:3], v[186:189], v[170:173], v[0:3]
	v_mfma_f32_16x16x32_f16 v[54:57], v[182:185], v[130:133], v[54:57]
	v_mfma_f32_16x16x32_f16 v[50:53], v[190:193], v[130:133], v[50:53]
	v_mfma_f32_16x16x32_f16 v[38:41], v[182:185], v[138:141], v[38:41]
	v_mfma_f32_16x16x32_f16 v[34:37], v[190:193], v[138:141], v[34:37]
	v_mfma_f32_16x16x32_f16 v[20:23], v[182:185], v[158:161], v[20:23]
	v_mfma_f32_16x16x32_f16 v[16:19], v[190:193], v[158:161], v[16:19]
	v_mfma_f32_16x16x32_f16 v[4:7], v[182:185], v[174:177], v[4:7]
	v_mfma_f32_16x16x32_f16 v[0:3], v[190:193], v[174:177], v[0:3]
	s_setprio 0
	s_add_i32 s42, 0, 0x18000
	v_add_u32_e32 v102, s42, v230
	s_barrier
	ds_read_b128 v[78:81], v102
	ds_read_b128 v[86:89], v102 offset:1024
	ds_read_b128 v[94:97], v102 offset:2048
	ds_read_b128 v[102:105], v102 offset:3072
	s_add_u32 s14, s24, 0x40000
	s_addc_u32 s15, s25, 0
	s_mov_b32 m0, s30
	v_lshl_add_u64 v[138:139], s[14:15], 0, v[32:33]
	ds_read_b128 v[126:129], v232 offset:32768
	ds_read_b128 v[130:133], v232 offset:33792
	ds_read_b128 v[134:137], v232 offset:34816
	ds_read_b128 v[154:157], v232 offset:35840
	ds_read_b128 v[158:161], v232 offset:36864
	ds_read_b128 v[174:177], v232 offset:38912
	ds_read_b128 v[170:173], v232 offset:37888
	ds_read_b128 v[178:181], v232 offset:39936
	global_load_lds_dwordx4 v[138:139], off
	v_lshl_add_u64 v[138:139], s[14:15], 0, v[198:199]
	s_mov_b32 m0, s31
	s_nop 0
	global_load_lds_dwordx4 v[138:139], off
	s_waitcnt lgkmcnt(8)
	s_barrier
	s_waitcnt lgkmcnt(3)
	s_setprio 1
	v_mfma_f32_16x16x32_f16 v[138:141], v[78:81], v[126:129], v[166:169]
	v_mfma_f32_16x16x32_f16 v[166:169], v[86:89], v[130:133], v[138:141]
	v_mfma_f32_16x16x32_f16 v[138:141], v[94:97], v[126:129], v[162:165]
	v_mfma_f32_16x16x32_f16 v[162:165], v[102:105], v[130:133], v[138:141]
	v_mfma_f32_16x16x32_f16 v[138:141], v[78:81], v[134:137], v[150:153]
	v_mfma_f32_16x16x32_f16 v[150:153], v[86:89], v[154:157], v[138:141]
	v_mfma_f32_16x16x32_f16 v[138:141], v[94:97], v[134:137], v[142:145]
	v_mfma_f32_16x16x32_f16 v[110:113], v[78:81], v[158:161], v[110:113]
	s_waitcnt lgkmcnt(0)
	v_mfma_f32_16x16x32_f16 v[106:109], v[94:97], v[158:161], v[106:109]
	v_mfma_f32_16x16x32_f16 v[82:85], v[78:81], v[174:177], v[82:85]
	v_mfma_f32_16x16x32_f16 v[74:77], v[94:97], v[174:177], v[74:77]
	v_mfma_f32_16x16x32_f16 v[142:145], v[102:105], v[154:157], v[138:141]
	v_mfma_f32_16x16x32_f16 v[110:113], v[86:89], v[170:173], v[110:113]
	v_mfma_f32_16x16x32_f16 v[106:109], v[102:105], v[170:173], v[106:109]
	v_mfma_f32_16x16x32_f16 v[82:85], v[86:89], v[178:181], v[82:85]
	v_mfma_f32_16x16x32_f16 v[74:77], v[102:105], v[178:181], v[74:77]
	s_setprio 0
	s_barrier
	s_add_i32 s24, 0, 0x1c000
	v_add_u32_e32 v138, s24, v230
	s_add_i32 s14, s42, s13
	ds_read_b128 v[182:185], v138
	ds_read_b128 v[190:193], v138 offset:2048
	ds_read_b128 v[186:189], v138 offset:1024
	ds_read_b128 v[194:197], v138 offset:3072
	v_lshl_add_u64 v[138:139], v[204:205], 0, s[84:85]
	s_mov_b32 m0, s14
	s_nop 0
	global_load_lds_dwordx4 v[138:139], off
	v_lshl_add_u64 v[138:139], v[206:207], 0, s[84:85]
	s_add_i32 m0, s14, 0x2000
	s_nop 0
	global_load_lds_dwordx4 v[138:139], off
	s_barrier
	s_waitcnt lgkmcnt(2)
	s_setprio 1
	v_mfma_f32_16x16x32_f16 v[138:141], v[182:185], v[126:129], v[146:149]
	v_mfma_f32_16x16x32_f16 v[122:125], v[190:193], v[126:129], v[122:125]
	v_mfma_f32_16x16x32_f16 v[118:121], v[182:185], v[134:137], v[118:121]
	v_mfma_f32_16x16x32_f16 v[114:117], v[190:193], v[134:137], v[114:117]
	v_mfma_f32_16x16x32_f16 v[98:101], v[182:185], v[158:161], v[98:101]
	v_mfma_f32_16x16x32_f16 v[90:93], v[190:193], v[158:161], v[90:93]
	v_mfma_f32_16x16x32_f16 v[70:73], v[182:185], v[174:177], v[70:73]
	v_mfma_f32_16x16x32_f16 v[66:69], v[190:193], v[174:177], v[66:69]
	s_waitcnt lgkmcnt(0)
	v_mfma_f32_16x16x32_f16 v[146:149], v[186:189], v[130:133], v[138:141]
	v_mfma_f32_16x16x32_f16 v[138:141], v[194:197], v[130:133], v[122:125]
	v_mfma_f32_16x16x32_f16 v[118:121], v[186:189], v[154:157], v[118:121]
	v_mfma_f32_16x16x32_f16 v[114:117], v[194:197], v[154:157], v[114:117]
	v_mfma_f32_16x16x32_f16 v[98:101], v[186:189], v[170:173], v[98:101]
	v_mfma_f32_16x16x32_f16 v[90:93], v[194:197], v[170:173], v[90:93]
	v_mfma_f32_16x16x32_f16 v[70:73], v[186:189], v[178:181], v[70:73]
	v_mfma_f32_16x16x32_f16 v[66:69], v[194:197], v[178:181], v[66:69]
	s_setprio 0
	s_mov_b32 m0, s34
	v_lshl_add_u64 v[178:179], v[208:209], 0, s[84:85]
	s_barrier
	ds_read_b128 v[122:125], v232 offset:49152
	ds_read_b128 v[130:133], v232 offset:51200
	ds_read_b128 v[154:157], v232 offset:53248
	ds_read_b128 v[170:173], v232 offset:55296
	ds_read_b128 v[126:129], v232 offset:50176
	ds_read_b128 v[134:137], v232 offset:52224
	ds_read_b128 v[158:161], v232 offset:54272
	ds_read_b128 v[174:177], v232 offset:56320
	global_load_lds_dwordx4 v[178:179], off
	v_lshl_add_u64 v[178:179], v[210:211], 0, s[84:85]
	s_mov_b32 m0, s35
	s_nop 0
	global_load_lds_dwordx4 v[178:179], off
	s_barrier
	s_waitcnt lgkmcnt(4)
	s_setprio 1
	v_mfma_f32_16x16x32_f16 v[62:65], v[78:81], v[122:125], v[62:65]
	v_mfma_f32_16x16x32_f16 v[58:61], v[94:97], v[122:125], v[58:61]
	v_mfma_f32_16x16x32_f16 v[46:49], v[78:81], v[130:133], v[46:49]
	v_mfma_f32_16x16x32_f16 v[42:45], v[94:97], v[130:133], v[42:45]
	v_mfma_f32_16x16x32_f16 v[28:31], v[78:81], v[154:157], v[28:31]
	v_mfma_f32_16x16x32_f16 v[24:27], v[94:97], v[154:157], v[24:27]
	v_mfma_f32_16x16x32_f16 v[12:15], v[78:81], v[170:173], v[12:15]
	v_mfma_f32_16x16x32_f16 v[8:11], v[94:97], v[170:173], v[8:11]
	s_waitcnt lgkmcnt(0)
	v_mfma_f32_16x16x32_f16 v[62:65], v[86:89], v[126:129], v[62:65]
	v_mfma_f32_16x16x32_f16 v[58:61], v[102:105], v[126:129], v[58:61]
	v_mfma_f32_16x16x32_f16 v[46:49], v[86:89], v[134:137], v[46:49]
	v_mfma_f32_16x16x32_f16 v[42:45], v[102:105], v[134:137], v[42:45]
	v_mfma_f32_16x16x32_f16 v[28:31], v[86:89], v[158:161], v[28:31]
	v_mfma_f32_16x16x32_f16 v[24:27], v[102:105], v[158:161], v[24:27]
	v_mfma_f32_16x16x32_f16 v[12:15], v[86:89], v[174:177], v[12:15]
	v_mfma_f32_16x16x32_f16 v[8:11], v[102:105], v[174:177], v[8:11]
	s_setprio 0
	s_barrier
	s_add_u32 s14, s22, 0x40080
	s_addc_u32 s15, s23, 0
	s_add_i32 s22, s24, s13
	v_lshl_add_u64 v[78:79], s[14:15], 0, v[32:33]
	s_mov_b32 m0, s22
	s_nop 0
	global_load_lds_dwordx4 v[78:79], off
	v_lshl_add_u64 v[78:79], s[14:15], 0, v[198:199]
	s_add_i32 m0, s22, 0x2000
	s_nop 0
	global_load_lds_dwordx4 v[78:79], off
	s_waitcnt vmcnt(6)
	s_barrier
	s_setprio 1
	v_mfma_f32_16x16x32_f16 v[54:57], v[182:185], v[122:125], v[54:57]
	v_mfma_f32_16x16x32_f16 v[50:53], v[190:193], v[122:125], v[50:53]
	v_mfma_f32_16x16x32_f16 v[38:41], v[182:185], v[130:133], v[38:41]
	v_mfma_f32_16x16x32_f16 v[34:37], v[190:193], v[130:133], v[34:37]
	v_mfma_f32_16x16x32_f16 v[20:23], v[182:185], v[154:157], v[20:23]
	v_mfma_f32_16x16x32_f16 v[16:19], v[190:193], v[154:157], v[16:19]
	v_mfma_f32_16x16x32_f16 v[4:7], v[182:185], v[170:173], v[4:7]
	v_mfma_f32_16x16x32_f16 v[0:3], v[190:193], v[170:173], v[0:3]
	v_mfma_f32_16x16x32_f16 v[54:57], v[186:189], v[126:129], v[54:57]
	v_mfma_f32_16x16x32_f16 v[50:53], v[194:197], v[126:129], v[50:53]
	v_mfma_f32_16x16x32_f16 v[38:41], v[186:189], v[134:137], v[38:41]
	v_mfma_f32_16x16x32_f16 v[34:37], v[194:197], v[134:137], v[34:37]
	v_mfma_f32_16x16x32_f16 v[20:23], v[186:189], v[158:161], v[20:23]
	v_mfma_f32_16x16x32_f16 v[16:19], v[194:197], v[158:161], v[16:19]
	v_mfma_f32_16x16x32_f16 v[4:7], v[186:189], v[174:177], v[4:7]
	v_mfma_f32_16x16x32_f16 v[0:3], v[194:197], v[174:177], v[0:3]
	s_setprio 0
	s_add_u32 s39, s39, 0x100
	s_addc_u32 s40, s40, 0
	s_cmp_ge_u32 s41, s37
	s_mov_b64 s[14:15], s[20:21]
	s_mov_b32 s22, s41
	s_barrier
	s_cbranch_scc0 .LBB0_1117
	v_lshl_or_b32 v124, s12, 8, v231
	s_cmp_eq_u32 s10, 0
	s_movk_i32 s12, 0x5000
	s_cselect_b32 s12, 0xe000, s12
	v_readlane_b32 s14, v252, 51
	s_add_u32 s14, s14, s12
	v_readlane_b32 s12, v252, 52
	s_addc_u32 s15, s12, 0
	v_ashrrev_i32_e32 v125, 31, v124
	v_lshl_add_u64 v[86:87], v[124:125], 2, s[14:15]
	global_load_dwordx4 v[94:97], v[86:87], off offset:16
	global_load_dwordx4 v[102:105], v[86:87], off
	global_load_dwordx4 v[78:81], v[86:87], off offset:528
	s_nop 0
	global_load_dwordx4 v[86:89], v[86:87], off offset:512
	v_lshl_add_u32 v130, s10, 8, v229
	v_or_b32_e32 v128, 16, v130
	v_or_b32_e32 v126, 32, v130
	v_or_b32_e32 v122, 48, v130
	s_cmp_eq_u32 s11, 0
	v_ashrrev_i32_e32 v131, 31, v130
	v_ashrrev_i32_e32 v129, 31, v128
	v_ashrrev_i32_e32 v127, 31, v126
	v_ashrrev_i32_e32 v123, 31, v122
	s_cbranch_scc1 .LBB0_1120
	s_add_i32 s96, s11, -1
	s_lshl_b64 s[10:11], s[96:97], 20
	v_readlane_b32 s14, v252, 11
	v_readlane_b32 s15, v252, 12
	s_add_u32 s10, s14, s10
	s_addc_u32 s11, s15, s11
	v_lshlrev_b64 v[132:133], 2, v[124:125]
	v_lshrrev_b32_e32 v134, 5, v220
	v_mul_u32_u24_e32 v134, 48, v134
	s_nop 0
	v_sub_co_u32_e32 v132, vcc, v132, v134
	s_nop 1
	v_subbrev_co_u32_e32 v133, vcc, 0, v133, vcc
	v_lshl_add_u64 v[132:133], s[10:11], 0, v[132:133]
	s_mov_b64 s[10:11], 0x80000
	v_lshlrev_b64 v[204:205], 12, v[130:131]
	v_lshl_add_u64 v[204:205], v[204:205], 0, v[132:133]
	v_lshl_add_u64 v[212:213], v[204:205], 0, s[10:11]
	v_lshlrev_b64 v[206:207], 12, v[128:129]
	v_lshl_add_u64 v[206:207], v[206:207], 0, v[132:133]
	v_lshl_add_u64 v[214:215], v[206:207], 0, s[10:11]
	v_lshlrev_b64 v[208:209], 12, v[126:127]
	v_lshl_add_u64 v[208:209], v[208:209], 0, v[132:133]
	v_lshl_add_u64 v[216:217], v[208:209], 0, s[10:11]
	v_lshlrev_b64 v[210:211], 12, v[122:123]
	v_lshl_add_u64 v[210:211], v[210:211], 0, v[132:133]
	v_lshl_add_u64 v[218:219], v[210:211], 0, s[10:11]
	s_waitcnt vmcnt(0)
	v_pk_mul_f32 v[172:173], v[166:167], v[102:103]
	v_pk_mul_f32 v[174:175], v[168:169], v[104:105]
	v_pk_mul_f32 v[176:177], v[162:163], v[94:95]
	v_pk_mul_f32 v[178:179], v[164:165], v[96:97]
	s_nop 1
	v_permlane32_swap_b32_e32 v172, v176
	v_permlane32_swap_b32_e32 v173, v177
	v_permlane32_swap_b32_e32 v174, v178
	v_permlane32_swap_b32_e32 v175, v179
	s_nop 0
	global_store_dwordx4 v[204:205], v[172:175], off
	global_store_dwordx4 v[204:205], v[176:179], off offset:64
	v_pk_mul_f32 v[180:181], v[146:147], v[86:87]
	v_pk_mul_f32 v[182:183], v[148:149], v[88:89]
	v_pk_mul_f32 v[184:185], v[138:139], v[78:79]
	v_pk_mul_f32 v[186:187], v[140:141], v[80:81]
	s_nop 1
	v_permlane32_swap_b32_e32 v180, v184
	v_permlane32_swap_b32_e32 v181, v185
	v_permlane32_swap_b32_e32 v182, v186
	v_permlane32_swap_b32_e32 v183, v187
	s_nop 0
	global_store_dwordx4 v[204:205], v[180:183], off offset:512
	global_store_dwordx4 v[204:205], v[184:187], off offset:576
	v_pk_mul_f32 v[188:189], v[150:151], v[102:103]
	v_pk_mul_f32 v[190:191], v[152:153], v[104:105]
	v_pk_mul_f32 v[192:193], v[142:143], v[94:95]
	v_pk_mul_f32 v[194:195], v[144:145], v[96:97]
	s_nop 1
	v_permlane32_swap_b32_e32 v188, v192
	v_permlane32_swap_b32_e32 v189, v193
	v_permlane32_swap_b32_e32 v190, v194
	v_permlane32_swap_b32_e32 v191, v195
	s_nop 0
	global_store_dwordx4 v[206:207], v[188:191], off
	global_store_dwordx4 v[206:207], v[192:195], off offset:64
	v_pk_mul_f32 v[154:155], v[118:119], v[86:87]
	v_pk_mul_f32 v[156:157], v[120:121], v[88:89]
	v_pk_mul_f32 v[158:159], v[114:115], v[78:79]
	v_pk_mul_f32 v[160:161], v[116:117], v[80:81]
	s_nop 1
	v_permlane32_swap_b32_e32 v154, v158
	v_permlane32_swap_b32_e32 v155, v159
	v_permlane32_swap_b32_e32 v156, v160
	v_permlane32_swap_b32_e32 v157, v161
	s_nop 0
	global_store_dwordx4 v[206:207], v[154:157], off offset:512
	global_store_dwordx4 v[206:207], v[158:161], off offset:576
	v_pk_mul_f32 v[172:173], v[110:111], v[102:103]
	v_pk_mul_f32 v[174:175], v[112:113], v[104:105]
	v_pk_mul_f32 v[176:177], v[106:107], v[94:95]
	v_pk_mul_f32 v[178:179], v[108:109], v[96:97]
	s_nop 1
	v_permlane32_swap_b32_e32 v172, v176
	v_permlane32_swap_b32_e32 v173, v177
	v_permlane32_swap_b32_e32 v174, v178
	v_permlane32_swap_b32_e32 v175, v179
	s_nop 0
	global_store_dwordx4 v[208:209], v[172:175], off
	global_store_dwordx4 v[208:209], v[176:179], off offset:64
	v_pk_mul_f32 v[180:181], v[98:99], v[86:87]
	v_pk_mul_f32 v[182:183], v[100:101], v[88:89]
	v_pk_mul_f32 v[184:185], v[90:91], v[78:79]
	v_pk_mul_f32 v[186:187], v[92:93], v[80:81]
	s_nop 1
	v_permlane32_swap_b32_e32 v180, v184
	v_permlane32_swap_b32_e32 v181, v185
	v_permlane32_swap_b32_e32 v182, v186
	v_permlane32_swap_b32_e32 v183, v187
	s_nop 0
	global_store_dwordx4 v[208:209], v[180:183], off offset:512
	global_store_dwordx4 v[208:209], v[184:187], off offset:576
	v_pk_mul_f32 v[188:189], v[82:83], v[102:103]
	v_pk_mul_f32 v[190:191], v[84:85], v[104:105]
	v_pk_mul_f32 v[192:193], v[74:75], v[94:95]
	v_pk_mul_f32 v[194:195], v[76:77], v[96:97]
	s_nop 1
	v_permlane32_swap_b32_e32 v188, v192
	v_permlane32_swap_b32_e32 v189, v193
	v_permlane32_swap_b32_e32 v190, v194
	v_permlane32_swap_b32_e32 v191, v195
	s_nop 0
	global_store_dwordx4 v[210:211], v[188:191], off
	global_store_dwordx4 v[210:211], v[192:195], off offset:64
	v_pk_mul_f32 v[154:155], v[70:71], v[86:87]
	v_pk_mul_f32 v[156:157], v[72:73], v[88:89]
	v_pk_mul_f32 v[158:159], v[66:67], v[78:79]
	v_pk_mul_f32 v[160:161], v[68:69], v[80:81]
	s_nop 1
	v_permlane32_swap_b32_e32 v154, v158
	v_permlane32_swap_b32_e32 v155, v159
	v_permlane32_swap_b32_e32 v156, v160
	v_permlane32_swap_b32_e32 v157, v161
	s_nop 0
	global_store_dwordx4 v[210:211], v[154:157], off offset:512
	global_store_dwordx4 v[210:211], v[158:161], off offset:576
	v_pk_mul_f32 v[172:173], v[62:63], v[102:103]
	v_pk_mul_f32 v[174:175], v[64:65], v[104:105]
	v_pk_mul_f32 v[176:177], v[58:59], v[94:95]
	v_pk_mul_f32 v[178:179], v[60:61], v[96:97]
	s_nop 1
	v_permlane32_swap_b32_e32 v172, v176
	v_permlane32_swap_b32_e32 v173, v177
	v_permlane32_swap_b32_e32 v174, v178
	v_permlane32_swap_b32_e32 v175, v179
	s_nop 0
	global_store_dwordx4 v[212:213], v[172:175], off
	global_store_dwordx4 v[212:213], v[176:179], off offset:64
	v_pk_mul_f32 v[180:181], v[54:55], v[86:87]
	v_pk_mul_f32 v[182:183], v[56:57], v[88:89]
	v_pk_mul_f32 v[184:185], v[50:51], v[78:79]
	v_pk_mul_f32 v[186:187], v[52:53], v[80:81]
	s_nop 1
	v_permlane32_swap_b32_e32 v180, v184
	v_permlane32_swap_b32_e32 v181, v185
	v_permlane32_swap_b32_e32 v182, v186
	v_permlane32_swap_b32_e32 v183, v187
	s_nop 0
	global_store_dwordx4 v[212:213], v[180:183], off offset:512
	global_store_dwordx4 v[212:213], v[184:187], off offset:576
	v_pk_mul_f32 v[188:189], v[46:47], v[102:103]
	v_pk_mul_f32 v[190:191], v[48:49], v[104:105]
	v_pk_mul_f32 v[192:193], v[42:43], v[94:95]
	v_pk_mul_f32 v[194:195], v[44:45], v[96:97]
	s_nop 1
	v_permlane32_swap_b32_e32 v188, v192
	v_permlane32_swap_b32_e32 v189, v193
	v_permlane32_swap_b32_e32 v190, v194
	v_permlane32_swap_b32_e32 v191, v195
	s_nop 0
	global_store_dwordx4 v[214:215], v[188:191], off
	global_store_dwordx4 v[214:215], v[192:195], off offset:64
	v_pk_mul_f32 v[154:155], v[38:39], v[86:87]
	v_pk_mul_f32 v[156:157], v[40:41], v[88:89]
	v_pk_mul_f32 v[158:159], v[34:35], v[78:79]
	v_pk_mul_f32 v[160:161], v[36:37], v[80:81]
	s_nop 1
	v_permlane32_swap_b32_e32 v154, v158
	v_permlane32_swap_b32_e32 v155, v159
	v_permlane32_swap_b32_e32 v156, v160
	v_permlane32_swap_b32_e32 v157, v161
	s_nop 0
	global_store_dwordx4 v[214:215], v[154:157], off offset:512
	global_store_dwordx4 v[214:215], v[158:161], off offset:576
	v_pk_mul_f32 v[172:173], v[28:29], v[102:103]
	v_pk_mul_f32 v[174:175], v[30:31], v[104:105]
	v_pk_mul_f32 v[176:177], v[24:25], v[94:95]
	v_pk_mul_f32 v[178:179], v[26:27], v[96:97]
	s_nop 1
	v_permlane32_swap_b32_e32 v172, v176
	v_permlane32_swap_b32_e32 v173, v177
	v_permlane32_swap_b32_e32 v174, v178
	v_permlane32_swap_b32_e32 v175, v179
	s_nop 0
	global_store_dwordx4 v[216:217], v[172:175], off
	global_store_dwordx4 v[216:217], v[176:179], off offset:64
	v_pk_mul_f32 v[180:181], v[20:21], v[86:87]
	v_pk_mul_f32 v[182:183], v[22:23], v[88:89]
	v_pk_mul_f32 v[184:185], v[16:17], v[78:79]
	v_pk_mul_f32 v[186:187], v[18:19], v[80:81]
	s_nop 1
	v_permlane32_swap_b32_e32 v180, v184
	v_permlane32_swap_b32_e32 v181, v185
	v_permlane32_swap_b32_e32 v182, v186
	v_permlane32_swap_b32_e32 v183, v187
	s_nop 0
	global_store_dwordx4 v[216:217], v[180:183], off offset:512
	global_store_dwordx4 v[216:217], v[184:187], off offset:576
	v_pk_mul_f32 v[188:189], v[12:13], v[102:103]
	v_pk_mul_f32 v[190:191], v[14:15], v[104:105]
	v_pk_mul_f32 v[192:193], v[8:9], v[94:95]
	v_pk_mul_f32 v[194:195], v[10:11], v[96:97]
	s_nop 1
	v_permlane32_swap_b32_e32 v188, v192
	v_permlane32_swap_b32_e32 v189, v193
	v_permlane32_swap_b32_e32 v190, v194
	v_permlane32_swap_b32_e32 v191, v195
	s_nop 0
	global_store_dwordx4 v[218:219], v[188:191], off
	global_store_dwordx4 v[218:219], v[192:195], off offset:64
	v_pk_mul_f32 v[154:155], v[4:5], v[86:87]
	v_pk_mul_f32 v[156:157], v[6:7], v[88:89]
	v_pk_mul_f32 v[158:159], v[0:1], v[78:79]
	v_pk_mul_f32 v[160:161], v[2:3], v[80:81]
	s_nop 1
	v_permlane32_swap_b32_e32 v154, v158
	v_permlane32_swap_b32_e32 v155, v159
	v_permlane32_swap_b32_e32 v156, v160
	v_permlane32_swap_b32_e32 v157, v161
	s_nop 0
	global_store_dwordx4 v[218:219], v[154:157], off offset:512
	global_store_dwordx4 v[218:219], v[158:161], off offset:576
	s_cbranch_execnz .LBB0_1104
	s_branch .LBB0_1103

.LBB0_1276:
	s_add_u32 s16, s14, 0x100
	s_addc_u32 s17, s15, 0
	s_add_i32 s39, 0, 0x10000
	v_add_u32_e32 v152, s39, v137
	ds_read_b128 v[140:143], v152
	ds_read_b128 v[148:151], v152 offset:2048
	ds_read_b128 v[144:147], v152 offset:1024
	ds_read_b128 v[152:155], v152 offset:3072
	s_cmp_eq_u32 s38, 12
	s_cselect_b32 s21, s11, s17
	s_cselect_b32 s20, s10, s16
	s_cselect_b32 s19, s13, s37
	s_cselect_b32 s18, s12, s3
	v_lshl_add_u64 v[188:189], s[14:15], 0, v[132:133]
	s_add_i32 m0, s9, 0xc000
	ds_read_b128 v[156:159], v139
	ds_read_b128 v[164:167], v139 offset:2048
	ds_read_b128 v[172:175], v139 offset:4096
	ds_read_b128 v[180:183], v139 offset:6144
	ds_read_b128 v[160:163], v139 offset:1024
	ds_read_b128 v[168:171], v139 offset:3072
	ds_read_b128 v[176:179], v139 offset:5120
	ds_read_b128 v[184:187], v139 offset:7168
	global_load_lds_dwordx4 v[188:189], off
	v_lshl_add_u64 v[188:189], s[14:15], 0, v[134:135]
	s_add_i32 m0, s9, 0xe000
	s_nop 0
	global_load_lds_dwordx4 v[188:189], off
	s_waitcnt lgkmcnt(8)
	s_barrier
	s_waitcnt lgkmcnt(4)
	s_setprio 1
	v_mfma_f32_16x16x32_f16 v[126:129], v[140:143], v[156:159], v[126:129]
	v_mfma_f32_16x16x32_f16 v[122:125], v[148:151], v[156:159], v[122:125]
	v_mfma_f32_16x16x32_f16 v[110:113], v[140:143], v[164:167], v[110:113]
	v_mfma_f32_16x16x32_f16 v[106:109], v[148:151], v[164:167], v[106:109]
	v_mfma_f32_16x16x32_f16 v[94:97], v[140:143], v[172:175], v[94:97]
	v_mfma_f32_16x16x32_f16 v[90:93], v[148:151], v[172:175], v[90:93]
	v_mfma_f32_16x16x32_f16 v[78:81], v[140:143], v[180:183], v[78:81]
	v_mfma_f32_16x16x32_f16 v[74:77], v[148:151], v[180:183], v[74:77]
	s_waitcnt lgkmcnt(0)
	v_mfma_f32_16x16x32_f16 v[126:129], v[144:147], v[160:163], v[126:129]
	v_mfma_f32_16x16x32_f16 v[122:125], v[152:155], v[160:163], v[122:125]
	v_mfma_f32_16x16x32_f16 v[110:113], v[144:147], v[168:171], v[110:113]
	v_mfma_f32_16x16x32_f16 v[106:109], v[152:155], v[168:171], v[106:109]
	v_mfma_f32_16x16x32_f16 v[94:97], v[144:147], v[176:179], v[94:97]
	v_mfma_f32_16x16x32_f16 v[90:93], v[152:155], v[176:179], v[90:93]
	v_mfma_f32_16x16x32_f16 v[78:81], v[144:147], v[184:187], v[78:81]
	v_mfma_f32_16x16x32_f16 v[74:77], v[152:155], v[184:187], v[74:77]
	s_setprio 0
	s_barrier
	s_add_i32 s40, 0, 0x14000
	s_add_i32 s14, s39, s26
	v_add_u32_e32 v200, s40, v137
	v_lshl_add_u64 v[204:205], s[18:19], 0, v[32:33]
	s_mov_b32 m0, s14
	ds_read_b128 v[188:191], v200
	ds_read_b128 v[196:199], v200 offset:2048
	ds_read_b128 v[192:195], v200 offset:1024
	ds_read_b128 v[200:203], v200 offset:3072
	global_load_lds_dwordx4 v[204:205], off
	v_lshl_add_u64 v[206:207], s[18:19], 0, v[130:131]
	s_add_i32 m0, s14, 0x2000
	s_nop 0
	global_load_lds_dwordx4 v[206:207], off
	s_barrier
	s_waitcnt lgkmcnt(2)
	s_setprio 1
	v_mfma_f32_16x16x32_f16 v[118:121], v[188:191], v[156:159], v[118:121]
	v_mfma_f32_16x16x32_f16 v[114:117], v[196:199], v[156:159], v[114:117]
	v_mfma_f32_16x16x32_f16 v[102:105], v[188:191], v[164:167], v[102:105]
	v_mfma_f32_16x16x32_f16 v[98:101], v[196:199], v[164:167], v[98:101]
	v_mfma_f32_16x16x32_f16 v[86:89], v[188:191], v[172:175], v[86:89]
	v_mfma_f32_16x16x32_f16 v[82:85], v[196:199], v[172:175], v[82:85]
	v_mfma_f32_16x16x32_f16 v[70:73], v[188:191], v[180:183], v[70:73]
	v_mfma_f32_16x16x32_f16 v[66:69], v[196:199], v[180:183], v[66:69]
	s_waitcnt lgkmcnt(0)
	v_mfma_f32_16x16x32_f16 v[118:121], v[192:195], v[160:163], v[118:121]
	v_mfma_f32_16x16x32_f16 v[114:117], v[200:203], v[160:163], v[114:117]
	v_mfma_f32_16x16x32_f16 v[102:105], v[192:195], v[168:171], v[102:105]
	v_mfma_f32_16x16x32_f16 v[98:101], v[200:203], v[168:171], v[98:101]
	v_mfma_f32_16x16x32_f16 v[86:89], v[192:195], v[176:179], v[86:89]
	v_mfma_f32_16x16x32_f16 v[82:85], v[200:203], v[176:179], v[82:85]
	v_mfma_f32_16x16x32_f16 v[70:73], v[192:195], v[184:187], v[70:73]
	v_mfma_f32_16x16x32_f16 v[66:69], v[200:203], v[184:187], v[66:69]
	s_setprio 0
	s_mov_b32 m0, s9
	v_lshl_add_u64 v[208:209], s[20:21], 0, v[32:33]
	s_barrier
	ds_read_b128 v[156:159], v139 offset:16384
	ds_read_b128 v[164:167], v139 offset:18432
	ds_read_b128 v[172:175], v139 offset:20480
	ds_read_b128 v[180:183], v139 offset:22528
	ds_read_b128 v[160:163], v139 offset:17408
	ds_read_b128 v[168:171], v139 offset:19456
	ds_read_b128 v[176:179], v139 offset:21504
	ds_read_b128 v[184:187], v139 offset:23552
	global_load_lds_dwordx4 v[208:209], off
	v_lshl_add_u64 v[210:211], s[20:21], 0, v[130:131]
	s_mov_b32 m0, s27
	s_nop 0
	global_load_lds_dwordx4 v[210:211], off
	s_barrier
	s_waitcnt lgkmcnt(4)
	s_setprio 1
	v_mfma_f32_16x16x32_f16 v[62:65], v[140:143], v[156:159], v[62:65]
	v_mfma_f32_16x16x32_f16 v[58:61], v[148:151], v[156:159], v[58:61]
	v_mfma_f32_16x16x32_f16 v[46:49], v[140:143], v[164:167], v[46:49]
	v_mfma_f32_16x16x32_f16 v[42:45], v[148:151], v[164:167], v[42:45]
	v_mfma_f32_16x16x32_f16 v[28:31], v[140:143], v[172:175], v[28:31]
	v_mfma_f32_16x16x32_f16 v[24:27], v[148:151], v[172:175], v[24:27]
	v_mfma_f32_16x16x32_f16 v[12:15], v[140:143], v[180:183], v[12:15]
	v_mfma_f32_16x16x32_f16 v[8:11], v[148:151], v[180:183], v[8:11]
	s_waitcnt lgkmcnt(0)
	v_mfma_f32_16x16x32_f16 v[62:65], v[144:147], v[160:163], v[62:65]
	v_mfma_f32_16x16x32_f16 v[58:61], v[152:155], v[160:163], v[58:61]
	v_mfma_f32_16x16x32_f16 v[46:49], v[144:147], v[168:171], v[46:49]
	v_mfma_f32_16x16x32_f16 v[42:45], v[152:155], v[168:171], v[42:45]
	v_mfma_f32_16x16x32_f16 v[28:31], v[144:147], v[176:179], v[28:31]
	v_mfma_f32_16x16x32_f16 v[24:27], v[152:155], v[176:179], v[24:27]
	v_mfma_f32_16x16x32_f16 v[12:15], v[144:147], v[184:187], v[12:15]
	v_mfma_f32_16x16x32_f16 v[8:11], v[152:155], v[184:187], v[8:11]
	s_setprio 0
	s_barrier
	s_add_u32 s14, s18, 0x40000
	s_addc_u32 s15, s19, 0
	s_add_i32 s39, s40, s26
	v_lshl_add_u64 v[140:141], s[14:15], 0, v[32:33]
	s_mov_b32 m0, s39
	s_nop 0
	global_load_lds_dwordx4 v[140:141], off
	v_lshl_add_u64 v[140:141], s[14:15], 0, v[130:131]
	s_add_i32 m0, s39, 0x2000
	s_nop 0
	global_load_lds_dwordx4 v[140:141], off
	s_waitcnt vmcnt(6)
	s_barrier
	s_setprio 1
	v_mfma_f32_16x16x32_f16 v[54:57], v[188:191], v[156:159], v[54:57]
	v_mfma_f32_16x16x32_f16 v[50:53], v[196:199], v[156:159], v[50:53]
	v_mfma_f32_16x16x32_f16 v[38:41], v[188:191], v[164:167], v[38:41]
	v_mfma_f32_16x16x32_f16 v[34:37], v[196:199], v[164:167], v[34:37]
	v_mfma_f32_16x16x32_f16 v[20:23], v[188:191], v[172:175], v[20:23]
	v_mfma_f32_16x16x32_f16 v[16:19], v[196:199], v[172:175], v[16:19]
	v_mfma_f32_16x16x32_f16 v[4:7], v[188:191], v[180:183], v[4:7]
	v_mfma_f32_16x16x32_f16 v[0:3], v[196:199], v[180:183], v[0:3]
	v_mfma_f32_16x16x32_f16 v[54:57], v[192:195], v[160:163], v[54:57]
	v_mfma_f32_16x16x32_f16 v[50:53], v[200:203], v[160:163], v[50:53]
	v_mfma_f32_16x16x32_f16 v[38:41], v[192:195], v[168:171], v[38:41]
	v_mfma_f32_16x16x32_f16 v[34:37], v[200:203], v[168:171], v[34:37]
	v_mfma_f32_16x16x32_f16 v[20:23], v[192:195], v[176:179], v[20:23]
	v_mfma_f32_16x16x32_f16 v[16:19], v[200:203], v[176:179], v[16:19]
	v_mfma_f32_16x16x32_f16 v[4:7], v[192:195], v[184:187], v[4:7]
	v_mfma_f32_16x16x32_f16 v[0:3], v[200:203], v[184:187], v[0:3]
	s_setprio 0
	s_add_i32 s39, 0, 0x18000
	v_add_u32_e32 v152, s39, v137
	s_barrier
	ds_read_b128 v[140:143], v152
	ds_read_b128 v[148:151], v152 offset:2048
	ds_read_b128 v[144:147], v152 offset:1024
	ds_read_b128 v[152:155], v152 offset:3072
	s_add_u32 s14, s20, 0x40000
	s_addc_u32 s15, s21, 0
	s_mov_b32 m0, s28
	v_lshl_add_u64 v[188:189], s[14:15], 0, v[32:33]
	ds_read_b128 v[156:159], v139 offset:32768
	ds_read_b128 v[164:167], v139 offset:34816
	ds_read_b128 v[172:175], v139 offset:36864
	ds_read_b128 v[180:183], v139 offset:38912
	ds_read_b128 v[160:163], v139 offset:33792
	ds_read_b128 v[168:171], v139 offset:35840
	ds_read_b128 v[176:179], v139 offset:37888
	ds_read_b128 v[184:187], v139 offset:39936
	global_load_lds_dwordx4 v[188:189], off
	v_lshl_add_u64 v[188:189], s[14:15], 0, v[130:131]
	s_mov_b32 m0, s29
	s_nop 0
	global_load_lds_dwordx4 v[188:189], off
	s_waitcnt lgkmcnt(8)
	s_barrier
	s_waitcnt lgkmcnt(4)
	s_setprio 1
	v_mfma_f32_16x16x32_f16 v[126:129], v[140:143], v[156:159], v[126:129]
	v_mfma_f32_16x16x32_f16 v[122:125], v[148:151], v[156:159], v[122:125]
	v_mfma_f32_16x16x32_f16 v[110:113], v[140:143], v[164:167], v[110:113]
	v_mfma_f32_16x16x32_f16 v[106:109], v[148:151], v[164:167], v[106:109]
	v_mfma_f32_16x16x32_f16 v[94:97], v[140:143], v[172:175], v[94:97]
	v_mfma_f32_16x16x32_f16 v[90:93], v[148:151], v[172:175], v[90:93]
	v_mfma_f32_16x16x32_f16 v[78:81], v[140:143], v[180:183], v[78:81]
	v_mfma_f32_16x16x32_f16 v[74:77], v[148:151], v[180:183], v[74:77]
	s_waitcnt lgkmcnt(0)
	v_mfma_f32_16x16x32_f16 v[126:129], v[144:147], v[160:163], v[126:129]
	v_mfma_f32_16x16x32_f16 v[122:125], v[152:155], v[160:163], v[122:125]
	v_mfma_f32_16x16x32_f16 v[110:113], v[144:147], v[168:171], v[110:113]
	v_mfma_f32_16x16x32_f16 v[106:109], v[152:155], v[168:171], v[106:109]
	v_mfma_f32_16x16x32_f16 v[94:97], v[144:147], v[176:179], v[94:97]
	v_mfma_f32_16x16x32_f16 v[90:93], v[152:155], v[176:179], v[90:93]
	v_mfma_f32_16x16x32_f16 v[78:81], v[144:147], v[184:187], v[78:81]
	v_mfma_f32_16x16x32_f16 v[74:77], v[152:155], v[184:187], v[74:77]
	s_setprio 0
	s_barrier
	s_add_i32 s20, 0, 0x1c000
	s_add_i32 s14, s39, s26
	v_add_u32_e32 v200, s20, v137
	v_lshl_add_u64 v[204:205], v[204:205], 0, s[84:85]
	s_mov_b32 m0, s14
	ds_read_b128 v[188:191], v200
	ds_read_b128 v[196:199], v200 offset:2048
	ds_read_b128 v[192:195], v200 offset:1024
	ds_read_b128 v[200:203], v200 offset:3072
	global_load_lds_dwordx4 v[204:205], off
	v_lshl_add_u64 v[204:205], v[206:207], 0, s[84:85]
	s_add_i32 m0, s14, 0x2000
	s_nop 0
	global_load_lds_dwordx4 v[204:205], off
	s_barrier
	s_waitcnt lgkmcnt(2)
	s_setprio 1
	v_mfma_f32_16x16x32_f16 v[118:121], v[188:191], v[156:159], v[118:121]
	v_mfma_f32_16x16x32_f16 v[114:117], v[196:199], v[156:159], v[114:117]
	v_mfma_f32_16x16x32_f16 v[102:105], v[188:191], v[164:167], v[102:105]
	v_mfma_f32_16x16x32_f16 v[98:101], v[196:199], v[164:167], v[98:101]
	v_mfma_f32_16x16x32_f16 v[86:89], v[188:191], v[172:175], v[86:89]
	v_mfma_f32_16x16x32_f16 v[82:85], v[196:199], v[172:175], v[82:85]
	v_mfma_f32_16x16x32_f16 v[70:73], v[188:191], v[180:183], v[70:73]
	v_mfma_f32_16x16x32_f16 v[66:69], v[196:199], v[180:183], v[66:69]
	s_waitcnt lgkmcnt(0)
	v_mfma_f32_16x16x32_f16 v[118:121], v[192:195], v[160:163], v[118:121]
	v_mfma_f32_16x16x32_f16 v[114:117], v[200:203], v[160:163], v[114:117]
	v_mfma_f32_16x16x32_f16 v[102:105], v[192:195], v[168:171], v[102:105]
	v_mfma_f32_16x16x32_f16 v[98:101], v[200:203], v[168:171], v[98:101]
	v_mfma_f32_16x16x32_f16 v[86:89], v[192:195], v[176:179], v[86:89]
	v_mfma_f32_16x16x32_f16 v[82:85], v[200:203], v[176:179], v[82:85]
	v_mfma_f32_16x16x32_f16 v[70:73], v[192:195], v[184:187], v[70:73]
	v_mfma_f32_16x16x32_f16 v[66:69], v[200:203], v[184:187], v[66:69]
	s_setprio 0
	s_mov_b32 m0, s30
	v_lshl_add_u64 v[204:205], v[208:209], 0, s[84:85]
	s_barrier
	ds_read_b128 v[156:159], v139 offset:49152
	ds_read_b128 v[164:167], v139 offset:51200
	ds_read_b128 v[172:175], v139 offset:53248
	ds_read_b128 v[180:183], v139 offset:55296
	ds_read_b128 v[160:163], v139 offset:50176
	ds_read_b128 v[168:171], v139 offset:52224
	ds_read_b128 v[176:179], v139 offset:54272
	ds_read_b128 v[184:187], v139 offset:56320
	global_load_lds_dwordx4 v[204:205], off
	v_lshl_add_u64 v[204:205], v[210:211], 0, s[84:85]
	s_mov_b32 m0, s31
	s_nop 0
	global_load_lds_dwordx4 v[204:205], off
	s_barrier
	s_waitcnt lgkmcnt(4)
	s_setprio 1
	v_mfma_f32_16x16x32_f16 v[62:65], v[140:143], v[156:159], v[62:65]
	v_mfma_f32_16x16x32_f16 v[58:61], v[148:151], v[156:159], v[58:61]
	v_mfma_f32_16x16x32_f16 v[46:49], v[140:143], v[164:167], v[46:49]
	v_mfma_f32_16x16x32_f16 v[42:45], v[148:151], v[164:167], v[42:45]
	v_mfma_f32_16x16x32_f16 v[28:31], v[140:143], v[172:175], v[28:31]
	v_mfma_f32_16x16x32_f16 v[24:27], v[148:151], v[172:175], v[24:27]
	v_mfma_f32_16x16x32_f16 v[12:15], v[140:143], v[180:183], v[12:15]
	v_mfma_f32_16x16x32_f16 v[8:11], v[148:151], v[180:183], v[8:11]
	s_waitcnt lgkmcnt(0)
	v_mfma_f32_16x16x32_f16 v[62:65], v[144:147], v[160:163], v[62:65]
	v_mfma_f32_16x16x32_f16 v[58:61], v[152:155], v[160:163], v[58:61]
	v_mfma_f32_16x16x32_f16 v[46:49], v[144:147], v[168:171], v[46:49]
	v_mfma_f32_16x16x32_f16 v[42:45], v[152:155], v[168:171], v[42:45]
	v_mfma_f32_16x16x32_f16 v[28:31], v[144:147], v[176:179], v[28:31]
	v_mfma_f32_16x16x32_f16 v[24:27], v[152:155], v[176:179], v[24:27]
	v_mfma_f32_16x16x32_f16 v[12:15], v[144:147], v[184:187], v[12:15]
	v_mfma_f32_16x16x32_f16 v[8:11], v[152:155], v[184:187], v[8:11]
	s_setprio 0
	s_barrier
	s_add_u32 s14, s18, 0x40080
	s_addc_u32 s15, s19, 0
	s_add_i32 s18, s20, s26
	v_lshl_add_u64 v[140:141], s[14:15], 0, v[32:33]
	s_mov_b32 m0, s18
	s_nop 0
	global_load_lds_dwordx4 v[140:141], off
	v_lshl_add_u64 v[140:141], s[14:15], 0, v[130:131]
	s_add_i32 m0, s18, 0x2000
	s_nop 0
	global_load_lds_dwordx4 v[140:141], off
	s_waitcnt vmcnt(6)
	s_barrier
	s_setprio 1
	v_mfma_f32_16x16x32_f16 v[54:57], v[188:191], v[156:159], v[54:57]
	v_mfma_f32_16x16x32_f16 v[50:53], v[196:199], v[156:159], v[50:53]
	v_mfma_f32_16x16x32_f16 v[38:41], v[188:191], v[164:167], v[38:41]
	v_mfma_f32_16x16x32_f16 v[34:37], v[196:199], v[164:167], v[34:37]
	v_mfma_f32_16x16x32_f16 v[20:23], v[188:191], v[172:175], v[20:23]
	v_mfma_f32_16x16x32_f16 v[16:19], v[196:199], v[172:175], v[16:19]
	v_mfma_f32_16x16x32_f16 v[4:7], v[188:191], v[180:183], v[4:7]
	v_mfma_f32_16x16x32_f16 v[0:3], v[196:199], v[180:183], v[0:3]
	v_mfma_f32_16x16x32_f16 v[54:57], v[192:195], v[160:163], v[54:57]
	v_mfma_f32_16x16x32_f16 v[50:53], v[200:203], v[160:163], v[50:53]
	v_mfma_f32_16x16x32_f16 v[38:41], v[192:195], v[168:171], v[38:41]
	v_mfma_f32_16x16x32_f16 v[34:37], v[200:203], v[168:171], v[34:37]
	v_mfma_f32_16x16x32_f16 v[20:23], v[192:195], v[176:179], v[20:23]
	v_mfma_f32_16x16x32_f16 v[16:19], v[200:203], v[176:179], v[16:19]
	v_mfma_f32_16x16x32_f16 v[4:7], v[192:195], v[184:187], v[4:7]
	v_mfma_f32_16x16x32_f16 v[0:3], v[200:203], v[184:187], v[0:3]
	s_setprio 0
	s_add_i32 s38, s38, 2
	s_add_u32 s3, s3, 0x100
	s_addc_u32 s37, s37, 0
	s_cmp_gt_u32 s38, 13
	s_mov_b64 s[14:15], s[16:17]
	s_barrier
	s_cbranch_scc0 .LBB0_1276
	v_mul_f32_e32 v144, 0xbfb8aa3b, v127
	v_mul_f32_e32 v141, 0xbfb8aa3b, v126
	v_exp_f32_e32 v145, v144
	v_mul_f32_e32 v144, 0xbfb8aa3b, v128
	v_exp_f32_e32 v141, v141
	v_exp_f32_e32 v146, v144
	v_mul_f32_e32 v144, 0xbfb8aa3b, v129
	v_exp_f32_e32 v147, v144
	v_mul_f32_e32 v144, 0xbfb8aa3b, v122
	v_exp_f32_e32 v148, v144
	v_mul_f32_e32 v144, 0xbfb8aa3b, v123
	v_exp_f32_e32 v149, v144
	v_mul_f32_e32 v144, 0xbfb8aa3b, v124
	v_exp_f32_e32 v150, v144
	v_mul_f32_e32 v144, 0xbfb8aa3b, v125
	v_add_f32_e32 v141, 1.0, v141
	v_exp_f32_e32 v151, v144
	v_rcp_f32_e32 v144, v141
	v_add_f32_e32 v141, 1.0, v145
	v_rcp_f32_e32 v145, v141
	v_add_f32_e32 v141, 1.0, v146
	v_rcp_f32_e32 v146, v141
	v_add_f32_e32 v141, 1.0, v147
	v_rcp_f32_e32 v147, v141
	v_add_f32_e32 v141, 1.0, v148
	v_rcp_f32_e32 v148, v141
	v_add_f32_e32 v141, 1.0, v149
	v_rcp_f32_e32 v149, v141
	v_add_f32_e32 v141, 1.0, v150
	v_rcp_f32_e32 v150, v141
	v_add_f32_e32 v141, 1.0, v151
	v_pk_mul_f32 v[126:127], v[126:127], v[144:145]
	v_rcp_f32_e32 v151, v141
	v_pk_mul_f32 v[118:119], v[126:127], v[118:119]
	v_pk_mul_f32 v[126:127], v[128:129], v[146:147]
	v_cvt_pk_f16_f32 v118, v118, v119
	v_pk_mul_f32 v[120:121], v[126:127], v[120:121]
	v_lshl_or_b32 v142, s36, 7, v138
	v_cvt_pk_f16_f32 v119, v120, v121
	v_pk_mul_f32 v[120:121], v[122:123], v[148:149]
	v_lshl_add_u32 v140, s8, 8, v136
	v_pk_mul_f32 v[114:115], v[120:121], v[114:115]
	v_ashrrev_i32_e32 v143, 31, v142
	v_cvt_pk_f16_f32 v120, v114, v115
	v_pk_mul_f32 v[114:115], v[124:125], v[150:151]
	s_movk_i32 s3, 0x1600
	v_pk_mul_f32 v[114:115], v[114:115], v[116:117]
	v_lshlrev_b64 v[116:117], 1, v[142:143]
	v_cvt_pk_f16_f32 v121, v114, v115
	v_mov_b64_e32 v[114:115], s[92:93]
	v_mad_i64_i32 v[122:123], s[10:11], v140, s3, v[114:115]
	v_lshl_add_u64 v[122:123], v[122:123], 0, v[116:117]
	global_store_dwordx4 v[122:123], v[118:121], off
	v_mul_f32_e32 v122, 0xbfb8aa3b, v106
	v_mul_f32_e32 v123, 0xbfb8aa3b, v107
	v_mul_f32_e32 v118, 0xbfb8aa3b, v110
	v_mul_f32_e32 v119, 0xbfb8aa3b, v111
	v_exp_f32_e32 v118, v118
	v_exp_f32_e32 v119, v119
	v_mul_f32_e32 v120, 0xbfb8aa3b, v112
	v_mul_f32_e32 v121, 0xbfb8aa3b, v113
	v_exp_f32_e32 v120, v120
	v_exp_f32_e32 v121, v121
	v_exp_f32_e32 v122, v122
	v_exp_f32_e32 v123, v123
	v_mul_f32_e32 v124, 0xbfb8aa3b, v108
	v_mul_f32_e32 v125, 0xbfb8aa3b, v109
	v_add_f32_e32 v118, 1.0, v118
	v_add_f32_e32 v119, 1.0, v119
	v_exp_f32_e32 v124, v124
	v_exp_f32_e32 v125, v125
	v_rcp_f32_e32 v118, v118
	v_rcp_f32_e32 v119, v119
	v_add_f32_e32 v120, 1.0, v120
	v_add_f32_e32 v121, 1.0, v121
	v_rcp_f32_e32 v120, v120
	v_rcp_f32_e32 v121, v121
	v_add_f32_e32 v122, 1.0, v122
	v_add_f32_e32 v123, 1.0, v123
	v_rcp_f32_e32 v122, v122
	v_rcp_f32_e32 v123, v123
	v_add_f32_e32 v124, 1.0, v124
	v_add_f32_e32 v125, 1.0, v125
	v_pk_mul_f32 v[110:111], v[110:111], v[118:119]
	v_rcp_f32_e32 v124, v124
	v_rcp_f32_e32 v125, v125
	v_pk_mul_f32 v[102:103], v[110:111], v[102:103]
	v_pk_mul_f32 v[110:111], v[112:113], v[120:121]
	v_cvt_pk_f16_f32 v102, v102, v103
	v_pk_mul_f32 v[104:105], v[110:111], v[104:105]
	s_and_b64 vcc, exec, s[0:1]
	v_cvt_pk_f16_f32 v103, v104, v105
	v_pk_mul_f32 v[104:105], v[106:107], v[122:123]
	s_mov_b32 s36, s35
	v_pk_mul_f32 v[98:99], v[104:105], v[98:99]
	s_mov_b32 s8, s2
	v_cvt_pk_f16_f32 v104, v98, v99
	v_pk_mul_f32 v[98:99], v[108:109], v[124:125]
	s_mov_b64 s[16:17], s[6:7]
	v_pk_mul_f32 v[98:99], v[98:99], v[100:101]
	v_mul_f32_e32 v100, 0xbfb8aa3b, v96
	v_cvt_pk_f16_f32 v105, v98, v99
	v_or_b32_e32 v98, 16, v140
	v_mad_i64_i32 v[98:99], s[10:11], v98, s3, v[114:115]
	v_lshl_add_u64 v[98:99], v[98:99], 0, v[116:117]
	global_store_dwordx4 v[98:99], v[102:105], off
	v_mul_f32_e32 v98, 0xbfb8aa3b, v94
	v_mul_f32_e32 v99, 0xbfb8aa3b, v95
	v_exp_f32_e32 v98, v98
	v_exp_f32_e32 v99, v99
	v_mul_f32_e32 v101, 0xbfb8aa3b, v97
	v_exp_f32_e32 v100, v100
	v_exp_f32_e32 v101, v101
	v_mul_f32_e32 v102, 0xbfb8aa3b, v90
	v_mul_f32_e32 v103, 0xbfb8aa3b, v91
	v_exp_f32_e32 v102, v102
	v_exp_f32_e32 v103, v103
	v_mul_f32_e32 v104, 0xbfb8aa3b, v92
	v_mul_f32_e32 v105, 0xbfb8aa3b, v93
	v_add_f32_e32 v98, 1.0, v98
	v_add_f32_e32 v99, 1.0, v99
	v_exp_f32_e32 v104, v104
	v_exp_f32_e32 v105, v105
	v_rcp_f32_e32 v98, v98
	v_rcp_f32_e32 v99, v99
	v_add_f32_e32 v100, 1.0, v100
	v_add_f32_e32 v101, 1.0, v101
	v_rcp_f32_e32 v100, v100
	v_rcp_f32_e32 v101, v101
	v_add_f32_e32 v102, 1.0, v102
	v_add_f32_e32 v103, 1.0, v103
	v_rcp_f32_e32 v102, v102
	v_rcp_f32_e32 v103, v103
	v_add_f32_e32 v104, 1.0, v104
	v_add_f32_e32 v105, 1.0, v105
	v_pk_mul_f32 v[94:95], v[94:95], v[98:99]
	v_rcp_f32_e32 v104, v104
	v_rcp_f32_e32 v105, v105
	v_pk_mul_f32 v[86:87], v[94:95], v[86:87]
	v_pk_mul_f32 v[94:95], v[96:97], v[100:101]
	v_cvt_pk_f16_f32 v86, v86, v87
	v_pk_mul_f32 v[88:89], v[94:95], v[88:89]
	s_mov_b64 s[14:15], s[4:5]
	v_cvt_pk_f16_f32 v87, v88, v89
	v_pk_mul_f32 v[88:89], v[90:91], v[102:103]
	s_nop 0
	v_pk_mul_f32 v[82:83], v[88:89], v[82:83]
	s_nop 0
	v_cvt_pk_f16_f32 v88, v82, v83
	v_pk_mul_f32 v[82:83], v[92:93], v[104:105]
	s_nop 0
	v_pk_mul_f32 v[82:83], v[82:83], v[84:85]
	v_mul_f32_e32 v84, 0xbfb8aa3b, v80
	v_cvt_pk_f16_f32 v89, v82, v83
	v_or_b32_e32 v82, 32, v140
	v_mad_i64_i32 v[82:83], s[10:11], v82, s3, v[114:115]
	v_lshl_add_u64 v[82:83], v[82:83], 0, v[116:117]
	global_store_dwordx4 v[82:83], v[86:89], off
	v_mul_f32_e32 v82, 0xbfb8aa3b, v78
	v_mul_f32_e32 v83, 0xbfb8aa3b, v79
	v_exp_f32_e32 v82, v82
	v_exp_f32_e32 v83, v83
	v_mul_f32_e32 v85, 0xbfb8aa3b, v81
	v_exp_f32_e32 v84, v84
	v_exp_f32_e32 v85, v85
	v_mul_f32_e32 v86, 0xbfb8aa3b, v74
	v_mul_f32_e32 v87, 0xbfb8aa3b, v75
	v_exp_f32_e32 v86, v86
	v_exp_f32_e32 v87, v87
	v_mul_f32_e32 v88, 0xbfb8aa3b, v76
	v_mul_f32_e32 v89, 0xbfb8aa3b, v77
	v_add_f32_e32 v82, 1.0, v82
	v_add_f32_e32 v83, 1.0, v83
	v_exp_f32_e32 v88, v88
	v_exp_f32_e32 v89, v89
	v_rcp_f32_e32 v82, v82
	v_rcp_f32_e32 v83, v83
	v_add_f32_e32 v84, 1.0, v84
	v_add_f32_e32 v85, 1.0, v85
	v_rcp_f32_e32 v84, v84
	v_rcp_f32_e32 v85, v85
	v_add_f32_e32 v86, 1.0, v86
	v_add_f32_e32 v87, 1.0, v87
	v_rcp_f32_e32 v86, v86
	v_rcp_f32_e32 v87, v87
	v_add_f32_e32 v88, 1.0, v88
	v_add_f32_e32 v89, 1.0, v89
	v_pk_mul_f32 v[78:79], v[78:79], v[82:83]
	v_rcp_f32_e32 v88, v88
	v_rcp_f32_e32 v89, v89
	v_pk_mul_f32 v[70:71], v[78:79], v[70:71]
	v_pk_mul_f32 v[78:79], v[80:81], v[84:85]
	v_cvt_pk_f16_f32 v70, v70, v71
	v_pk_mul_f32 v[72:73], v[78:79], v[72:73]
	s_nop 0
	v_cvt_pk_f16_f32 v71, v72, v73
	v_pk_mul_f32 v[72:73], v[74:75], v[86:87]
	v_add_u32_e32 v74, 0x80, v140
	v_pk_mul_f32 v[66:67], v[72:73], v[66:67]
	s_nop 0
	v_cvt_pk_f16_f32 v72, v66, v67
	v_pk_mul_f32 v[66:67], v[76:77], v[88:89]
	s_nop 0
	v_pk_mul_f32 v[66:67], v[66:67], v[68:69]
	v_mul_f32_e32 v68, 0xbfb8aa3b, v64
	v_cvt_pk_f16_f32 v73, v66, v67
	v_or_b32_e32 v66, 48, v140
	v_mad_i64_i32 v[66:67], s[10:11], v66, s3, v[114:115]
	v_lshl_add_u64 v[66:67], v[66:67], 0, v[116:117]
	global_store_dwordx4 v[66:67], v[70:73], off
	v_mul_f32_e32 v66, 0xbfb8aa3b, v62
	v_mul_f32_e32 v67, 0xbfb8aa3b, v63
	v_exp_f32_e32 v66, v66
	v_exp_f32_e32 v67, v67
	v_mul_f32_e32 v69, 0xbfb8aa3b, v65
	v_exp_f32_e32 v68, v68
	v_exp_f32_e32 v69, v69
	v_mul_f32_e32 v70, 0xbfb8aa3b, v58
	v_mul_f32_e32 v71, 0xbfb8aa3b, v59
	v_exp_f32_e32 v70, v70
	v_exp_f32_e32 v71, v71
	v_mul_f32_e32 v72, 0xbfb8aa3b, v60
	v_mul_f32_e32 v73, 0xbfb8aa3b, v61
	v_add_f32_e32 v66, 1.0, v66
	v_add_f32_e32 v67, 1.0, v67
	v_exp_f32_e32 v72, v72
	v_exp_f32_e32 v73, v73
	v_rcp_f32_e32 v66, v66
	v_rcp_f32_e32 v67, v67
	v_add_f32_e32 v68, 1.0, v68
	v_add_f32_e32 v69, 1.0, v69
	v_rcp_f32_e32 v68, v68
	v_rcp_f32_e32 v69, v69
	v_add_f32_e32 v70, 1.0, v70
	v_add_f32_e32 v71, 1.0, v71
	v_rcp_f32_e32 v70, v70
	v_rcp_f32_e32 v71, v71
	v_add_f32_e32 v72, 1.0, v72
	v_add_f32_e32 v73, 1.0, v73
	v_pk_mul_f32 v[62:63], v[62:63], v[66:67]
	v_rcp_f32_e32 v72, v72
	v_rcp_f32_e32 v73, v73
	v_pk_mul_f32 v[54:55], v[62:63], v[54:55]
	v_pk_mul_f32 v[62:63], v[64:65], v[68:69]
	v_cvt_pk_f16_f32 v54, v54, v55
	v_pk_mul_f32 v[56:57], v[62:63], v[56:57]
	s_nop 0
	v_cvt_pk_f16_f32 v55, v56, v57
	v_pk_mul_f32 v[56:57], v[58:59], v[70:71]
	s_nop 0
	v_pk_mul_f32 v[50:51], v[56:57], v[50:51]
	s_nop 0
	v_cvt_pk_f16_f32 v56, v50, v51
	v_pk_mul_f32 v[50:51], v[60:61], v[72:73]
	s_nop 0
	v_pk_mul_f32 v[50:51], v[50:51], v[52:53]
	v_mul_f32_e32 v52, 0xbfb8aa3b, v48
	v_cvt_pk_f16_f32 v57, v50, v51
	v_mad_i64_i32 v[50:51], s[10:11], v74, s3, v[114:115]
	v_lshl_add_u64 v[50:51], v[50:51], 0, v[116:117]
	global_store_dwordx4 v[50:51], v[54:57], off
	v_mul_f32_e32 v50, 0xbfb8aa3b, v46
	v_mul_f32_e32 v51, 0xbfb8aa3b, v47
	v_exp_f32_e32 v50, v50
	v_exp_f32_e32 v51, v51
	v_mul_f32_e32 v53, 0xbfb8aa3b, v49
	v_exp_f32_e32 v52, v52
	v_exp_f32_e32 v53, v53
	v_mul_f32_e32 v54, 0xbfb8aa3b, v42
	v_mul_f32_e32 v55, 0xbfb8aa3b, v43
	v_exp_f32_e32 v54, v54
	v_exp_f32_e32 v55, v55
	v_mul_f32_e32 v56, 0xbfb8aa3b, v44
	v_mul_f32_e32 v57, 0xbfb8aa3b, v45
	v_add_f32_e32 v50, 1.0, v50
	v_add_f32_e32 v51, 1.0, v51
	v_exp_f32_e32 v56, v56
	v_exp_f32_e32 v57, v57
	v_rcp_f32_e32 v50, v50
	v_rcp_f32_e32 v51, v51
	v_add_f32_e32 v52, 1.0, v52
	v_add_f32_e32 v53, 1.0, v53
	v_rcp_f32_e32 v52, v52
	v_rcp_f32_e32 v53, v53
	v_add_f32_e32 v54, 1.0, v54
	v_add_f32_e32 v55, 1.0, v55
	v_rcp_f32_e32 v54, v54
	v_rcp_f32_e32 v55, v55
	v_add_f32_e32 v56, 1.0, v56
	v_add_f32_e32 v57, 1.0, v57
	v_pk_mul_f32 v[46:47], v[46:47], v[50:51]
	v_rcp_f32_e32 v56, v56
	v_rcp_f32_e32 v57, v57
	v_pk_mul_f32 v[38:39], v[46:47], v[38:39]
	v_pk_mul_f32 v[46:47], v[48:49], v[52:53]
	v_cvt_pk_f16_f32 v38, v38, v39
	v_pk_mul_f32 v[40:41], v[46:47], v[40:41]
	s_nop 0
	v_cvt_pk_f16_f32 v39, v40, v41
	v_pk_mul_f32 v[40:41], v[42:43], v[54:55]
	s_nop 0
	v_pk_mul_f32 v[34:35], v[40:41], v[34:35]
	s_nop 0
	v_cvt_pk_f16_f32 v40, v34, v35
	v_pk_mul_f32 v[34:35], v[44:45], v[56:57]
	s_nop 0
	v_pk_mul_f32 v[34:35], v[34:35], v[36:37]
	v_mul_f32_e32 v36, 0xbfb8aa3b, v30
	v_cvt_pk_f16_f32 v41, v34, v35
	v_add_u32_e32 v34, 0x90, v140
	v_mad_i64_i32 v[34:35], s[10:11], v34, s3, v[114:115]
	v_lshl_add_u64 v[34:35], v[34:35], 0, v[116:117]
	global_store_dwordx4 v[34:35], v[38:41], off
	v_mul_f32_e32 v34, 0xbfb8aa3b, v28
	v_mul_f32_e32 v35, 0xbfb8aa3b, v29
	v_exp_f32_e32 v34, v34
	v_exp_f32_e32 v35, v35
	v_mul_f32_e32 v37, 0xbfb8aa3b, v31
	v_exp_f32_e32 v36, v36
	v_exp_f32_e32 v37, v37
	v_mul_f32_e32 v38, 0xbfb8aa3b, v24
	v_mul_f32_e32 v39, 0xbfb8aa3b, v25
	v_exp_f32_e32 v38, v38
	v_exp_f32_e32 v39, v39
	v_mul_f32_e32 v40, 0xbfb8aa3b, v26
	v_mul_f32_e32 v41, 0xbfb8aa3b, v27
	v_add_f32_e32 v34, 1.0, v34
	v_add_f32_e32 v35, 1.0, v35
	v_exp_f32_e32 v40, v40
	v_exp_f32_e32 v41, v41
	v_rcp_f32_e32 v34, v34
	v_rcp_f32_e32 v35, v35
	v_add_f32_e32 v36, 1.0, v36
	v_add_f32_e32 v37, 1.0, v37
	v_rcp_f32_e32 v36, v36
	v_rcp_f32_e32 v37, v37
	v_add_f32_e32 v38, 1.0, v38
	v_add_f32_e32 v39, 1.0, v39
	v_rcp_f32_e32 v38, v38
	v_rcp_f32_e32 v39, v39
	v_add_f32_e32 v40, 1.0, v40
	v_add_f32_e32 v41, 1.0, v41
	v_pk_mul_f32 v[28:29], v[28:29], v[34:35]
	v_rcp_f32_e32 v40, v40
	v_rcp_f32_e32 v41, v41
	v_pk_mul_f32 v[20:21], v[28:29], v[20:21]
	v_pk_mul_f32 v[28:29], v[30:31], v[36:37]
	v_cvt_pk_f16_f32 v20, v20, v21
	v_pk_mul_f32 v[22:23], v[28:29], v[22:23]
	s_nop 0
	v_cvt_pk_f16_f32 v21, v22, v23
	v_pk_mul_f32 v[22:23], v[24:25], v[38:39]
	s_nop 0
	v_pk_mul_f32 v[16:17], v[22:23], v[16:17]
	s_nop 0
	v_cvt_pk_f16_f32 v22, v16, v17
	v_pk_mul_f32 v[16:17], v[26:27], v[40:41]
	s_nop 0
	v_pk_mul_f32 v[16:17], v[16:17], v[18:19]
	v_mul_f32_e32 v18, 0xbfb8aa3b, v14
	v_cvt_pk_f16_f32 v23, v16, v17
	v_add_u32_e32 v16, 0xa0, v140
	v_mad_i64_i32 v[16:17], s[10:11], v16, s3, v[114:115]
	v_lshl_add_u64 v[16:17], v[16:17], 0, v[116:117]
	global_store_dwordx4 v[16:17], v[20:23], off
	v_mul_f32_e32 v16, 0xbfb8aa3b, v12
	v_mul_f32_e32 v17, 0xbfb8aa3b, v13
	v_exp_f32_e32 v16, v16
	v_exp_f32_e32 v17, v17
	v_mul_f32_e32 v19, 0xbfb8aa3b, v15
	v_exp_f32_e32 v18, v18
	v_exp_f32_e32 v19, v19
	v_mul_f32_e32 v20, 0xbfb8aa3b, v8
	v_mul_f32_e32 v21, 0xbfb8aa3b, v9
	v_exp_f32_e32 v20, v20
	v_exp_f32_e32 v21, v21
	v_mul_f32_e32 v22, 0xbfb8aa3b, v10
	v_mul_f32_e32 v23, 0xbfb8aa3b, v11
	v_add_f32_e32 v16, 1.0, v16
	v_add_f32_e32 v17, 1.0, v17
	v_exp_f32_e32 v22, v22
	v_exp_f32_e32 v23, v23
	v_rcp_f32_e32 v16, v16
	v_rcp_f32_e32 v17, v17
	v_add_f32_e32 v18, 1.0, v18
	v_add_f32_e32 v19, 1.0, v19
	v_rcp_f32_e32 v18, v18
	v_rcp_f32_e32 v19, v19
	v_add_f32_e32 v20, 1.0, v20
	v_add_f32_e32 v21, 1.0, v21
	v_rcp_f32_e32 v20, v20
	v_rcp_f32_e32 v21, v21
	v_add_f32_e32 v22, 1.0, v22
	v_add_f32_e32 v23, 1.0, v23
	v_pk_mul_f32 v[12:13], v[12:13], v[16:17]
	v_rcp_f32_e32 v22, v22
	v_rcp_f32_e32 v23, v23
	v_pk_mul_f32 v[4:5], v[12:13], v[4:5]
	v_pk_mul_f32 v[12:13], v[14:15], v[18:19]
	v_cvt_pk_f16_f32 v4, v4, v5
	v_pk_mul_f32 v[6:7], v[12:13], v[6:7]
	s_nop 0
	v_cvt_pk_f16_f32 v5, v6, v7
	v_pk_mul_f32 v[6:7], v[8:9], v[20:21]
	s_nop 0
	v_pk_mul_f32 v[0:1], v[6:7], v[0:1]
	s_nop 0
	v_cvt_pk_f16_f32 v6, v0, v1
	v_pk_mul_f32 v[0:1], v[10:11], v[22:23]
	s_nop 0
	v_pk_mul_f32 v[0:1], v[0:1], v[2:3]
	s_nop 0
	v_cvt_pk_f16_f32 v7, v0, v1
	v_add_u32_e32 v0, 0xb0, v140
	v_mad_i64_i32 v[0:1], s[10:11], v0, s3, v[114:115]
	v_lshl_add_u64 v[0:1], v[0:1], 0, v[116:117]
	global_store_dwordx4 v[0:1], v[4:7], off
	s_cmp_lg_u32 s34, 1
	s_cbranch_scc1 .Lups_skip
	s_and_b32 s0, s91, 63
	s_cmp_gt_u32 s0, 5
	s_cbranch_scc1 .Lups_skip
	s_cmp_gt_u32 s91, 196
	s_cbranch_scc1 .Lups_skip
	s_waitcnt vmcnt(0)
	s_barrier
	v_readlane_b32 s0, v251, 36
	s_cmp_lg_u32 s0, 0
	s_cbranch_scc1 .Lups_skip
	buffer_wbl2 sc1
	s_waitcnt vmcnt(0)
	v_readlane_b32 s2, v255, 45
	v_readlane_b32 s3, v254, 25
	s_lshl_b32 s2, s2, 1
	s_cmp_eq_u32 s3, 0
	s_cselect_b32 s3, 1, 0
	s_add_i32 s2, s2, s3
	s_lshl_b32 s2, s2, 2
	s_add_i32 s2, s2, 14016
	v_readlane_b32 s0, v251, 32
	v_readlane_b32 s1, v251, 33
	s_add_u32 s0, s0, s2
	s_addc_u32 s1, s1, 0
	s_mov_b64 s[2:3], exec
	s_mov_b64 exec, 1
	global_atomic_add v33, v248, s[0:1]
	s_mov_b64 exec, s[2:3]

.LBB0_1365:
	s_add_i32 s46, s14, 2
	s_add_u32 s12, s10, 0x100
	s_addc_u32 s13, s11, 0
	s_add_i32 s47, 0, 0x10000
	v_add_u32_e32 v134, s47, v230
	ds_read_b128 v[106:109], v134
	ds_read_b128 v[114:117], v134 offset:2048
	ds_read_b128 v[110:113], v134 offset:1024
	ds_read_b128 v[134:137], v134 offset:3072
	s_cmp_eq_u32 s43, s14
	s_cselect_b32 s14, s8, s44
	s_cselect_b32 s17, s7, s13
	s_cselect_b32 s16, s6, s12
	s_cselect_b32 s15, s9, s45
	v_lshl_add_u64 v[178:179], s[10:11], 0, v[184:185]
	s_add_i32 m0, s24, 0xc000
	ds_read_b128 v[138:141], v232
	ds_read_b128 v[154:157], v232 offset:2048
	ds_read_b128 v[162:165], v232 offset:4096
	ds_read_b128 v[170:173], v232 offset:6144
	ds_read_b128 v[150:153], v232 offset:1024
	ds_read_b128 v[158:161], v232 offset:3072
	ds_read_b128 v[166:169], v232 offset:5120
	ds_read_b128 v[174:177], v232 offset:7168
	global_load_lds_dwordx4 v[178:179], off
	v_lshl_add_u64 v[178:179], s[10:11], 0, v[186:187]
	s_add_i32 m0, s24, 0xe000
	s_nop 0
	global_load_lds_dwordx4 v[178:179], off
	s_waitcnt lgkmcnt(8)
	s_barrier
	s_waitcnt lgkmcnt(4)
	s_setprio 1
	v_mfma_f32_16x16x32_f16 v[146:149], v[106:109], v[138:141], v[146:149]
	v_mfma_f32_16x16x32_f16 v[142:145], v[114:117], v[138:141], v[142:145]
	v_mfma_f32_16x16x32_f16 v[130:133], v[106:109], v[154:157], v[130:133]
	v_mfma_f32_16x16x32_f16 v[122:125], v[114:117], v[154:157], v[122:125]
	v_mfma_f32_16x16x32_f16 v[94:97], v[106:109], v[162:165], v[94:97]
	v_mfma_f32_16x16x32_f16 v[90:93], v[114:117], v[162:165], v[90:93]
	v_mfma_f32_16x16x32_f16 v[78:81], v[106:109], v[170:173], v[78:81]
	v_mfma_f32_16x16x32_f16 v[74:77], v[114:117], v[170:173], v[74:77]
	s_waitcnt lgkmcnt(0)
	v_mfma_f32_16x16x32_f16 v[146:149], v[110:113], v[150:153], v[146:149]
	v_mfma_f32_16x16x32_f16 v[142:145], v[134:137], v[150:153], v[142:145]
	v_mfma_f32_16x16x32_f16 v[130:133], v[110:113], v[158:161], v[130:133]
	v_mfma_f32_16x16x32_f16 v[122:125], v[134:137], v[158:161], v[122:125]
	v_mfma_f32_16x16x32_f16 v[94:97], v[110:113], v[166:169], v[94:97]
	v_mfma_f32_16x16x32_f16 v[90:93], v[134:137], v[166:169], v[90:93]
	v_mfma_f32_16x16x32_f16 v[78:81], v[110:113], v[174:177], v[78:81]
	v_mfma_f32_16x16x32_f16 v[74:77], v[134:137], v[174:177], v[74:77]
	s_setprio 0
	s_barrier
	s_add_i32 s48, 0, 0x14000
	s_add_i32 s10, s47, s23
	v_add_u32_e32 v196, s48, v230
	v_lshl_add_u64 v[200:201], s[14:15], 0, v[32:33]
	s_mov_b32 m0, s10
	ds_read_b128 v[178:181], v196
	ds_read_b128 v[192:195], v196 offset:2048
	ds_read_b128 v[188:191], v196 offset:1024
	ds_read_b128 v[196:199], v196 offset:3072
	global_load_lds_dwordx4 v[200:201], off
	v_lshl_add_u64 v[202:203], s[14:15], 0, v[182:183]
	s_add_i32 m0, s10, 0x2000
	s_nop 0
	global_load_lds_dwordx4 v[202:203], off
	s_barrier
	s_waitcnt lgkmcnt(2)
	s_setprio 1
	v_mfma_f32_16x16x32_f16 v[126:129], v[178:181], v[138:141], v[126:129]
	v_mfma_f32_16x16x32_f16 v[118:121], v[192:195], v[138:141], v[118:121]
	v_mfma_f32_16x16x32_f16 v[102:105], v[178:181], v[154:157], v[102:105]
	v_mfma_f32_16x16x32_f16 v[98:101], v[192:195], v[154:157], v[98:101]
	v_mfma_f32_16x16x32_f16 v[86:89], v[178:181], v[162:165], v[86:89]
	v_mfma_f32_16x16x32_f16 v[82:85], v[192:195], v[162:165], v[82:85]
	v_mfma_f32_16x16x32_f16 v[70:73], v[178:181], v[170:173], v[70:73]
	v_mfma_f32_16x16x32_f16 v[66:69], v[192:195], v[170:173], v[66:69]
	s_waitcnt lgkmcnt(0)
	v_mfma_f32_16x16x32_f16 v[126:129], v[188:191], v[150:153], v[126:129]
	v_mfma_f32_16x16x32_f16 v[118:121], v[196:199], v[150:153], v[118:121]
	v_mfma_f32_16x16x32_f16 v[102:105], v[188:191], v[158:161], v[102:105]
	v_mfma_f32_16x16x32_f16 v[98:101], v[196:199], v[158:161], v[98:101]
	v_mfma_f32_16x16x32_f16 v[86:89], v[188:191], v[166:169], v[86:89]
	v_mfma_f32_16x16x32_f16 v[82:85], v[196:199], v[166:169], v[82:85]
	v_mfma_f32_16x16x32_f16 v[70:73], v[188:191], v[174:177], v[70:73]
	v_mfma_f32_16x16x32_f16 v[66:69], v[196:199], v[174:177], v[66:69]
	s_setprio 0
	s_mov_b32 m0, s24
	v_lshl_add_u64 v[204:205], s[16:17], 0, v[32:33]
	s_barrier
	ds_read_b128 v[138:141], v232 offset:16384
	ds_read_b128 v[154:157], v232 offset:18432
	ds_read_b128 v[162:165], v232 offset:20480
	ds_read_b128 v[170:173], v232 offset:22528
	ds_read_b128 v[150:153], v232 offset:17408
	ds_read_b128 v[158:161], v232 offset:19456
	ds_read_b128 v[166:169], v232 offset:21504
	ds_read_b128 v[174:177], v232 offset:23552
	global_load_lds_dwordx4 v[204:205], off
	v_lshl_add_u64 v[206:207], s[16:17], 0, v[182:183]
	s_mov_b32 m0, s25
	s_nop 0
	global_load_lds_dwordx4 v[206:207], off
	s_barrier
	s_waitcnt lgkmcnt(4)
	s_setprio 1
	v_mfma_f32_16x16x32_f16 v[62:65], v[106:109], v[138:141], v[62:65]
	v_mfma_f32_16x16x32_f16 v[58:61], v[114:117], v[138:141], v[58:61]
	v_mfma_f32_16x16x32_f16 v[46:49], v[106:109], v[154:157], v[46:49]
	v_mfma_f32_16x16x32_f16 v[42:45], v[114:117], v[154:157], v[42:45]
	v_mfma_f32_16x16x32_f16 v[28:31], v[106:109], v[162:165], v[28:31]
	v_mfma_f32_16x16x32_f16 v[24:27], v[114:117], v[162:165], v[24:27]
	v_mfma_f32_16x16x32_f16 v[12:15], v[106:109], v[170:173], v[12:15]
	v_mfma_f32_16x16x32_f16 v[8:11], v[114:117], v[170:173], v[8:11]
	s_waitcnt lgkmcnt(0)
	v_mfma_f32_16x16x32_f16 v[62:65], v[110:113], v[150:153], v[62:65]
	v_mfma_f32_16x16x32_f16 v[58:61], v[134:137], v[150:153], v[58:61]
	v_mfma_f32_16x16x32_f16 v[46:49], v[110:113], v[158:161], v[46:49]
	v_mfma_f32_16x16x32_f16 v[42:45], v[134:137], v[158:161], v[42:45]
	v_mfma_f32_16x16x32_f16 v[28:31], v[110:113], v[166:169], v[28:31]
	v_mfma_f32_16x16x32_f16 v[24:27], v[134:137], v[166:169], v[24:27]
	v_mfma_f32_16x16x32_f16 v[12:15], v[110:113], v[174:177], v[12:15]
	v_mfma_f32_16x16x32_f16 v[8:11], v[134:137], v[174:177], v[8:11]
	s_setprio 0
	s_barrier
	s_add_u32 s10, s14, 0xb0000
	s_addc_u32 s11, s15, 0
	s_add_i32 s47, s48, s23
	v_lshl_add_u64 v[106:107], s[10:11], 0, v[32:33]
	s_mov_b32 m0, s47
	s_nop 0
	global_load_lds_dwordx4 v[106:107], off
	v_lshl_add_u64 v[106:107], s[10:11], 0, v[182:183]
	s_add_i32 m0, s47, 0x2000
	s_nop 0
	global_load_lds_dwordx4 v[106:107], off
	s_waitcnt vmcnt(6)
	s_barrier
	s_setprio 1
	v_mfma_f32_16x16x32_f16 v[54:57], v[178:181], v[138:141], v[54:57]
	v_mfma_f32_16x16x32_f16 v[50:53], v[192:195], v[138:141], v[50:53]
	v_mfma_f32_16x16x32_f16 v[38:41], v[178:181], v[154:157], v[38:41]
	v_mfma_f32_16x16x32_f16 v[34:37], v[192:195], v[154:157], v[34:37]
	v_mfma_f32_16x16x32_f16 v[20:23], v[178:181], v[162:165], v[20:23]
	v_mfma_f32_16x16x32_f16 v[16:19], v[192:195], v[162:165], v[16:19]
	v_mfma_f32_16x16x32_f16 v[4:7], v[178:181], v[170:173], v[4:7]
	v_mfma_f32_16x16x32_f16 v[0:3], v[192:195], v[170:173], v[0:3]
	v_mfma_f32_16x16x32_f16 v[54:57], v[188:191], v[150:153], v[54:57]
	v_mfma_f32_16x16x32_f16 v[50:53], v[196:199], v[150:153], v[50:53]
	v_mfma_f32_16x16x32_f16 v[38:41], v[188:191], v[158:161], v[38:41]
	v_mfma_f32_16x16x32_f16 v[34:37], v[196:199], v[158:161], v[34:37]
	v_mfma_f32_16x16x32_f16 v[20:23], v[188:191], v[166:169], v[20:23]
	v_mfma_f32_16x16x32_f16 v[16:19], v[196:199], v[166:169], v[16:19]
	v_mfma_f32_16x16x32_f16 v[4:7], v[188:191], v[174:177], v[4:7]
	v_mfma_f32_16x16x32_f16 v[0:3], v[196:199], v[174:177], v[0:3]
	s_setprio 0
	s_add_i32 s47, 0, 0x18000
	v_add_u32_e32 v134, s47, v230
	s_barrier
	ds_read_b128 v[106:109], v134
	ds_read_b128 v[114:117], v134 offset:2048
	ds_read_b128 v[110:113], v134 offset:1024
	ds_read_b128 v[134:137], v134 offset:3072
	s_add_u32 s10, s16, 0xb0000
	s_addc_u32 s11, s17, 0
	s_mov_b32 m0, s26
	v_lshl_add_u64 v[178:179], s[10:11], 0, v[32:33]
	ds_read_b128 v[138:141], v232 offset:32768
	ds_read_b128 v[154:157], v232 offset:34816
	ds_read_b128 v[162:165], v232 offset:36864
	ds_read_b128 v[170:173], v232 offset:38912
	ds_read_b128 v[150:153], v232 offset:33792
	ds_read_b128 v[158:161], v232 offset:35840
	ds_read_b128 v[166:169], v232 offset:37888
	ds_read_b128 v[174:177], v232 offset:39936
	global_load_lds_dwordx4 v[178:179], off
	v_lshl_add_u64 v[178:179], s[10:11], 0, v[182:183]
	s_mov_b32 m0, s27
	s_nop 0
	global_load_lds_dwordx4 v[178:179], off
	s_waitcnt lgkmcnt(8)
	s_barrier
	s_waitcnt lgkmcnt(4)
	s_setprio 1
	v_mfma_f32_16x16x32_f16 v[146:149], v[106:109], v[138:141], v[146:149]
	v_mfma_f32_16x16x32_f16 v[142:145], v[114:117], v[138:141], v[142:145]
	v_mfma_f32_16x16x32_f16 v[130:133], v[106:109], v[154:157], v[130:133]
	v_mfma_f32_16x16x32_f16 v[122:125], v[114:117], v[154:157], v[122:125]
	v_mfma_f32_16x16x32_f16 v[94:97], v[106:109], v[162:165], v[94:97]
	v_mfma_f32_16x16x32_f16 v[90:93], v[114:117], v[162:165], v[90:93]
	v_mfma_f32_16x16x32_f16 v[78:81], v[106:109], v[170:173], v[78:81]
	v_mfma_f32_16x16x32_f16 v[74:77], v[114:117], v[170:173], v[74:77]
	s_waitcnt lgkmcnt(0)
	v_mfma_f32_16x16x32_f16 v[146:149], v[110:113], v[150:153], v[146:149]
	v_mfma_f32_16x16x32_f16 v[142:145], v[134:137], v[150:153], v[142:145]
	v_mfma_f32_16x16x32_f16 v[130:133], v[110:113], v[158:161], v[130:133]
	v_mfma_f32_16x16x32_f16 v[122:125], v[134:137], v[158:161], v[122:125]
	v_mfma_f32_16x16x32_f16 v[94:97], v[110:113], v[166:169], v[94:97]
	v_mfma_f32_16x16x32_f16 v[90:93], v[134:137], v[166:169], v[90:93]
	v_mfma_f32_16x16x32_f16 v[78:81], v[110:113], v[174:177], v[78:81]
	v_mfma_f32_16x16x32_f16 v[74:77], v[134:137], v[174:177], v[74:77]
	s_setprio 0
	s_barrier
	s_add_i32 s16, 0, 0x1c000
	s_add_i32 s10, s47, s23
	v_add_u32_e32 v196, s16, v230
	v_lshl_add_u64 v[200:201], v[200:201], 0, s[84:85]
	s_mov_b32 m0, s10
	ds_read_b128 v[178:181], v196
	ds_read_b128 v[192:195], v196 offset:2048
	ds_read_b128 v[188:191], v196 offset:1024
	ds_read_b128 v[196:199], v196 offset:3072
	global_load_lds_dwordx4 v[200:201], off
	v_lshl_add_u64 v[200:201], v[202:203], 0, s[84:85]
	s_add_i32 m0, s10, 0x2000
	s_nop 0
	global_load_lds_dwordx4 v[200:201], off
	s_barrier
	s_waitcnt lgkmcnt(2)
	s_setprio 1
	v_mfma_f32_16x16x32_f16 v[126:129], v[178:181], v[138:141], v[126:129]
	v_mfma_f32_16x16x32_f16 v[118:121], v[192:195], v[138:141], v[118:121]
	v_mfma_f32_16x16x32_f16 v[102:105], v[178:181], v[154:157], v[102:105]
	v_mfma_f32_16x16x32_f16 v[98:101], v[192:195], v[154:157], v[98:101]
	v_mfma_f32_16x16x32_f16 v[86:89], v[178:181], v[162:165], v[86:89]
	v_mfma_f32_16x16x32_f16 v[82:85], v[192:195], v[162:165], v[82:85]
	v_mfma_f32_16x16x32_f16 v[70:73], v[178:181], v[170:173], v[70:73]
	v_mfma_f32_16x16x32_f16 v[66:69], v[192:195], v[170:173], v[66:69]
	s_waitcnt lgkmcnt(0)
	v_mfma_f32_16x16x32_f16 v[126:129], v[188:191], v[150:153], v[126:129]
	v_mfma_f32_16x16x32_f16 v[118:121], v[196:199], v[150:153], v[118:121]
	v_mfma_f32_16x16x32_f16 v[102:105], v[188:191], v[158:161], v[102:105]
	v_mfma_f32_16x16x32_f16 v[98:101], v[196:199], v[158:161], v[98:101]
	v_mfma_f32_16x16x32_f16 v[86:89], v[188:191], v[166:169], v[86:89]
	v_mfma_f32_16x16x32_f16 v[82:85], v[196:199], v[166:169], v[82:85]
	v_mfma_f32_16x16x32_f16 v[70:73], v[188:191], v[174:177], v[70:73]
	v_mfma_f32_16x16x32_f16 v[66:69], v[196:199], v[174:177], v[66:69]
	s_setprio 0
	s_mov_b32 m0, s29
	v_lshl_add_u64 v[200:201], v[204:205], 0, s[84:85]
	s_barrier
	ds_read_b128 v[138:141], v232 offset:49152
	ds_read_b128 v[154:157], v232 offset:51200
	ds_read_b128 v[162:165], v232 offset:53248
	ds_read_b128 v[170:173], v232 offset:55296
	ds_read_b128 v[150:153], v232 offset:50176
	ds_read_b128 v[158:161], v232 offset:52224
	ds_read_b128 v[166:169], v232 offset:54272
	ds_read_b128 v[174:177], v232 offset:56320
	global_load_lds_dwordx4 v[200:201], off
	v_lshl_add_u64 v[200:201], v[206:207], 0, s[84:85]
	s_mov_b32 m0, s30
	s_nop 0
	global_load_lds_dwordx4 v[200:201], off
	s_barrier
	s_waitcnt lgkmcnt(4)
	s_setprio 1
	v_mfma_f32_16x16x32_f16 v[62:65], v[106:109], v[138:141], v[62:65]
	v_mfma_f32_16x16x32_f16 v[58:61], v[114:117], v[138:141], v[58:61]
	v_mfma_f32_16x16x32_f16 v[46:49], v[106:109], v[154:157], v[46:49]
	v_mfma_f32_16x16x32_f16 v[42:45], v[114:117], v[154:157], v[42:45]
	v_mfma_f32_16x16x32_f16 v[28:31], v[106:109], v[162:165], v[28:31]
	v_mfma_f32_16x16x32_f16 v[24:27], v[114:117], v[162:165], v[24:27]
	v_mfma_f32_16x16x32_f16 v[12:15], v[106:109], v[170:173], v[12:15]
	v_mfma_f32_16x16x32_f16 v[8:11], v[114:117], v[170:173], v[8:11]
	s_waitcnt lgkmcnt(0)
	v_mfma_f32_16x16x32_f16 v[62:65], v[110:113], v[150:153], v[62:65]
	v_mfma_f32_16x16x32_f16 v[58:61], v[134:137], v[150:153], v[58:61]
	v_mfma_f32_16x16x32_f16 v[46:49], v[110:113], v[158:161], v[46:49]
	v_mfma_f32_16x16x32_f16 v[42:45], v[134:137], v[158:161], v[42:45]
	v_mfma_f32_16x16x32_f16 v[28:31], v[110:113], v[166:169], v[28:31]
	v_mfma_f32_16x16x32_f16 v[24:27], v[134:137], v[166:169], v[24:27]
	v_mfma_f32_16x16x32_f16 v[12:15], v[110:113], v[174:177], v[12:15]
	v_mfma_f32_16x16x32_f16 v[8:11], v[134:137], v[174:177], v[8:11]
	s_setprio 0
	s_barrier
	s_add_u32 s10, s14, 0xb0080
	s_addc_u32 s11, s15, 0
	s_add_i32 s14, s16, s23
	v_lshl_add_u64 v[106:107], s[10:11], 0, v[32:33]
	s_mov_b32 m0, s14
	s_nop 0
	global_load_lds_dwordx4 v[106:107], off
	v_lshl_add_u64 v[106:107], s[10:11], 0, v[182:183]
	s_add_i32 m0, s14, 0x2000
	s_nop 0
	global_load_lds_dwordx4 v[106:107], off
	s_waitcnt vmcnt(6)
	s_barrier
	s_setprio 1
	v_mfma_f32_16x16x32_f16 v[54:57], v[178:181], v[138:141], v[54:57]
	v_mfma_f32_16x16x32_f16 v[50:53], v[192:195], v[138:141], v[50:53]
	v_mfma_f32_16x16x32_f16 v[38:41], v[178:181], v[154:157], v[38:41]
	v_mfma_f32_16x16x32_f16 v[34:37], v[192:195], v[154:157], v[34:37]
	v_mfma_f32_16x16x32_f16 v[20:23], v[178:181], v[162:165], v[20:23]
	v_mfma_f32_16x16x32_f16 v[16:19], v[192:195], v[162:165], v[16:19]
	v_mfma_f32_16x16x32_f16 v[4:7], v[178:181], v[170:173], v[4:7]
	v_mfma_f32_16x16x32_f16 v[0:3], v[192:195], v[170:173], v[0:3]
	v_mfma_f32_16x16x32_f16 v[54:57], v[188:191], v[150:153], v[54:57]
	v_mfma_f32_16x16x32_f16 v[50:53], v[196:199], v[150:153], v[50:53]
	v_mfma_f32_16x16x32_f16 v[38:41], v[188:191], v[158:161], v[38:41]
	v_mfma_f32_16x16x32_f16 v[34:37], v[196:199], v[158:161], v[34:37]
	v_mfma_f32_16x16x32_f16 v[20:23], v[188:191], v[166:169], v[20:23]
	v_mfma_f32_16x16x32_f16 v[16:19], v[196:199], v[166:169], v[16:19]
	v_mfma_f32_16x16x32_f16 v[4:7], v[188:191], v[174:177], v[4:7]
	v_mfma_f32_16x16x32_f16 v[0:3], v[196:199], v[174:177], v[0:3]
	s_setprio 0
	s_add_u32 s44, s44, 0x100
	s_addc_u32 s45, s45, 0
	s_cmp_ge_u32 s46, s42
	s_mov_b64 s[10:11], s[12:13]
	s_mov_b32 s14, s46
	s_barrier
	s_cbranch_scc0 .LBB0_1365
	s_cmp_eq_u32 s40, 0
	s_cselect_b32 s6, 0x9000, 0
	v_lshl_or_b32 v106, s41, 8, v231
	s_add_u32 s6, s31, s6
	s_addc_u32 s7, s34, 0
	v_ashrrev_i32_e32 v107, 31, v106
	v_lshl_add_u64 v[116:117], v[106:107], 2, s[6:7]
	global_load_dwordx4 v[108:111], v[116:117], off offset:16
	global_load_dwordx4 v[112:115], v[116:117], off
	s_cmp_eq_u32 s39, 0
	s_waitcnt vmcnt(0)
	v_pk_mul_f32 v[194:195], v[110:111], 0.5 op_sel_hi:[1,0]
	v_pk_mul_f32 v[198:199], v[114:115], 0.5 op_sel_hi:[1,0]
	v_pk_mul_f32 v[202:203], v[112:113], 0.5 op_sel_hi:[1,0]
	v_pk_mul_f32 v[200:201], v[108:109], 0.5 op_sel_hi:[1,0]
	global_load_dwordx4 v[108:111], v[116:117], off offset:528
	global_load_dwordx4 v[112:115], v[116:117], off offset:512
	s_waitcnt vmcnt(0)
	v_pk_mul_f32 v[188:189], v[110:111], 0.5 op_sel_hi:[1,0]
	v_pk_mul_f32 v[196:197], v[112:113], 0.5 op_sel_hi:[1,0]
	v_lshl_add_u32 v112, s40, 8, v229
	v_pk_mul_f32 v[190:191], v[114:115], 0.5 op_sel_hi:[1,0]
	v_pk_mul_f32 v[192:193], v[108:109], 0.5 op_sel_hi:[1,0]
	v_or_b32_e32 v114, 16, v112
	v_or_b32_e32 v110, 32, v112
	v_or_b32_e32 v108, 48, v112
	v_ashrrev_i32_e32 v113, 31, v112
	v_ashrrev_i32_e32 v115, 31, v114
	v_ashrrev_i32_e32 v111, 31, v110
	v_ashrrev_i32_e32 v109, 31, v108
	s_cbranch_scc1 .LBB0_1368
	s_add_i32 s96, s39, -1
	s_lshl_b64 s[6:7], s[96:97], 20
	v_readlane_b32 s8, v252, 11
	v_readlane_b32 s9, v252, 12
	s_add_u32 s6, s8, s6
	s_addc_u32 s7, s9, s7
	v_lshlrev_b64 v[138:139], 2, v[106:107]
	v_lshrrev_b32_e32 v150, 5, v220
	v_mul_u32_u24_e32 v150, 48, v150
	s_nop 0
	v_sub_co_u32_e32 v138, vcc, v138, v150
	s_nop 1
	v_subbrev_co_u32_e32 v139, vcc, 0, v139, vcc
	v_lshl_add_u64 v[138:139], s[6:7], 0, v[138:139]
	s_mov_b64 s[6:7], 0x80000
	v_lshlrev_b64 v[204:205], 12, v[112:113]
	v_lshl_add_u64 v[204:205], v[204:205], 0, v[138:139]
	v_lshl_add_u64 v[212:213], v[204:205], 0, s[6:7]
	v_lshlrev_b64 v[206:207], 12, v[114:115]
	v_lshl_add_u64 v[206:207], v[206:207], 0, v[138:139]
	v_lshl_add_u64 v[214:215], v[206:207], 0, s[6:7]
	v_lshlrev_b64 v[208:209], 12, v[110:111]
	v_lshl_add_u64 v[208:209], v[208:209], 0, v[138:139]
	v_lshl_add_u64 v[216:217], v[208:209], 0, s[6:7]
	v_lshlrev_b64 v[210:211], 12, v[108:109]
	v_lshl_add_u64 v[210:211], v[210:211], 0, v[138:139]
	v_lshl_add_u64 v[218:219], v[210:211], 0, s[6:7]
	s_waitcnt vmcnt(0)
	v_pk_mul_f32 v[152:153], v[146:147], v[202:203]
	v_pk_mul_f32 v[154:155], v[148:149], v[198:199]
	v_pk_mul_f32 v[156:157], v[142:143], v[200:201]
	v_pk_mul_f32 v[158:159], v[144:145], v[194:195]
	s_nop 1
	v_permlane32_swap_b32_e32 v152, v156
	v_permlane32_swap_b32_e32 v153, v157
	v_permlane32_swap_b32_e32 v154, v158
	v_permlane32_swap_b32_e32 v155, v159
	s_nop 0
	global_store_dwordx4 v[204:205], v[152:155], off
	global_store_dwordx4 v[204:205], v[156:159], off offset:64
	v_pk_mul_f32 v[160:161], v[126:127], v[196:197]
	v_pk_mul_f32 v[162:163], v[128:129], v[190:191]
	v_pk_mul_f32 v[164:165], v[118:119], v[192:193]
	v_pk_mul_f32 v[166:167], v[120:121], v[188:189]
	s_nop 1
	v_permlane32_swap_b32_e32 v160, v164
	v_permlane32_swap_b32_e32 v161, v165
	v_permlane32_swap_b32_e32 v162, v166
	v_permlane32_swap_b32_e32 v163, v167
	s_nop 0
	global_store_dwordx4 v[204:205], v[160:163], off offset:512
	global_store_dwordx4 v[204:205], v[164:167], off offset:576
	v_pk_mul_f32 v[168:169], v[130:131], v[202:203]
	v_pk_mul_f32 v[170:171], v[132:133], v[198:199]
	v_pk_mul_f32 v[172:173], v[122:123], v[200:201]
	v_pk_mul_f32 v[174:175], v[124:125], v[194:195]
	s_nop 1
	v_permlane32_swap_b32_e32 v168, v172
	v_permlane32_swap_b32_e32 v169, v173
	v_permlane32_swap_b32_e32 v170, v174
	v_permlane32_swap_b32_e32 v171, v175
	s_nop 0
	global_store_dwordx4 v[206:207], v[168:171], off
	global_store_dwordx4 v[206:207], v[172:175], off offset:64
	v_pk_mul_f32 v[176:177], v[102:103], v[196:197]
	v_pk_mul_f32 v[178:179], v[104:105], v[190:191]
	v_pk_mul_f32 v[180:181], v[98:99], v[192:193]
	v_pk_mul_f32 v[182:183], v[100:101], v[188:189]
	s_nop 1
	v_permlane32_swap_b32_e32 v176, v180
	v_permlane32_swap_b32_e32 v177, v181
	v_permlane32_swap_b32_e32 v178, v182
	v_permlane32_swap_b32_e32 v179, v183
	s_nop 0
	global_store_dwordx4 v[206:207], v[176:179], off offset:512
	global_store_dwordx4 v[206:207], v[180:183], off offset:576
	v_pk_mul_f32 v[152:153], v[94:95], v[202:203]
	v_pk_mul_f32 v[154:155], v[96:97], v[198:199]
	v_pk_mul_f32 v[156:157], v[90:91], v[200:201]
	v_pk_mul_f32 v[158:159], v[92:93], v[194:195]
	s_nop 1
	v_permlane32_swap_b32_e32 v152, v156
	v_permlane32_swap_b32_e32 v153, v157
	v_permlane32_swap_b32_e32 v154, v158
	v_permlane32_swap_b32_e32 v155, v159
	s_nop 0
	global_store_dwordx4 v[208:209], v[152:155], off
	global_store_dwordx4 v[208:209], v[156:159], off offset:64
	v_pk_mul_f32 v[160:161], v[86:87], v[196:197]
	v_pk_mul_f32 v[162:163], v[88:89], v[190:191]
	v_pk_mul_f32 v[164:165], v[82:83], v[192:193]
	v_pk_mul_f32 v[166:167], v[84:85], v[188:189]
	s_nop 1
	v_permlane32_swap_b32_e32 v160, v164
	v_permlane32_swap_b32_e32 v161, v165
	v_permlane32_swap_b32_e32 v162, v166
	v_permlane32_swap_b32_e32 v163, v167
	s_nop 0
	global_store_dwordx4 v[208:209], v[160:163], off offset:512
	global_store_dwordx4 v[208:209], v[164:167], off offset:576
	v_pk_mul_f32 v[168:169], v[78:79], v[202:203]
	v_pk_mul_f32 v[170:171], v[80:81], v[198:199]
	v_pk_mul_f32 v[172:173], v[74:75], v[200:201]
	v_pk_mul_f32 v[174:175], v[76:77], v[194:195]
	s_nop 1
	v_permlane32_swap_b32_e32 v168, v172
	v_permlane32_swap_b32_e32 v169, v173
	v_permlane32_swap_b32_e32 v170, v174
	v_permlane32_swap_b32_e32 v171, v175
	s_nop 0
	global_store_dwordx4 v[210:211], v[168:171], off
	global_store_dwordx4 v[210:211], v[172:175], off offset:64
	v_pk_mul_f32 v[176:177], v[70:71], v[196:197]
	v_pk_mul_f32 v[178:179], v[72:73], v[190:191]
	v_pk_mul_f32 v[180:181], v[66:67], v[192:193]
	v_pk_mul_f32 v[182:183], v[68:69], v[188:189]
	s_nop 1
	v_permlane32_swap_b32_e32 v176, v180
	v_permlane32_swap_b32_e32 v177, v181
	v_permlane32_swap_b32_e32 v178, v182
	v_permlane32_swap_b32_e32 v179, v183
	s_nop 0
	global_store_dwordx4 v[210:211], v[176:179], off offset:512
	global_store_dwordx4 v[210:211], v[180:183], off offset:576
	v_pk_mul_f32 v[152:153], v[62:63], v[202:203]
	v_pk_mul_f32 v[154:155], v[64:65], v[198:199]
	v_pk_mul_f32 v[156:157], v[58:59], v[200:201]
	v_pk_mul_f32 v[158:159], v[60:61], v[194:195]
	s_nop 1
	v_permlane32_swap_b32_e32 v152, v156
	v_permlane32_swap_b32_e32 v153, v157
	v_permlane32_swap_b32_e32 v154, v158
	v_permlane32_swap_b32_e32 v155, v159
	s_nop 0
	global_store_dwordx4 v[212:213], v[152:155], off
	global_store_dwordx4 v[212:213], v[156:159], off offset:64
	v_pk_mul_f32 v[160:161], v[54:55], v[196:197]
	v_pk_mul_f32 v[162:163], v[56:57], v[190:191]
	v_pk_mul_f32 v[164:165], v[50:51], v[192:193]
	v_pk_mul_f32 v[166:167], v[52:53], v[188:189]
	s_nop 1
	v_permlane32_swap_b32_e32 v160, v164
	v_permlane32_swap_b32_e32 v161, v165
	v_permlane32_swap_b32_e32 v162, v166
	v_permlane32_swap_b32_e32 v163, v167
	s_nop 0
	global_store_dwordx4 v[212:213], v[160:163], off offset:512
	global_store_dwordx4 v[212:213], v[164:167], off offset:576
	v_pk_mul_f32 v[168:169], v[46:47], v[202:203]
	v_pk_mul_f32 v[170:171], v[48:49], v[198:199]
	v_pk_mul_f32 v[172:173], v[42:43], v[200:201]
	v_pk_mul_f32 v[174:175], v[44:45], v[194:195]
	s_nop 1
	v_permlane32_swap_b32_e32 v168, v172
	v_permlane32_swap_b32_e32 v169, v173
	v_permlane32_swap_b32_e32 v170, v174
	v_permlane32_swap_b32_e32 v171, v175
	s_nop 0
	global_store_dwordx4 v[214:215], v[168:171], off
	global_store_dwordx4 v[214:215], v[172:175], off offset:64
	v_pk_mul_f32 v[176:177], v[38:39], v[196:197]
	v_pk_mul_f32 v[178:179], v[40:41], v[190:191]
	v_pk_mul_f32 v[180:181], v[34:35], v[192:193]
	v_pk_mul_f32 v[182:183], v[36:37], v[188:189]
	s_nop 1
	v_permlane32_swap_b32_e32 v176, v180
	v_permlane32_swap_b32_e32 v177, v181
	v_permlane32_swap_b32_e32 v178, v182
	v_permlane32_swap_b32_e32 v179, v183
	s_nop 0
	global_store_dwordx4 v[214:215], v[176:179], off offset:512
	global_store_dwordx4 v[214:215], v[180:183], off offset:576
	v_pk_mul_f32 v[152:153], v[28:29], v[202:203]
	v_pk_mul_f32 v[154:155], v[30:31], v[198:199]
	v_pk_mul_f32 v[156:157], v[24:25], v[200:201]
	v_pk_mul_f32 v[158:159], v[26:27], v[194:195]
	s_nop 1
	v_permlane32_swap_b32_e32 v152, v156
	v_permlane32_swap_b32_e32 v153, v157
	v_permlane32_swap_b32_e32 v154, v158
	v_permlane32_swap_b32_e32 v155, v159
	s_nop 0
	global_store_dwordx4 v[216:217], v[152:155], off
	global_store_dwordx4 v[216:217], v[156:159], off offset:64
	v_pk_mul_f32 v[160:161], v[20:21], v[196:197]
	v_pk_mul_f32 v[162:163], v[22:23], v[190:191]
	v_pk_mul_f32 v[164:165], v[16:17], v[192:193]
	v_pk_mul_f32 v[166:167], v[18:19], v[188:189]
	s_nop 1
	v_permlane32_swap_b32_e32 v160, v164
	v_permlane32_swap_b32_e32 v161, v165
	v_permlane32_swap_b32_e32 v162, v166
	v_permlane32_swap_b32_e32 v163, v167
	s_nop 0
	global_store_dwordx4 v[216:217], v[160:163], off offset:512
	global_store_dwordx4 v[216:217], v[164:167], off offset:576
	v_pk_mul_f32 v[168:169], v[12:13], v[202:203]
	v_pk_mul_f32 v[170:171], v[14:15], v[198:199]
	v_pk_mul_f32 v[172:173], v[8:9], v[200:201]
	v_pk_mul_f32 v[174:175], v[10:11], v[194:195]
	s_nop 1
	v_permlane32_swap_b32_e32 v168, v172
	v_permlane32_swap_b32_e32 v169, v173
	v_permlane32_swap_b32_e32 v170, v174
	v_permlane32_swap_b32_e32 v171, v175
	s_nop 0
	global_store_dwordx4 v[218:219], v[168:171], off
	global_store_dwordx4 v[218:219], v[172:175], off offset:64
	v_pk_mul_f32 v[176:177], v[4:5], v[196:197]
	v_pk_mul_f32 v[178:179], v[6:7], v[190:191]
	v_pk_mul_f32 v[180:181], v[0:1], v[192:193]
	v_pk_mul_f32 v[182:183], v[2:3], v[188:189]
	s_nop 1
	v_permlane32_swap_b32_e32 v176, v180
	v_permlane32_swap_b32_e32 v177, v181
	v_permlane32_swap_b32_e32 v178, v182
	v_permlane32_swap_b32_e32 v179, v183
	s_nop 0
	global_store_dwordx4 v[218:219], v[176:179], off offset:512
	global_store_dwordx4 v[218:219], v[180:183], off offset:576
	s_cbranch_execnz .LBB0_1352
	s_branch .LBB0_1351
